# speedup vs baseline: 1.0239x; 1.0097x over previous
; #define STAGE(P, BASE, kt) do { const char* _g = (const char*)(BASE) + (size_t)((kt) * (BK * 2)); \
;     __builtin_amdgcn_global_load_lds((const unsigned*)(_g + (size_t)goff0), (unsigned*)((char*)(P) + tid_ * 16), 16, 0, 0); \
;     __builtin_amdgcn_global_load_lds((const unsigned*)(_g + (size_t)goff1), (unsigned*)((char*)(P) + tid_ * 16 + 8192), 16, 0, 0); } while (0)
; #define STAGEA(P, BASE, kt) do { const char* _g = (const char*)(BASE) + (size_t)((kt) * a_kbytes); \
;     __builtin_amdgcn_global_load_lds((const unsigned*)(_g + (size_t)goffA0), (unsigned*)((char*)(P) + tid_ * 16), 16, 0, 0); \
;     __builtin_amdgcn_global_load_lds((const unsigned*)(_g + (size_t)goffA1), (unsigned*)((char*)(P) + tid_ * 16 + 8192), 16, 0, 0); } while (0)
; #define LDA(dst, b, h) for (int m = 0; m < 4; ++m) for (int k = 0; k < 2; ++k) \
;     dst[m][k] = *reinterpret_cast<const bf16x8*>((char*)SA(b, h) + lds_byte(wr * 64 + m * 16 + fr, k * 32 + fq * 8))
; #define LDB(dst, b, h) for (int n = 0; n < 2; ++n) for (int k = 0; k < 2; ++k) \
;     dst[n][k] = *reinterpret_cast<const bf16x8*>((char*)SB(b, h) + lds_byte(wc * 32 + n * 16 + fr, k * 32 + fq * 8))
; #define MMA(ai, bj, At, Bt) do { __builtin_amdgcn_s_setprio(1); \
;     for (int m = 0; m < 4; ++m) for (int n = 0; n < 2; ++n) for (int k = 0; k < 2; ++k) \
;       acc[ai][bj][m][n] = __builtin_amdgcn_mfma_f32_16x16x32_bf16(At[m][k], Bt[n][k], acc[ai][bj][m][n], 0, 0, 0); \
;     __builtin_amdgcn_s_setprio(0); } while (0)
; #define WAIT_V(n) asm volatile("s_waitcnt vmcnt(" #n ")" ::: "memory")
; #define WAIT_L(n) asm volatile("s_waitcnt lgkmcnt(" #n ")" ::: "memory")
; #define BAR __builtin_amdgcn_s_barrier()
; #define SCHED __builtin_amdgcn_sched_barrier(0)
; template <int EPI> ...
;     ...
;   for (int t = 0; t < nt - 2; t += 2) {
;     LDB(B0, 0, 0); SCHED; LDA(At, 0, 0); STAGEA(SA(1, 1), A1, t + 1);
;     WAIT_L(8); BAR; WAIT_L(0); MMA(0, 0, At, B0); BAR; SCHED;
;     LDB(B1, 0, 1); STAGE(SB(0, 0), B0p, t + 2);
;     BAR; WAIT_L(0); MMA(0, 1, At, B1); BAR;
;     LDA(At, 0, 1); STAGEA(SA(0, 0), A0, t + 2);
;     BAR; WAIT_L(0); MMA(1, 0, At, B0); BAR; SCHED;
;     STAGE(SB(0, 1), B1p, t + 2);
;     WAIT_V(6); BAR; MMA(1, 1, At, B1); BAR;
;     LDB(B0, 1, 0); SCHED; LDA(At, 1, 0); STAGEA(SA(0, 1), A1, t + 2);
;     WAIT_L(8); BAR; WAIT_L(0); MMA(0, 0, At, B0); BAR; SCHED;
.LBB0_760:
	ds_read_b128 v[176:179], v172
	ds_read_b128 v[180:183], v172 offset:1024
	ds_read_b128 v[184:187], v172 offset:2048
	ds_read_b128 v[188:191], v172 offset:3072
	v_add_u32_e32 v173, 0xc000, v159
	v_lshl_add_u64 v[240:241], s[58:59], 0, v[142:143]
	v_readfirstlane_b32 s55, v173
	v_lshl_add_u64 v[174:175], v[240:241], 0, s[6:7]
	s_mov_b32 m0, s55
	ds_read_b128 v[192:195], v154
	ds_read_b128 v[196:199], v154 offset:1024
	ds_read_b128 v[200:203], v153
	ds_read_b128 v[204:207], v153 offset:1024
	ds_read_b128 v[208:211], v152
	ds_read_b128 v[212:215], v152 offset:1024
	ds_read_b128 v[216:219], v151
	ds_read_b128 v[220:223], v151 offset:1024
	global_load_lds_dwordx4 v[174:175], off
	v_add_u32_e32 v174, 0xe000, v159
	v_lshl_add_u64 v[242:243], s[58:59], 0, v[144:145]
	v_readfirstlane_b32 s55, v174
	v_lshl_add_u64 v[224:225], v[242:243], 0, s[6:7]
	s_mov_b32 m0, s55
	s_nop 0
	global_load_lds_dwordx4 v[224:225], off
	s_waitcnt lgkmcnt(8)
	s_setprio 1
	s_barrier
	s_waitcnt lgkmcnt(0)
	v_mfma_f32_16x16x32_bf16 v[124:127], v[192:195], v[176:179], v[124:127]
	v_mfma_f32_16x16x32_bf16 v[120:123], v[192:195], v[184:187], v[120:123]
	v_mfma_f32_16x16x32_bf16 v[116:119], v[200:203], v[176:179], v[116:119]
	v_mfma_f32_16x16x32_bf16 v[112:115], v[200:203], v[184:187], v[112:115]
	v_mfma_f32_16x16x32_bf16 v[108:111], v[208:211], v[176:179], v[108:111]
	v_mfma_f32_16x16x32_bf16 v[104:107], v[208:211], v[184:187], v[104:107]
	v_mfma_f32_16x16x32_bf16 v[100:103], v[216:219], v[176:179], v[100:103]
	v_mfma_f32_16x16x32_bf16 v[96:99], v[216:219], v[184:187], v[96:99]
	v_mfma_f32_16x16x32_bf16 v[124:127], v[196:199], v[180:183], v[124:127]
	v_mfma_f32_16x16x32_bf16 v[120:123], v[196:199], v[188:191], v[120:123]
	v_mfma_f32_16x16x32_bf16 v[116:119], v[204:207], v[180:183], v[116:119]
	v_mfma_f32_16x16x32_bf16 v[112:115], v[204:207], v[188:191], v[112:115]
	v_mfma_f32_16x16x32_bf16 v[108:111], v[212:215], v[180:183], v[108:111]
	v_mfma_f32_16x16x32_bf16 v[104:107], v[212:215], v[188:191], v[104:107]
	v_mfma_f32_16x16x32_bf16 v[100:103], v[220:223], v[180:183], v[100:103]
	v_mfma_f32_16x16x32_bf16 v[96:99], v[220:223], v[188:191], v[96:99]
	s_barrier
	s_setprio 0
	v_lshl_add_u64 v[244:245], s[58:59], 0, v[128:129]
	v_readfirstlane_b32 s55, v156
	v_lshl_add_u64 v[246:247], v[244:245], 0, s[8:9]
	s_mov_b32 m0, s55
	ds_read_b128 v[224:227], v169
	ds_read_b128 v[228:231], v169 offset:1024
	ds_read_b128 v[232:235], v169 offset:2048
	ds_read_b128 v[236:239], v169 offset:3072
	global_load_lds_dwordx4 v[246:247], off
	v_lshl_add_u64 v[246:247], s[58:59], 0, v[130:131]
	v_readfirstlane_b32 s55, v158
	v_lshl_add_u64 v[248:249], v[246:247], 0, s[8:9]
	s_mov_b32 m0, s55
	s_nop 0
	global_load_lds_dwordx4 v[248:249], off
	s_setprio 1
	s_barrier
	s_waitcnt lgkmcnt(0)
	v_mfma_f32_16x16x32_bf16 v[92:95], v[192:195], v[224:227], v[92:95]
	v_mfma_f32_16x16x32_bf16 v[88:91], v[192:195], v[232:235], v[88:91]
	v_mfma_f32_16x16x32_bf16 v[84:87], v[200:203], v[224:227], v[84:87]
	v_mfma_f32_16x16x32_bf16 v[80:83], v[200:203], v[232:235], v[80:83]
	v_mfma_f32_16x16x32_bf16 v[76:79], v[208:211], v[224:227], v[76:79]
	v_mfma_f32_16x16x32_bf16 v[72:75], v[208:211], v[232:235], v[72:75]
	v_mfma_f32_16x16x32_bf16 v[68:71], v[216:219], v[224:227], v[68:71]
	v_mfma_f32_16x16x32_bf16 v[64:67], v[216:219], v[232:235], v[64:67]
	v_mfma_f32_16x16x32_bf16 v[92:95], v[196:199], v[228:231], v[92:95]
	v_mfma_f32_16x16x32_bf16 v[88:91], v[196:199], v[236:239], v[88:91]
	v_mfma_f32_16x16x32_bf16 v[84:87], v[204:207], v[228:231], v[84:87]
	v_mfma_f32_16x16x32_bf16 v[80:83], v[204:207], v[236:239], v[80:83]
	v_mfma_f32_16x16x32_bf16 v[76:79], v[212:215], v[228:231], v[76:79]
	v_mfma_f32_16x16x32_bf16 v[72:75], v[212:215], v[236:239], v[72:75]
	v_mfma_f32_16x16x32_bf16 v[68:71], v[220:223], v[228:231], v[68:71]
	v_mfma_f32_16x16x32_bf16 v[64:67], v[220:223], v[236:239], v[64:67]
	s_barrier
	s_setprio 0
	v_readfirstlane_b32 s55, v159
	v_lshl_add_u64 v[248:249], v[240:241], 0, s[10:11]
	s_mov_b32 m0, s55
	v_readfirstlane_b32 s55, v160
	ds_read_b128 v[192:195], v154 offset:16384
	ds_read_b128 v[196:199], v154 offset:17408
	ds_read_b128 v[200:203], v153 offset:16384
	ds_read_b128 v[204:207], v153 offset:17408
	ds_read_b128 v[208:211], v152 offset:16384
	ds_read_b128 v[212:215], v152 offset:17408
	ds_read_b128 v[216:219], v151 offset:16384
	ds_read_b128 v[220:223], v151 offset:17408
	global_load_lds_dwordx4 v[248:249], off
	v_lshl_add_u64 v[248:249], v[242:243], 0, s[10:11]
	s_mov_b32 m0, s55
	s_nop 0
	global_load_lds_dwordx4 v[248:249], off
	s_setprio 1
	s_barrier
	s_waitcnt lgkmcnt(0)
	v_mfma_f32_16x16x32_bf16 v[60:63], v[192:195], v[176:179], v[60:63]
	v_mfma_f32_16x16x32_bf16 v[56:59], v[192:195], v[184:187], v[56:59]
	v_mfma_f32_16x16x32_bf16 v[52:55], v[200:203], v[176:179], v[52:55]
	v_mfma_f32_16x16x32_bf16 v[48:51], v[200:203], v[184:187], v[48:51]
	v_mfma_f32_16x16x32_bf16 v[44:47], v[208:211], v[176:179], v[44:47]
	v_mfma_f32_16x16x32_bf16 v[40:43], v[208:211], v[184:187], v[40:43]
	v_mfma_f32_16x16x32_bf16 v[36:39], v[216:219], v[176:179], v[36:39]
	v_mfma_f32_16x16x32_bf16 v[32:35], v[216:219], v[184:187], v[32:35]
	v_mfma_f32_16x16x32_bf16 v[60:63], v[196:199], v[180:183], v[60:63]
	v_mfma_f32_16x16x32_bf16 v[56:59], v[196:199], v[188:191], v[56:59]
	v_mfma_f32_16x16x32_bf16 v[52:55], v[204:207], v[180:183], v[52:55]
	v_mfma_f32_16x16x32_bf16 v[48:51], v[204:207], v[188:191], v[48:51]
	v_mfma_f32_16x16x32_bf16 v[44:47], v[212:215], v[180:183], v[44:47]
	v_mfma_f32_16x16x32_bf16 v[40:43], v[212:215], v[188:191], v[40:43]
	v_mfma_f32_16x16x32_bf16 v[36:39], v[220:223], v[180:183], v[36:39]
	v_mfma_f32_16x16x32_bf16 v[32:35], v[220:223], v[188:191], v[32:35]
	s_barrier
; #define STAGE(P, BASE, kt) do { const char* _g = (const char*)(BASE) + (size_t)((kt) * (BK * 2)); \
;     __builtin_amdgcn_global_load_lds((const unsigned*)(_g + (size_t)goff0), (unsigned*)((char*)(P) + tid_ * 16), 16, 0, 0); \
;     __builtin_amdgcn_global_load_lds((const unsigned*)(_g + (size_t)goff1), (unsigned*)((char*)(P) + tid_ * 16 + 8192), 16, 0, 0); } while (0)
; #define STAGEA(P, BASE, kt) do { const char* _g = (const char*)(BASE) + (size_t)((kt) * a_kbytes); \
;     __builtin_amdgcn_global_load_lds((const unsigned*)(_g + (size_t)goffA0), (unsigned*)((char*)(P) + tid_ * 16), 16, 0, 0); \
;     __builtin_amdgcn_global_load_lds((const unsigned*)(_g + (size_t)goffA1), (unsigned*)((char*)(P) + tid_ * 16 + 8192), 16, 0, 0); } while (0)
; #define LDA(dst, b, h) for (int m = 0; m < 4; ++m) for (int k = 0; k < 2; ++k) \
;     dst[m][k] = *reinterpret_cast<const bf16x8*>((char*)SA(b, h) + lds_byte(wr * 64 + m * 16 + fr, k * 32 + fq * 8))
; #define LDB(dst, b, h) for (int n = 0; n < 2; ++n) for (int k = 0; k < 2; ++k) \
;     dst[n][k] = *reinterpret_cast<const bf16x8*>((char*)SB(b, h) + lds_byte(wc * 32 + n * 16 + fr, k * 32 + fq * 8))
; #define MMA(ai, bj, At, Bt) do { __builtin_amdgcn_s_setprio(1); \
;     for (int m = 0; m < 4; ++m) for (int n = 0; n < 2; ++n) for (int k = 0; k < 2; ++k) \
;       acc[ai][bj][m][n] = __builtin_amdgcn_mfma_f32_16x16x32_bf16(At[m][k], Bt[n][k], acc[ai][bj][m][n], 0, 0, 0); \
;     __builtin_amdgcn_s_setprio(0); } while (0)
; #define WAIT_V(n) asm volatile("s_waitcnt vmcnt(" #n ")" ::: "memory")
; #define WAIT_L(n) asm volatile("s_waitcnt lgkmcnt(" #n ")" ::: "memory")
; #define BAR __builtin_amdgcn_s_barrier()
; #define SCHED __builtin_amdgcn_sched_barrier(0)
; template <int EPI> ...
;     ...
;     STAGE(SB(0, 1), B1p, t + 2);
;     WAIT_V(6); BAR; MMA(1, 1, At, B1); BAR;
;     LDB(B0, 1, 0); SCHED; LDA(At, 1, 0); STAGEA(SA(0, 1), A1, t + 2);
;     WAIT_L(8); BAR; WAIT_L(0); MMA(0, 0, At, B0); BAR; SCHED;
;     LDB(B1, 1, 1); STAGE(SB(1, 0), B0p, t + 3);
;     BAR; WAIT_L(0); MMA(0, 1, At, B1); BAR;
;     LDA(At, 1, 1); STAGEA(SA(1, 0), A0, t + 3);
	s_setprio 0
	v_readfirstlane_b32 s55, v161
	v_lshl_add_u64 v[176:177], v[244:245], 0, s[12:13]
	s_mov_b32 m0, s55
	v_readfirstlane_b32 s55, v162
	global_load_lds_dwordx4 v[176:177], off
	v_lshl_add_u64 v[176:177], v[246:247], 0, s[12:13]
	s_mov_b32 m0, s55
	s_nop 0
	global_load_lds_dwordx4 v[176:177], off
	s_waitcnt vmcnt(6)
	s_setprio 1
	s_barrier
	v_mfma_f32_16x16x32_bf16 v[28:31], v[192:195], v[224:227], v[28:31]
	v_mfma_f32_16x16x32_bf16 v[24:27], v[192:195], v[232:235], v[24:27]
	v_mfma_f32_16x16x32_bf16 v[20:23], v[200:203], v[224:227], v[20:23]
	v_mfma_f32_16x16x32_bf16 v[16:19], v[200:203], v[232:235], v[16:19]
	v_mfma_f32_16x16x32_bf16 v[12:15], v[208:211], v[224:227], v[12:15]
	v_mfma_f32_16x16x32_bf16 v[8:11], v[208:211], v[232:235], v[8:11]
	v_mfma_f32_16x16x32_bf16 v[4:7], v[216:219], v[224:227], v[4:7]
	v_mfma_f32_16x16x32_bf16 v[0:3], v[216:219], v[232:235], v[0:3]
	v_mfma_f32_16x16x32_bf16 v[28:31], v[196:199], v[228:231], v[28:31]
	v_mfma_f32_16x16x32_bf16 v[24:27], v[196:199], v[236:239], v[24:27]
	v_mfma_f32_16x16x32_bf16 v[20:23], v[204:207], v[228:231], v[20:23]
	v_mfma_f32_16x16x32_bf16 v[16:19], v[204:207], v[236:239], v[16:19]
	v_mfma_f32_16x16x32_bf16 v[12:15], v[212:215], v[228:231], v[12:15]
	v_mfma_f32_16x16x32_bf16 v[8:11], v[212:215], v[236:239], v[8:11]
	v_mfma_f32_16x16x32_bf16 v[4:7], v[220:223], v[228:231], v[4:7]
	v_mfma_f32_16x16x32_bf16 v[0:3], v[220:223], v[236:239], v[0:3]
	s_barrier
	s_setprio 0
	ds_read_b128 v[176:179], v157
	ds_read_b128 v[180:183], v157 offset:1024
	ds_read_b128 v[184:187], v157 offset:2048
	ds_read_b128 v[188:191], v157 offset:3072
	v_readfirstlane_b32 s55, v163
	v_lshl_add_u64 v[224:225], v[240:241], 0, s[14:15]
	s_mov_b32 m0, s55
	v_readfirstlane_b32 s55, v164
	ds_read_b128 v[192:195], v154 offset:32768
	ds_read_b128 v[196:199], v154 offset:33792
	ds_read_b128 v[200:203], v153 offset:32768
	ds_read_b128 v[204:207], v153 offset:33792
	ds_read_b128 v[208:211], v152 offset:32768
	ds_read_b128 v[212:215], v152 offset:33792
	ds_read_b128 v[216:219], v151 offset:32768
	ds_read_b128 v[220:223], v151 offset:33792
	global_load_lds_dwordx4 v[224:225], off
	v_lshl_add_u64 v[224:225], v[242:243], 0, s[14:15]
	s_mov_b32 m0, s55
	s_nop 0
	global_load_lds_dwordx4 v[224:225], off
	s_waitcnt lgkmcnt(8)
	s_setprio 1
	s_barrier
	s_waitcnt lgkmcnt(0)
	v_mfma_f32_16x16x32_bf16 v[124:127], v[192:195], v[176:179], v[124:127]
	v_mfma_f32_16x16x32_bf16 v[120:123], v[192:195], v[184:187], v[120:123]
	v_mfma_f32_16x16x32_bf16 v[116:119], v[200:203], v[176:179], v[116:119]
	v_mfma_f32_16x16x32_bf16 v[112:115], v[200:203], v[184:187], v[112:115]
	v_mfma_f32_16x16x32_bf16 v[108:111], v[208:211], v[176:179], v[108:111]
	v_mfma_f32_16x16x32_bf16 v[104:107], v[208:211], v[184:187], v[104:107]
	v_mfma_f32_16x16x32_bf16 v[100:103], v[216:219], v[176:179], v[100:103]
	v_mfma_f32_16x16x32_bf16 v[96:99], v[216:219], v[184:187], v[96:99]
	v_mfma_f32_16x16x32_bf16 v[124:127], v[196:199], v[180:183], v[124:127]
	v_mfma_f32_16x16x32_bf16 v[120:123], v[196:199], v[188:191], v[120:123]
	v_mfma_f32_16x16x32_bf16 v[116:119], v[204:207], v[180:183], v[116:119]
	v_mfma_f32_16x16x32_bf16 v[112:115], v[204:207], v[188:191], v[112:115]
	v_mfma_f32_16x16x32_bf16 v[108:111], v[212:215], v[180:183], v[108:111]
	v_mfma_f32_16x16x32_bf16 v[104:107], v[212:215], v[188:191], v[104:107]
	v_mfma_f32_16x16x32_bf16 v[100:103], v[220:223], v[180:183], v[100:103]
	v_mfma_f32_16x16x32_bf16 v[96:99], v[220:223], v[188:191], v[96:99]
	s_barrier
	s_setprio 0
	v_readfirstlane_b32 s55, v165
	v_lshl_add_u64 v[248:249], v[244:245], 0, s[24:25]
	s_mov_b32 m0, s55
	v_readfirstlane_b32 s55, v166
	ds_read_b128 v[224:227], v155
	ds_read_b128 v[228:231], v155 offset:1024
	ds_read_b128 v[232:235], v155 offset:2048
	ds_read_b128 v[236:239], v155 offset:3072
	global_load_lds_dwordx4 v[248:249], off
	v_lshl_add_u64 v[248:249], v[246:247], 0, s[24:25]
	s_mov_b32 m0, s55
	s_nop 0
	global_load_lds_dwordx4 v[248:249], off
	s_setprio 1
	s_barrier
	s_waitcnt lgkmcnt(0)
	v_mfma_f32_16x16x32_bf16 v[92:95], v[192:195], v[224:227], v[92:95]
	v_mfma_f32_16x16x32_bf16 v[88:91], v[192:195], v[232:235], v[88:91]
	v_mfma_f32_16x16x32_bf16 v[84:87], v[200:203], v[224:227], v[84:87]
	v_mfma_f32_16x16x32_bf16 v[80:83], v[200:203], v[232:235], v[80:83]
	v_mfma_f32_16x16x32_bf16 v[76:79], v[208:211], v[224:227], v[76:79]
	v_mfma_f32_16x16x32_bf16 v[72:75], v[208:211], v[232:235], v[72:75]
	v_mfma_f32_16x16x32_bf16 v[68:71], v[216:219], v[224:227], v[68:71]
	v_mfma_f32_16x16x32_bf16 v[64:67], v[216:219], v[232:235], v[64:67]
	v_mfma_f32_16x16x32_bf16 v[92:95], v[196:199], v[228:231], v[92:95]
	v_mfma_f32_16x16x32_bf16 v[88:91], v[196:199], v[236:239], v[88:91]
	v_mfma_f32_16x16x32_bf16 v[84:87], v[204:207], v[228:231], v[84:87]
	v_mfma_f32_16x16x32_bf16 v[80:83], v[204:207], v[236:239], v[80:83]
	v_mfma_f32_16x16x32_bf16 v[76:79], v[212:215], v[228:231], v[76:79]
	v_mfma_f32_16x16x32_bf16 v[72:75], v[212:215], v[236:239], v[72:75]
	v_mfma_f32_16x16x32_bf16 v[68:71], v[220:223], v[228:231], v[68:71]
	v_mfma_f32_16x16x32_bf16 v[64:67], v[220:223], v[236:239], v[64:67]
	s_barrier
	s_setprio 0
	v_readfirstlane_b32 s55, v167
	v_lshl_add_u64 v[240:241], v[240:241], 0, s[42:43]
	s_mov_b32 m0, s55
	v_readfirstlane_b32 s55, v168
	ds_read_b128 v[192:195], v154 offset:49152
	ds_read_b128 v[196:199], v154 offset:50176
	ds_read_b128 v[200:203], v153 offset:49152
	ds_read_b128 v[204:207], v153 offset:50176
	ds_read_b128 v[208:211], v152 offset:49152
	ds_read_b128 v[212:215], v152 offset:50176
	ds_read_b128 v[216:219], v151 offset:49152
	ds_read_b128 v[220:223], v151 offset:50176
	global_load_lds_dwordx4 v[240:241], off
	v_lshl_add_u64 v[240:241], v[242:243], 0, s[42:43]
	s_mov_b32 m0, s55
	s_nop 0
	global_load_lds_dwordx4 v[240:241], off
	s_setprio 1
	s_barrier
; #define STAGE(P, BASE, kt) do { const char* _g = (const char*)(BASE) + (size_t)((kt) * (BK * 2)); \
;     __builtin_amdgcn_global_load_lds((const unsigned*)(_g + (size_t)goff0), (unsigned*)((char*)(P) + tid_ * 16), 16, 0, 0); \
;     __builtin_amdgcn_global_load_lds((const unsigned*)(_g + (size_t)goff1), (unsigned*)((char*)(P) + tid_ * 16 + 8192), 16, 0, 0); } while (0)
; #define STAGEA(P, BASE, kt) do { const char* _g = (const char*)(BASE) + (size_t)((kt) * a_kbytes); \
;     __builtin_amdgcn_global_load_lds((const unsigned*)(_g + (size_t)goffA0), (unsigned*)((char*)(P) + tid_ * 16), 16, 0, 0); \
;     __builtin_amdgcn_global_load_lds((const unsigned*)(_g + (size_t)goffA1), (unsigned*)((char*)(P) + tid_ * 16 + 8192), 16, 0, 0); } while (0)
; #define LDA(dst, b, h) for (int m = 0; m < 4; ++m) for (int k = 0; k < 2; ++k) \
;     dst[m][k] = *reinterpret_cast<const bf16x8*>((char*)SA(b, h) + lds_byte(wr * 64 + m * 16 + fr, k * 32 + fq * 8))
; #define LDB(dst, b, h) for (int n = 0; n < 2; ++n) for (int k = 0; k < 2; ++k) \
;     dst[n][k] = *reinterpret_cast<const bf16x8*>((char*)SB(b, h) + lds_byte(wc * 32 + n * 16 + fr, k * 32 + fq * 8))
; #define MMA(ai, bj, At, Bt) do { __builtin_amdgcn_s_setprio(1); \
;     for (int m = 0; m < 4; ++m) for (int n = 0; n < 2; ++n) for (int k = 0; k < 2; ++k) \
;       acc[ai][bj][m][n] = __builtin_amdgcn_mfma_f32_16x16x32_bf16(At[m][k], Bt[n][k], acc[ai][bj][m][n], 0, 0, 0); \
;     __builtin_amdgcn_s_setprio(0); } while (0)
; #define WAIT_V(n) asm volatile("s_waitcnt vmcnt(" #n ")" ::: "memory")
; #define WAIT_L(n) asm volatile("s_waitcnt lgkmcnt(" #n ")" ::: "memory")
; #define BAR __builtin_amdgcn_s_barrier()
; #define SCHED __builtin_amdgcn_sched_barrier(0)
; template <int EPI> ...
;     ...
;     BAR; WAIT_L(0); MMA(1, 0, At, B0); BAR; SCHED;
;     STAGE(SB(1, 1), B1p, t + 3);
;     WAIT_V(6); BAR; MMA(1, 1, At, B1); BAR;
;   }
;   { LDB(B0, 0, 0); LDA(At, 0, 0); STAGEA(SA(1, 1), A1, nt - 1);
;     BAR; WAIT_L(0); MMA(0, 0, At, B0); BAR;
;     LDB(B1, 0, 1); BAR; WAIT_L(0); MMA(0, 1, At, B1); BAR;
	s_waitcnt lgkmcnt(0)
	v_mfma_f32_16x16x32_bf16 v[60:63], v[192:195], v[176:179], v[60:63]
	v_mfma_f32_16x16x32_bf16 v[56:59], v[192:195], v[184:187], v[56:59]
	v_mfma_f32_16x16x32_bf16 v[52:55], v[200:203], v[176:179], v[52:55]
	v_mfma_f32_16x16x32_bf16 v[48:51], v[200:203], v[184:187], v[48:51]
	v_mfma_f32_16x16x32_bf16 v[44:47], v[208:211], v[176:179], v[44:47]
	v_mfma_f32_16x16x32_bf16 v[40:43], v[208:211], v[184:187], v[40:43]
	v_mfma_f32_16x16x32_bf16 v[36:39], v[216:219], v[176:179], v[36:39]
	v_mfma_f32_16x16x32_bf16 v[32:35], v[216:219], v[184:187], v[32:35]
	v_mfma_f32_16x16x32_bf16 v[60:63], v[196:199], v[180:183], v[60:63]
	v_mfma_f32_16x16x32_bf16 v[56:59], v[196:199], v[188:191], v[56:59]
	v_mfma_f32_16x16x32_bf16 v[52:55], v[204:207], v[180:183], v[52:55]
	v_mfma_f32_16x16x32_bf16 v[48:51], v[204:207], v[188:191], v[48:51]
	v_mfma_f32_16x16x32_bf16 v[44:47], v[212:215], v[180:183], v[44:47]
	v_mfma_f32_16x16x32_bf16 v[40:43], v[212:215], v[188:191], v[40:43]
	v_mfma_f32_16x16x32_bf16 v[36:39], v[220:223], v[180:183], v[36:39]
	v_mfma_f32_16x16x32_bf16 v[32:35], v[220:223], v[188:191], v[32:35]
	s_barrier
	s_setprio 0
	v_readfirstlane_b32 s55, v170
	v_lshl_add_u64 v[176:177], v[244:245], 0, s[46:47]
	s_mov_b32 m0, s55
	v_readfirstlane_b32 s55, v171
	global_load_lds_dwordx4 v[176:177], off
	v_lshl_add_u64 v[176:177], v[246:247], 0, s[46:47]
	s_mov_b32 m0, s55
	s_nop 0
	global_load_lds_dwordx4 v[176:177], off
	s_waitcnt vmcnt(6)
	s_setprio 1
	s_barrier
	v_mfma_f32_16x16x32_bf16 v[28:31], v[192:195], v[224:227], v[28:31]
	v_mfma_f32_16x16x32_bf16 v[24:27], v[192:195], v[232:235], v[24:27]
	v_mfma_f32_16x16x32_bf16 v[20:23], v[200:203], v[224:227], v[20:23]
	v_mfma_f32_16x16x32_bf16 v[16:19], v[200:203], v[232:235], v[16:19]
	v_mfma_f32_16x16x32_bf16 v[12:15], v[208:211], v[224:227], v[12:15]
	v_mfma_f32_16x16x32_bf16 v[8:11], v[208:211], v[232:235], v[8:11]
	v_mfma_f32_16x16x32_bf16 v[4:7], v[216:219], v[224:227], v[4:7]
	v_mfma_f32_16x16x32_bf16 v[0:3], v[216:219], v[232:235], v[0:3]
	v_mfma_f32_16x16x32_bf16 v[28:31], v[196:199], v[228:231], v[28:31]
	v_mfma_f32_16x16x32_bf16 v[24:27], v[196:199], v[236:239], v[24:27]
	v_mfma_f32_16x16x32_bf16 v[20:23], v[204:207], v[228:231], v[20:23]
	v_mfma_f32_16x16x32_bf16 v[16:19], v[204:207], v[236:239], v[16:19]
	v_mfma_f32_16x16x32_bf16 v[12:15], v[212:215], v[228:231], v[12:15]
	v_mfma_f32_16x16x32_bf16 v[8:11], v[212:215], v[236:239], v[8:11]
	v_mfma_f32_16x16x32_bf16 v[4:7], v[220:223], v[228:231], v[4:7]
	v_mfma_f32_16x16x32_bf16 v[0:3], v[220:223], v[236:239], v[0:3]
	s_barrier
	s_setprio 0
	s_add_i32 s53, s53, 2
	s_add_u32 s58, s58, 0x100
	s_addc_u32 s59, s59, 0
	s_cmp_lt_u32 s53, 28
	s_cbranch_scc1 .LBB0_760
	s_add_u32 s56, s56, 0x80f80
	s_addc_u32 s57, s57, 0
	v_readfirstlane_b32 s53, v173
	v_lshl_add_u64 v[166:167], s[56:57], 0, v[134:135]
	s_mov_b32 m0, s53
	v_readfirstlane_b32 s53, v174
	ds_read_b128 v[128:131], v172
	ds_read_b128 v[142:145], v172 offset:1024
	ds_read_b128 v[158:161], v172 offset:2048
	ds_read_b128 v[162:165], v172 offset:3072
	ds_read_b128 v[176:179], v154
	ds_read_b128 v[180:183], v154 offset:1024
	ds_read_b128 v[184:187], v153
	ds_read_b128 v[188:191], v153 offset:1024
	ds_read_b128 v[192:195], v152
	ds_read_b128 v[196:199], v152 offset:1024
	ds_read_b128 v[200:203], v151
	ds_read_b128 v[204:207], v151 offset:1024
	global_load_lds_dwordx4 v[166:167], off
	v_lshl_add_u64 v[166:167], s[56:57], 0, v[132:133]
	s_mov_b32 m0, s53
	s_nop 0
	global_load_lds_dwordx4 v[166:167], off
	s_setprio 1
	s_barrier
	s_waitcnt lgkmcnt(0)
	v_mfma_f32_16x16x32_bf16 v[124:127], v[176:179], v[128:131], v[124:127]
	v_mfma_f32_16x16x32_bf16 v[120:123], v[176:179], v[158:161], v[120:123]
	v_mfma_f32_16x16x32_bf16 v[108:111], v[192:195], v[128:131], v[108:111]
	v_mfma_f32_16x16x32_bf16 v[104:107], v[192:195], v[158:161], v[104:107]
	v_mfma_f32_16x16x32_bf16 v[124:127], v[180:183], v[142:145], v[124:127]
	v_mfma_f32_16x16x32_bf16 v[120:123], v[180:183], v[162:165], v[120:123]
	v_mfma_f32_16x16x32_bf16 v[116:119], v[184:187], v[128:131], v[116:119]
	v_mfma_f32_16x16x32_bf16 v[112:115], v[184:187], v[158:161], v[112:115]
	v_mfma_f32_16x16x32_bf16 v[108:111], v[196:199], v[142:145], v[108:111]
	v_mfma_f32_16x16x32_bf16 v[104:107], v[196:199], v[162:165], v[104:107]
	v_mfma_f32_16x16x32_bf16 v[100:103], v[200:203], v[128:131], v[100:103]
	v_mfma_f32_16x16x32_bf16 v[96:99], v[200:203], v[158:161], v[96:99]
	v_mfma_f32_16x16x32_bf16 v[170:173], v[188:191], v[142:145], v[116:119]
	v_mfma_f32_16x16x32_bf16 v[208:211], v[188:191], v[162:165], v[112:115]
	v_mfma_f32_16x16x32_bf16 v[212:215], v[204:207], v[142:145], v[100:103]
	v_mfma_f32_16x16x32_bf16 v[216:219], v[204:207], v[162:165], v[96:99]
	s_barrier
	s_setprio 0
	s_nop 1
	ds_read_b128 v[96:99], v169
	ds_read_b128 v[100:103], v169 offset:1024
	ds_read_b128 v[112:115], v169 offset:2048
	ds_read_b128 v[116:119], v169 offset:3072
	s_setprio 1
	s_barrier
	s_waitcnt lgkmcnt(0)
	v_mfma_f32_16x16x32_bf16 v[92:95], v[176:179], v[96:99], v[92:95]
	v_mfma_f32_16x16x32_bf16 v[88:91], v[176:179], v[112:115], v[88:91]
	v_mfma_f32_16x16x32_bf16 v[76:79], v[192:195], v[96:99], v[76:79]
	v_mfma_f32_16x16x32_bf16 v[72:75], v[192:195], v[112:115], v[72:75]
	v_mfma_f32_16x16x32_bf16 v[92:95], v[180:183], v[100:103], v[92:95]
	v_mfma_f32_16x16x32_bf16 v[88:91], v[180:183], v[116:119], v[88:91]
	v_mfma_f32_16x16x32_bf16 v[84:87], v[184:187], v[96:99], v[84:87]
	v_mfma_f32_16x16x32_bf16 v[80:83], v[184:187], v[112:115], v[80:83]
	v_mfma_f32_16x16x32_bf16 v[76:79], v[196:199], v[100:103], v[76:79]
	v_mfma_f32_16x16x32_bf16 v[72:75], v[196:199], v[116:119], v[72:75]
	v_mfma_f32_16x16x32_bf16 v[68:71], v[200:203], v[96:99], v[68:71]
	v_mfma_f32_16x16x32_bf16 v[64:67], v[200:203], v[112:115], v[64:67]
	v_mfma_f32_16x16x32_bf16 v[166:169], v[188:191], v[100:103], v[84:87]
	v_mfma_f32_16x16x32_bf16 v[174:177], v[188:191], v[116:119], v[80:83]
	v_mfma_f32_16x16x32_bf16 v[178:181], v[204:207], v[100:103], v[68:71]
	v_mfma_f32_16x16x32_bf16 v[182:185], v[204:207], v[116:119], v[64:67]
	s_barrier
; #define LDA(dst, b, h) for (int m = 0; m < 4; ++m) for (int k = 0; k < 2; ++k) \
;     dst[m][k] = *reinterpret_cast<const bf16x8*>((char*)SA(b, h) + lds_byte(wr * 64 + m * 16 + fr, k * 32 + fq * 8))
; #define LDB(dst, b, h) for (int n = 0; n < 2; ++n) for (int k = 0; k < 2; ++k) \
;     dst[n][k] = *reinterpret_cast<const bf16x8*>((char*)SB(b, h) + lds_byte(wc * 32 + n * 16 + fr, k * 32 + fq * 8))
; #define MMA(ai, bj, At, Bt) do { __builtin_amdgcn_s_setprio(1); \
;     for (int m = 0; m < 4; ++m) for (int n = 0; n < 2; ++n) for (int k = 0; k < 2; ++k) \
;       acc[ai][bj][m][n] = __builtin_amdgcn_mfma_f32_16x16x32_bf16(At[m][k], Bt[n][k], acc[ai][bj][m][n], 0, 0, 0); \
;     __builtin_amdgcn_s_setprio(0); } while (0)
; #define WAIT_V(n) asm volatile("s_waitcnt vmcnt(" #n ")" ::: "memory")
; #define WAIT_L(n) asm volatile("s_waitcnt lgkmcnt(" #n ")" ::: "memory")
; #define BAR __builtin_amdgcn_s_barrier()
; template <int EPI> ...
;     ...
;     LDA(At, 0, 1); WAIT_V(4); BAR; WAIT_L(0); MMA(1, 0, At, B0); MMA(1, 1, At, B1); BAR; }
;   { LDB(B0, 1, 0); LDA(At, 1, 0); WAIT_V(2); BAR; WAIT_L(0); MMA(0, 0, At, B0); BAR;
	s_setprio 0
	s_nop 1
	ds_read_b128 v[64:67], v154 offset:16384
	ds_read_b128 v[68:71], v154 offset:17408
	ds_read_b128 v[80:83], v153 offset:16384
	ds_read_b128 v[84:87], v153 offset:17408
	ds_read_b128 v[186:189], v152 offset:16384
	ds_read_b128 v[190:193], v152 offset:17408
	ds_read_b128 v[194:197], v151 offset:16384
	ds_read_b128 v[198:201], v151 offset:17408
	s_waitcnt vmcnt(4)
	s_setprio 1
	s_barrier
	s_waitcnt lgkmcnt(0)
	v_mfma_f32_16x16x32_bf16 v[60:63], v[64:67], v[128:131], v[60:63]
	v_mfma_f32_16x16x32_bf16 v[52:55], v[80:83], v[128:131], v[52:55]
	v_mfma_f32_16x16x32_bf16 v[44:47], v[186:189], v[128:131], v[44:47]
	v_mfma_f32_16x16x32_bf16 v[36:39], v[194:197], v[128:131], v[36:39]
	v_mfma_f32_16x16x32_bf16 v[60:63], v[68:71], v[142:145], v[60:63]
	v_mfma_f32_16x16x32_bf16 v[56:59], v[64:67], v[158:161], v[56:59]
	v_mfma_f32_16x16x32_bf16 v[52:55], v[84:87], v[142:145], v[52:55]
	v_mfma_f32_16x16x32_bf16 v[48:51], v[80:83], v[158:161], v[48:51]
	v_mfma_f32_16x16x32_bf16 v[44:47], v[190:193], v[142:145], v[44:47]
	v_mfma_f32_16x16x32_bf16 v[40:43], v[186:189], v[158:161], v[40:43]
	v_mfma_f32_16x16x32_bf16 v[36:39], v[198:201], v[142:145], v[36:39]
	v_mfma_f32_16x16x32_bf16 v[32:35], v[194:197], v[158:161], v[32:35]
	v_mfma_f32_16x16x32_bf16 v[202:205], v[68:71], v[162:165], v[56:59]
	v_mfma_f32_16x16x32_bf16 v[220:223], v[84:87], v[162:165], v[48:51]
	v_mfma_f32_16x16x32_bf16 v[224:227], v[190:193], v[162:165], v[40:43]
	v_mfma_f32_16x16x32_bf16 v[128:131], v[198:201], v[162:165], v[32:35]
	s_setprio 0
	s_setprio 1
	v_mfma_f32_16x16x32_bf16 v[28:31], v[64:67], v[96:99], v[28:31]
	v_mfma_f32_16x16x32_bf16 v[20:23], v[80:83], v[96:99], v[20:23]
	v_mfma_f32_16x16x32_bf16 v[12:15], v[186:189], v[96:99], v[12:15]
	v_mfma_f32_16x16x32_bf16 v[4:7], v[194:197], v[96:99], v[4:7]
	v_mfma_f32_16x16x32_bf16 v[28:31], v[68:71], v[100:103], v[28:31]
	v_mfma_f32_16x16x32_bf16 v[24:27], v[64:67], v[112:115], v[24:27]
	v_mfma_f32_16x16x32_bf16 v[20:23], v[84:87], v[100:103], v[20:23]
	v_mfma_f32_16x16x32_bf16 v[16:19], v[80:83], v[112:115], v[16:19]
	v_mfma_f32_16x16x32_bf16 v[12:15], v[190:193], v[100:103], v[12:15]
	v_mfma_f32_16x16x32_bf16 v[8:11], v[186:189], v[112:115], v[8:11]
	v_mfma_f32_16x16x32_bf16 v[4:7], v[198:201], v[100:103], v[4:7]
	v_mfma_f32_16x16x32_bf16 v[0:3], v[194:197], v[112:115], v[0:3]
	v_mfma_f32_16x16x32_bf16 v[142:145], v[68:71], v[116:119], v[24:27]
	v_mfma_f32_16x16x32_bf16 v[158:161], v[84:87], v[116:119], v[16:19]
	v_mfma_f32_16x16x32_bf16 v[162:165], v[190:193], v[116:119], v[8:11]
	v_mfma_f32_16x16x32_bf16 v[186:189], v[198:201], v[116:119], v[0:3]
	s_barrier
	s_setprio 0
	s_nop 1
	ds_read_b128 v[0:3], v157
	ds_read_b128 v[8:11], v157 offset:1024
	ds_read_b128 v[190:193], v157 offset:2048
	ds_read_b128 v[194:197], v157 offset:3072
	ds_read_b128 v[16:19], v154 offset:32768
	ds_read_b128 v[24:27], v154 offset:33792
	ds_read_b128 v[32:35], v153 offset:32768
	ds_read_b128 v[40:43], v153 offset:33792
	ds_read_b128 v[48:51], v152 offset:32768
	ds_read_b128 v[56:59], v152 offset:33792
	ds_read_b128 v[198:201], v151 offset:32768
	ds_read_b128 v[228:231], v151 offset:33792
	s_waitcnt vmcnt(2)
	s_setprio 1
	s_barrier
	s_waitcnt lgkmcnt(0)
	v_mfma_f32_16x16x32_bf16 v[64:67], v[16:19], v[0:3], v[124:127]
	v_mfma_f32_16x16x32_bf16 v[116:119], v[24:27], v[8:11], v[64:67]
	v_mfma_f32_16x16x32_bf16 v[64:67], v[16:19], v[190:193], v[120:123]
	v_mfma_f32_16x16x32_bf16 v[112:115], v[24:27], v[194:197], v[64:67]
	v_mfma_f32_16x16x32_bf16 v[64:67], v[32:35], v[0:3], v[170:173]
	v_mfma_f32_16x16x32_bf16 v[100:103], v[40:43], v[8:11], v[64:67]
	v_mfma_f32_16x16x32_bf16 v[64:67], v[32:35], v[190:193], v[208:211]
	v_mfma_f32_16x16x32_bf16 v[96:99], v[40:43], v[194:197], v[64:67]
	v_mfma_f32_16x16x32_bf16 v[64:67], v[48:51], v[0:3], v[108:111]
	v_mfma_f32_16x16x32_bf16 v[84:87], v[56:59], v[8:11], v[64:67]
	v_mfma_f32_16x16x32_bf16 v[64:67], v[48:51], v[190:193], v[104:107]
	v_mfma_f32_16x16x32_bf16 v[80:83], v[56:59], v[194:197], v[64:67]
	v_mfma_f32_16x16x32_bf16 v[64:67], v[198:201], v[0:3], v[212:215]
	v_mfma_f32_16x16x32_bf16 v[68:71], v[228:231], v[8:11], v[64:67]
	v_mfma_f32_16x16x32_bf16 v[64:67], v[198:201], v[190:193], v[216:219]
	v_mfma_f32_16x16x32_bf16 v[64:67], v[228:231], v[194:197], v[64:67]
	s_barrier
; #define LDA(dst, b, h) for (int m = 0; m < 4; ++m) for (int k = 0; k < 2; ++k) \
;     dst[m][k] = *reinterpret_cast<const bf16x8*>((char*)SA(b, h) + lds_byte(wr * 64 + m * 16 + fr, k * 32 + fq * 8))
; #define LDB(dst, b, h) for (int n = 0; n < 2; ++n) for (int k = 0; k < 2; ++k) \
;     dst[n][k] = *reinterpret_cast<const bf16x8*>((char*)SB(b, h) + lds_byte(wc * 32 + n * 16 + fr, k * 32 + fq * 8))
; #define MMA(ai, bj, At, Bt) do { __builtin_amdgcn_s_setprio(1); \
;     for (int m = 0; m < 4; ++m) for (int n = 0; n < 2; ++n) for (int k = 0; k < 2; ++k) \
;       acc[ai][bj][m][n] = __builtin_amdgcn_mfma_f32_16x16x32_bf16(At[m][k], Bt[n][k], acc[ai][bj][m][n], 0, 0, 0); \
;     __builtin_amdgcn_s_setprio(0); } while (0)
; #define WAIT_V(n) asm volatile("s_waitcnt vmcnt(" #n ")" ::: "memory")
; #define WAIT_L(n) asm volatile("s_waitcnt lgkmcnt(" #n ")" ::: "memory")
; #define BAR __builtin_amdgcn_s_barrier()
; template <int EPI> ...
;     ...
;   { LDB(B0, 1, 0); LDA(At, 1, 0); WAIT_V(2); BAR; WAIT_L(0); MMA(0, 0, At, B0); BAR;
;     LDB(B1, 1, 1); WAIT_V(0); BAR; WAIT_L(0); MMA(0, 1, At, B1); BAR;
;     LDA(At, 1, 1); BAR; WAIT_L(0); MMA(1, 0, At, B0); MMA(1, 1, At, B1); BAR; }
;   if (wr == 0) BAR;
	s_setprio 0
	ds_read_b128 v[170:173], v155
	ds_read_b128 v[206:209], v155 offset:1024
	ds_read_b128 v[210:213], v155 offset:2048
	ds_read_b128 v[214:217], v155 offset:3072
	s_waitcnt vmcnt(0)
	s_setprio 1
	s_barrier
	s_waitcnt lgkmcnt(0)
	v_mfma_f32_16x16x32_bf16 v[92:95], v[16:19], v[170:173], v[92:95]
	v_mfma_f32_16x16x32_bf16 v[16:19], v[16:19], v[210:213], v[88:91]
	v_mfma_f32_16x16x32_bf16 v[120:123], v[24:27], v[214:217], v[16:19]
	v_mfma_f32_16x16x32_bf16 v[16:19], v[32:35], v[170:173], v[166:169]
	v_mfma_f32_16x16x32_bf16 v[108:111], v[40:43], v[206:209], v[16:19]
	v_mfma_f32_16x16x32_bf16 v[16:19], v[32:35], v[210:213], v[174:177]
	v_mfma_f32_16x16x32_bf16 v[104:107], v[40:43], v[214:217], v[16:19]
	v_mfma_f32_16x16x32_bf16 v[16:19], v[48:51], v[170:173], v[76:79]
	v_mfma_f32_16x16x32_bf16 v[124:127], v[24:27], v[206:209], v[92:95]
	v_mfma_f32_16x16x32_bf16 v[92:95], v[56:59], v[206:209], v[16:19]
	v_mfma_f32_16x16x32_bf16 v[16:19], v[48:51], v[210:213], v[72:75]
	v_mfma_f32_16x16x32_bf16 v[88:91], v[56:59], v[214:217], v[16:19]
	v_mfma_f32_16x16x32_bf16 v[16:19], v[198:201], v[170:173], v[178:181]
	v_mfma_f32_16x16x32_bf16 v[76:79], v[228:231], v[206:209], v[16:19]
	v_mfma_f32_16x16x32_bf16 v[16:19], v[198:201], v[210:213], v[182:185]
	v_mfma_f32_16x16x32_bf16 v[72:75], v[228:231], v[214:217], v[16:19]
	s_barrier
	s_setprio 0
	ds_read_b128 v[166:169], v154 offset:49152
	ds_read_b128 v[154:157], v154 offset:50176
	ds_read_b128 v[174:177], v153 offset:49152
	ds_read_b128 v[178:181], v153 offset:50176
	ds_read_b128 v[182:185], v152 offset:49152
	ds_read_b128 v[198:201], v152 offset:50176
	ds_read_b128 v[228:231], v151 offset:49152
	ds_read_b128 v[232:235], v151 offset:50176
	s_setprio 1
	s_barrier
	s_waitcnt lgkmcnt(0)
	v_mfma_f32_16x16x32_bf16 v[16:19], v[166:169], v[0:3], v[60:63]
	v_mfma_f32_16x16x32_bf16 v[56:59], v[154:157], v[8:11], v[16:19]
	v_mfma_f32_16x16x32_bf16 v[16:19], v[166:169], v[190:193], v[202:205]
	v_mfma_f32_16x16x32_bf16 v[48:51], v[154:157], v[194:197], v[16:19]
	v_mfma_f32_16x16x32_bf16 v[16:19], v[174:177], v[0:3], v[52:55]
	v_mfma_f32_16x16x32_bf16 v[40:43], v[178:181], v[8:11], v[16:19]
	v_mfma_f32_16x16x32_bf16 v[16:19], v[174:177], v[190:193], v[220:223]
	v_mfma_f32_16x16x32_bf16 v[32:35], v[178:181], v[194:197], v[16:19]
	v_mfma_f32_16x16x32_bf16 v[16:19], v[182:185], v[0:3], v[44:47]
	v_mfma_f32_16x16x32_bf16 v[0:3], v[228:231], v[0:3], v[36:39]
	v_mfma_f32_16x16x32_bf16 v[24:27], v[198:201], v[8:11], v[16:19]
	v_mfma_f32_16x16x32_bf16 v[16:19], v[182:185], v[190:193], v[224:227]
	v_mfma_f32_16x16x32_bf16 v[8:11], v[232:235], v[8:11], v[0:3]
	v_mfma_f32_16x16x32_bf16 v[0:3], v[228:231], v[190:193], v[128:131]
	v_mfma_f32_16x16x32_bf16 v[16:19], v[198:201], v[194:197], v[16:19]
	v_mfma_f32_16x16x32_bf16 v[0:3], v[232:235], v[194:197], v[0:3]
	s_setprio 0
	s_setprio 1
	v_mfma_f32_16x16x32_bf16 v[28:31], v[166:169], v[170:173], v[28:31]
	v_mfma_f32_16x16x32_bf16 v[60:63], v[154:157], v[206:209], v[28:31]
	v_mfma_f32_16x16x32_bf16 v[28:31], v[166:169], v[210:213], v[142:145]
	v_mfma_f32_16x16x32_bf16 v[20:23], v[174:177], v[170:173], v[20:23]
	v_mfma_f32_16x16x32_bf16 v[12:15], v[182:185], v[170:173], v[12:15]
	v_mfma_f32_16x16x32_bf16 v[52:55], v[154:157], v[214:217], v[28:31]
	v_mfma_f32_16x16x32_bf16 v[44:47], v[178:181], v[206:209], v[20:23]
	v_mfma_f32_16x16x32_bf16 v[20:23], v[174:177], v[210:213], v[158:161]
	v_mfma_f32_16x16x32_bf16 v[28:31], v[198:201], v[206:209], v[12:15]
	v_mfma_f32_16x16x32_bf16 v[12:15], v[182:185], v[210:213], v[162:165]
	v_mfma_f32_16x16x32_bf16 v[4:7], v[228:231], v[170:173], v[4:7]
	v_mfma_f32_16x16x32_bf16 v[36:39], v[178:181], v[214:217], v[20:23]
	v_mfma_f32_16x16x32_bf16 v[20:23], v[198:201], v[214:217], v[12:15]
	v_mfma_f32_16x16x32_bf16 v[12:15], v[232:235], v[206:209], v[4:7]
	v_mfma_f32_16x16x32_bf16 v[4:7], v[228:231], v[210:213], v[186:189]
	v_mfma_f32_16x16x32_bf16 v[4:7], v[232:235], v[214:217], v[4:7]
	s_barrier
	s_setprio 0
	v_cmp_gt_u32_e32 vcc, s86, v136
	s_and_saveexec_b64 s[56:57], vcc
	s_cbranch_execz .LBB0_763
	s_barrier

; #define STAGE(P, BASE, kt) do { const char* _g = (const char*)(BASE) + (size_t)((kt) * (BK * 2)); \
;     __builtin_amdgcn_global_load_lds((const unsigned*)(_g + (size_t)goff0), (unsigned*)((char*)(P) + tid_ * 16), 16, 0, 0); \
;     __builtin_amdgcn_global_load_lds((const unsigned*)(_g + (size_t)goff1), (unsigned*)((char*)(P) + tid_ * 16 + 8192), 16, 0, 0); } while (0)
; #define STAGEA(P, BASE, kt) do { const char* _g = (const char*)(BASE) + (size_t)((kt) * a_kbytes); \
;     __builtin_amdgcn_global_load_lds((const unsigned*)(_g + (size_t)goffA0), (unsigned*)((char*)(P) + tid_ * 16), 16, 0, 0); \
;     __builtin_amdgcn_global_load_lds((const unsigned*)(_g + (size_t)goffA1), (unsigned*)((char*)(P) + tid_ * 16 + 8192), 16, 0, 0); } while (0)
; #define LDA(dst, b, h) for (int m = 0; m < 4; ++m) for (int k = 0; k < 2; ++k) \
;     dst[m][k] = *reinterpret_cast<const bf16x8*>((char*)SA(b, h) + lds_byte(wr * 64 + m * 16 + fr, k * 32 + fq * 8))
; #define LDB(dst, b, h) for (int n = 0; n < 2; ++n) for (int k = 0; k < 2; ++k) \
;     dst[n][k] = *reinterpret_cast<const bf16x8*>((char*)SB(b, h) + lds_byte(wc * 32 + n * 16 + fr, k * 32 + fq * 8))
; #define MMA(ai, bj, At, Bt) do { __builtin_amdgcn_s_setprio(1); \
;     for (int m = 0; m < 4; ++m) for (int n = 0; n < 2; ++n) for (int k = 0; k < 2; ++k) \
;       acc[ai][bj][m][n] = __builtin_amdgcn_mfma_f32_16x16x32_bf16(At[m][k], Bt[n][k], acc[ai][bj][m][n], 0, 0, 0); \
;     __builtin_amdgcn_s_setprio(0); } while (0)
; #define WAIT_L(n) asm volatile("s_waitcnt lgkmcnt(" #n ")" ::: "memory")
; #define BAR __builtin_amdgcn_s_barrier()
; #define SCHED __builtin_amdgcn_sched_barrier(0)
; template <int EPI> ...
;     ...
;   for (int t = 0; t < nt - 2; t += 2) {
;     LDB(B0, 0, 0); SCHED; LDA(At, 0, 0); STAGEA(SA(1, 1), A1, t + 1);
;     WAIT_L(8); BAR; WAIT_L(0); MMA(0, 0, At, B0); BAR; SCHED;
;     LDB(B1, 0, 1); STAGE(SB(0, 0), B0p, t + 2);
;     BAR; WAIT_L(0); MMA(0, 1, At, B1); BAR;
;     LDA(At, 0, 1); STAGEA(SA(0, 0), A0, t + 2);
;     BAR; WAIT_L(0); MMA(1, 0, At, B0); BAR; SCHED;
.LBB0_782:
	ds_read_b128 v[174:177], v171
	ds_read_b128 v[178:181], v171 offset:1024
	ds_read_b128 v[182:185], v171 offset:2048
	ds_read_b128 v[186:189], v171 offset:3072
	v_add_u32_e32 v172, 0xc000, v158
	v_lshl_add_u64 v[238:239], s[54:55], 0, v[136:137]
	v_readfirstlane_b32 s86, v172
	v_add_u32_e32 v173, 0xe000, v158
	v_lshl_add_u64 v[222:223], v[238:239], 0, s[4:5]
	s_mov_b32 m0, s86
	v_lshl_add_u64 v[240:241], s[54:55], 0, v[138:139]
	v_readfirstlane_b32 s86, v173
	ds_read_b128 v[190:193], v153
	ds_read_b128 v[194:197], v153 offset:1024
	ds_read_b128 v[198:201], v152
	ds_read_b128 v[202:205], v152 offset:1024
	ds_read_b128 v[206:209], v151
	ds_read_b128 v[210:213], v151 offset:1024
	ds_read_b128 v[214:217], v150
	ds_read_b128 v[218:221], v150 offset:1024
	global_load_lds_dwordx4 v[222:223], off
	v_lshl_add_u64 v[222:223], v[240:241], 0, s[4:5]
	s_mov_b32 m0, s86
	s_nop 0
	global_load_lds_dwordx4 v[222:223], off
	s_waitcnt lgkmcnt(8)
	s_setprio 1
	s_barrier
	s_waitcnt lgkmcnt(0)
	v_mfma_f32_16x16x32_bf16 v[124:127], v[190:193], v[174:177], v[124:127]
	v_mfma_f32_16x16x32_bf16 v[120:123], v[190:193], v[182:185], v[120:123]
	v_mfma_f32_16x16x32_bf16 v[116:119], v[198:201], v[174:177], v[116:119]
	v_mfma_f32_16x16x32_bf16 v[112:115], v[198:201], v[182:185], v[112:115]
	v_mfma_f32_16x16x32_bf16 v[108:111], v[206:209], v[174:177], v[108:111]
	v_mfma_f32_16x16x32_bf16 v[104:107], v[206:209], v[182:185], v[104:107]
	v_mfma_f32_16x16x32_bf16 v[100:103], v[214:217], v[174:177], v[100:103]
	v_mfma_f32_16x16x32_bf16 v[96:99], v[214:217], v[182:185], v[96:99]
	v_mfma_f32_16x16x32_bf16 v[124:127], v[194:197], v[178:181], v[124:127]
	v_mfma_f32_16x16x32_bf16 v[120:123], v[194:197], v[186:189], v[120:123]
	v_mfma_f32_16x16x32_bf16 v[116:119], v[202:205], v[178:181], v[116:119]
	v_mfma_f32_16x16x32_bf16 v[112:115], v[202:205], v[186:189], v[112:115]
	v_mfma_f32_16x16x32_bf16 v[108:111], v[210:213], v[178:181], v[108:111]
	v_mfma_f32_16x16x32_bf16 v[104:107], v[210:213], v[186:189], v[104:107]
	v_mfma_f32_16x16x32_bf16 v[100:103], v[218:221], v[178:181], v[100:103]
	v_mfma_f32_16x16x32_bf16 v[96:99], v[218:221], v[186:189], v[96:99]
	s_barrier
	s_setprio 0
	v_lshl_add_u64 v[242:243], s[52:53], 0, v[140:141]
	v_readfirstlane_b32 s86, v155
	v_lshl_add_u64 v[244:245], v[242:243], 0, s[6:7]
	s_mov_b32 m0, s86
	ds_read_b128 v[222:225], v167
	ds_read_b128 v[226:229], v167 offset:1024
	ds_read_b128 v[230:233], v167 offset:2048
	ds_read_b128 v[234:237], v167 offset:3072
	global_load_lds_dwordx4 v[244:245], off
	v_lshl_add_u64 v[244:245], s[52:53], 0, v[142:143]
	v_readfirstlane_b32 s86, v157
	v_lshl_add_u64 v[246:247], v[244:245], 0, s[6:7]
	s_mov_b32 m0, s86
	s_nop 0
	global_load_lds_dwordx4 v[246:247], off
	s_setprio 1
	s_barrier
	s_waitcnt lgkmcnt(0)
	v_mfma_f32_16x16x32_bf16 v[92:95], v[190:193], v[222:225], v[92:95]
	v_mfma_f32_16x16x32_bf16 v[88:91], v[190:193], v[230:233], v[88:91]
	v_mfma_f32_16x16x32_bf16 v[84:87], v[198:201], v[222:225], v[84:87]
	v_mfma_f32_16x16x32_bf16 v[80:83], v[198:201], v[230:233], v[80:83]
	v_mfma_f32_16x16x32_bf16 v[76:79], v[206:209], v[222:225], v[76:79]
	v_mfma_f32_16x16x32_bf16 v[72:75], v[206:209], v[230:233], v[72:75]
	v_mfma_f32_16x16x32_bf16 v[68:71], v[214:217], v[222:225], v[68:71]
	v_mfma_f32_16x16x32_bf16 v[64:67], v[214:217], v[230:233], v[64:67]
	v_mfma_f32_16x16x32_bf16 v[92:95], v[194:197], v[226:229], v[92:95]
	v_mfma_f32_16x16x32_bf16 v[88:91], v[194:197], v[234:237], v[88:91]
	v_mfma_f32_16x16x32_bf16 v[84:87], v[202:205], v[226:229], v[84:87]
	v_mfma_f32_16x16x32_bf16 v[80:83], v[202:205], v[234:237], v[80:83]
	v_mfma_f32_16x16x32_bf16 v[76:79], v[210:213], v[226:229], v[76:79]
	v_mfma_f32_16x16x32_bf16 v[72:75], v[210:213], v[234:237], v[72:75]
	v_mfma_f32_16x16x32_bf16 v[68:71], v[218:221], v[226:229], v[68:71]
	v_mfma_f32_16x16x32_bf16 v[64:67], v[218:221], v[234:237], v[64:67]
	s_barrier
	s_setprio 0
	v_readfirstlane_b32 s86, v158
	v_lshl_add_u64 v[246:247], v[238:239], 0, s[8:9]
	s_mov_b32 m0, s86
	v_readfirstlane_b32 s86, v159
	ds_read_b128 v[190:193], v153 offset:16384
	ds_read_b128 v[194:197], v153 offset:17408
	ds_read_b128 v[198:201], v152 offset:16384
	ds_read_b128 v[202:205], v152 offset:17408
	ds_read_b128 v[206:209], v151 offset:16384
	ds_read_b128 v[210:213], v151 offset:17408
	ds_read_b128 v[214:217], v150 offset:16384
	ds_read_b128 v[218:221], v150 offset:17408
	global_load_lds_dwordx4 v[246:247], off
	v_lshl_add_u64 v[246:247], v[240:241], 0, s[8:9]
	s_mov_b32 m0, s86
	s_nop 0
	global_load_lds_dwordx4 v[246:247], off
	s_setprio 1
	s_barrier
	s_waitcnt lgkmcnt(0)
	v_mfma_f32_16x16x32_bf16 v[60:63], v[190:193], v[174:177], v[60:63]
	v_mfma_f32_16x16x32_bf16 v[56:59], v[190:193], v[182:185], v[56:59]
	v_mfma_f32_16x16x32_bf16 v[52:55], v[198:201], v[174:177], v[52:55]
	v_mfma_f32_16x16x32_bf16 v[48:51], v[198:201], v[182:185], v[48:51]
	v_mfma_f32_16x16x32_bf16 v[44:47], v[206:209], v[174:177], v[44:47]
	v_mfma_f32_16x16x32_bf16 v[40:43], v[206:209], v[182:185], v[40:43]
	v_mfma_f32_16x16x32_bf16 v[36:39], v[214:217], v[174:177], v[36:39]
	v_mfma_f32_16x16x32_bf16 v[32:35], v[214:217], v[182:185], v[32:35]
	v_mfma_f32_16x16x32_bf16 v[60:63], v[194:197], v[178:181], v[60:63]
	v_mfma_f32_16x16x32_bf16 v[56:59], v[194:197], v[186:189], v[56:59]
	v_mfma_f32_16x16x32_bf16 v[52:55], v[202:205], v[178:181], v[52:55]
	v_mfma_f32_16x16x32_bf16 v[48:51], v[202:205], v[186:189], v[48:51]
	v_mfma_f32_16x16x32_bf16 v[44:47], v[210:213], v[178:181], v[44:47]
	v_mfma_f32_16x16x32_bf16 v[40:43], v[210:213], v[186:189], v[40:43]
	v_mfma_f32_16x16x32_bf16 v[36:39], v[218:221], v[178:181], v[36:39]
	v_mfma_f32_16x16x32_bf16 v[32:35], v[218:221], v[186:189], v[32:35]
	s_barrier
; #define STAGE(P, BASE, kt) do { const char* _g = (const char*)(BASE) + (size_t)((kt) * (BK * 2)); \
;     __builtin_amdgcn_global_load_lds((const unsigned*)(_g + (size_t)goff0), (unsigned*)((char*)(P) + tid_ * 16), 16, 0, 0); \
;     __builtin_amdgcn_global_load_lds((const unsigned*)(_g + (size_t)goff1), (unsigned*)((char*)(P) + tid_ * 16 + 8192), 16, 0, 0); } while (0)
; #define STAGEA(P, BASE, kt) do { const char* _g = (const char*)(BASE) + (size_t)((kt) * a_kbytes); \
;     __builtin_amdgcn_global_load_lds((const unsigned*)(_g + (size_t)goffA0), (unsigned*)((char*)(P) + tid_ * 16), 16, 0, 0); \
;     __builtin_amdgcn_global_load_lds((const unsigned*)(_g + (size_t)goffA1), (unsigned*)((char*)(P) + tid_ * 16 + 8192), 16, 0, 0); } while (0)
; #define LDA(dst, b, h) for (int m = 0; m < 4; ++m) for (int k = 0; k < 2; ++k) \
;     dst[m][k] = *reinterpret_cast<const bf16x8*>((char*)SA(b, h) + lds_byte(wr * 64 + m * 16 + fr, k * 32 + fq * 8))
; #define LDB(dst, b, h) for (int n = 0; n < 2; ++n) for (int k = 0; k < 2; ++k) \
;     dst[n][k] = *reinterpret_cast<const bf16x8*>((char*)SB(b, h) + lds_byte(wc * 32 + n * 16 + fr, k * 32 + fq * 8))
; #define MMA(ai, bj, At, Bt) do { __builtin_amdgcn_s_setprio(1); \
;     for (int m = 0; m < 4; ++m) for (int n = 0; n < 2; ++n) for (int k = 0; k < 2; ++k) \
;       acc[ai][bj][m][n] = __builtin_amdgcn_mfma_f32_16x16x32_bf16(At[m][k], Bt[n][k], acc[ai][bj][m][n], 0, 0, 0); \
;     __builtin_amdgcn_s_setprio(0); } while (0)
; #define WAIT_V(n) asm volatile("s_waitcnt vmcnt(" #n ")" ::: "memory")
; #define WAIT_L(n) asm volatile("s_waitcnt lgkmcnt(" #n ")" ::: "memory")
; #define BAR __builtin_amdgcn_s_barrier()
; #define SCHED __builtin_amdgcn_sched_barrier(0)
; template <int EPI> ...
;     ...
;     STAGE(SB(0, 1), B1p, t + 2);
;     WAIT_V(6); BAR; MMA(1, 1, At, B1); BAR;
;     LDB(B0, 1, 0); SCHED; LDA(At, 1, 0); STAGEA(SA(0, 1), A1, t + 2);
;     WAIT_L(8); BAR; WAIT_L(0); MMA(0, 0, At, B0); BAR; SCHED;
;     LDB(B1, 1, 1); STAGE(SB(1, 0), B0p, t + 3);
;     BAR; WAIT_L(0); MMA(0, 1, At, B1); BAR;
;     LDA(At, 1, 1); STAGEA(SA(1, 0), A0, t + 3);
	s_setprio 0
	v_readfirstlane_b32 s86, v160
	v_lshl_add_u64 v[174:175], v[242:243], 0, s[10:11]
	s_mov_b32 m0, s86
	v_readfirstlane_b32 s86, v161
	global_load_lds_dwordx4 v[174:175], off
	v_lshl_add_u64 v[174:175], v[244:245], 0, s[10:11]
	s_mov_b32 m0, s86
	s_nop 0
	global_load_lds_dwordx4 v[174:175], off
	s_waitcnt vmcnt(6)
	s_setprio 1
	s_barrier
	v_mfma_f32_16x16x32_bf16 v[28:31], v[190:193], v[222:225], v[28:31]
	v_mfma_f32_16x16x32_bf16 v[24:27], v[190:193], v[230:233], v[24:27]
	v_mfma_f32_16x16x32_bf16 v[20:23], v[198:201], v[222:225], v[20:23]
	v_mfma_f32_16x16x32_bf16 v[16:19], v[198:201], v[230:233], v[16:19]
	v_mfma_f32_16x16x32_bf16 v[12:15], v[206:209], v[222:225], v[12:15]
	v_mfma_f32_16x16x32_bf16 v[8:11], v[206:209], v[230:233], v[8:11]
	v_mfma_f32_16x16x32_bf16 v[4:7], v[214:217], v[222:225], v[4:7]
	v_mfma_f32_16x16x32_bf16 v[0:3], v[214:217], v[230:233], v[0:3]
	v_mfma_f32_16x16x32_bf16 v[28:31], v[194:197], v[226:229], v[28:31]
	v_mfma_f32_16x16x32_bf16 v[24:27], v[194:197], v[234:237], v[24:27]
	v_mfma_f32_16x16x32_bf16 v[20:23], v[202:205], v[226:229], v[20:23]
	v_mfma_f32_16x16x32_bf16 v[16:19], v[202:205], v[234:237], v[16:19]
	v_mfma_f32_16x16x32_bf16 v[12:15], v[210:213], v[226:229], v[12:15]
	v_mfma_f32_16x16x32_bf16 v[8:11], v[210:213], v[234:237], v[8:11]
	v_mfma_f32_16x16x32_bf16 v[4:7], v[218:221], v[226:229], v[4:7]
	v_mfma_f32_16x16x32_bf16 v[0:3], v[218:221], v[234:237], v[0:3]
	s_barrier
	s_setprio 0
	ds_read_b128 v[174:177], v156
	ds_read_b128 v[178:181], v156 offset:1024
	ds_read_b128 v[182:185], v156 offset:2048
	ds_read_b128 v[186:189], v156 offset:3072
	v_readfirstlane_b32 s86, v162
	v_lshl_add_u64 v[222:223], v[238:239], 0, s[12:13]
	s_mov_b32 m0, s86
	v_readfirstlane_b32 s86, v163
	ds_read_b128 v[190:193], v153 offset:32768
	ds_read_b128 v[194:197], v153 offset:33792
	ds_read_b128 v[198:201], v152 offset:32768
	ds_read_b128 v[202:205], v152 offset:33792
	ds_read_b128 v[206:209], v151 offset:32768
	ds_read_b128 v[210:213], v151 offset:33792
	ds_read_b128 v[214:217], v150 offset:32768
	ds_read_b128 v[218:221], v150 offset:33792
	global_load_lds_dwordx4 v[222:223], off
	v_lshl_add_u64 v[222:223], v[240:241], 0, s[12:13]
	s_mov_b32 m0, s86
	s_nop 0
	global_load_lds_dwordx4 v[222:223], off
	s_waitcnt lgkmcnt(8)
	s_setprio 1
	s_barrier
	s_waitcnt lgkmcnt(0)
	v_mfma_f32_16x16x32_bf16 v[124:127], v[190:193], v[174:177], v[124:127]
	v_mfma_f32_16x16x32_bf16 v[120:123], v[190:193], v[182:185], v[120:123]
	v_mfma_f32_16x16x32_bf16 v[116:119], v[198:201], v[174:177], v[116:119]
	v_mfma_f32_16x16x32_bf16 v[112:115], v[198:201], v[182:185], v[112:115]
	v_mfma_f32_16x16x32_bf16 v[108:111], v[206:209], v[174:177], v[108:111]
	v_mfma_f32_16x16x32_bf16 v[104:107], v[206:209], v[182:185], v[104:107]
	v_mfma_f32_16x16x32_bf16 v[100:103], v[214:217], v[174:177], v[100:103]
	v_mfma_f32_16x16x32_bf16 v[96:99], v[214:217], v[182:185], v[96:99]
	v_mfma_f32_16x16x32_bf16 v[124:127], v[194:197], v[178:181], v[124:127]
	v_mfma_f32_16x16x32_bf16 v[120:123], v[194:197], v[186:189], v[120:123]
	v_mfma_f32_16x16x32_bf16 v[116:119], v[202:205], v[178:181], v[116:119]
	v_mfma_f32_16x16x32_bf16 v[112:115], v[202:205], v[186:189], v[112:115]
	v_mfma_f32_16x16x32_bf16 v[108:111], v[210:213], v[178:181], v[108:111]
	v_mfma_f32_16x16x32_bf16 v[104:107], v[210:213], v[186:189], v[104:107]
	v_mfma_f32_16x16x32_bf16 v[100:103], v[218:221], v[178:181], v[100:103]
	v_mfma_f32_16x16x32_bf16 v[96:99], v[218:221], v[186:189], v[96:99]
	s_barrier
	s_setprio 0
	v_readfirstlane_b32 s86, v164
	v_lshl_add_u64 v[246:247], v[242:243], 0, s[14:15]
	s_mov_b32 m0, s86
	v_readfirstlane_b32 s86, v165
	ds_read_b128 v[222:225], v154
	ds_read_b128 v[226:229], v154 offset:1024
	ds_read_b128 v[230:233], v154 offset:2048
	ds_read_b128 v[234:237], v154 offset:3072
	global_load_lds_dwordx4 v[246:247], off
	v_lshl_add_u64 v[246:247], v[244:245], 0, s[14:15]
	s_mov_b32 m0, s86
	s_nop 0
	global_load_lds_dwordx4 v[246:247], off
	s_setprio 1
	s_barrier
	s_waitcnt lgkmcnt(0)
	v_mfma_f32_16x16x32_bf16 v[92:95], v[190:193], v[222:225], v[92:95]
	v_mfma_f32_16x16x32_bf16 v[88:91], v[190:193], v[230:233], v[88:91]
	v_mfma_f32_16x16x32_bf16 v[84:87], v[198:201], v[222:225], v[84:87]
	v_mfma_f32_16x16x32_bf16 v[80:83], v[198:201], v[230:233], v[80:83]
	v_mfma_f32_16x16x32_bf16 v[76:79], v[206:209], v[222:225], v[76:79]
	v_mfma_f32_16x16x32_bf16 v[72:75], v[206:209], v[230:233], v[72:75]
	v_mfma_f32_16x16x32_bf16 v[68:71], v[214:217], v[222:225], v[68:71]
	v_mfma_f32_16x16x32_bf16 v[64:67], v[214:217], v[230:233], v[64:67]
	v_mfma_f32_16x16x32_bf16 v[92:95], v[194:197], v[226:229], v[92:95]
	v_mfma_f32_16x16x32_bf16 v[88:91], v[194:197], v[234:237], v[88:91]
	v_mfma_f32_16x16x32_bf16 v[84:87], v[202:205], v[226:229], v[84:87]
	v_mfma_f32_16x16x32_bf16 v[80:83], v[202:205], v[234:237], v[80:83]
	v_mfma_f32_16x16x32_bf16 v[76:79], v[210:213], v[226:229], v[76:79]
	v_mfma_f32_16x16x32_bf16 v[72:75], v[210:213], v[234:237], v[72:75]
	v_mfma_f32_16x16x32_bf16 v[68:71], v[218:221], v[226:229], v[68:71]
	v_mfma_f32_16x16x32_bf16 v[64:67], v[218:221], v[234:237], v[64:67]
	s_barrier
	s_setprio 0
	v_readfirstlane_b32 s86, v166
	v_lshl_add_u64 v[238:239], v[238:239], 0, s[24:25]
	s_mov_b32 m0, s86
	v_readfirstlane_b32 s86, v168
	ds_read_b128 v[190:193], v153 offset:49152
	ds_read_b128 v[194:197], v153 offset:50176
	ds_read_b128 v[198:201], v152 offset:49152
	ds_read_b128 v[202:205], v152 offset:50176
	ds_read_b128 v[206:209], v151 offset:49152
	ds_read_b128 v[210:213], v151 offset:50176
	ds_read_b128 v[214:217], v150 offset:49152
	ds_read_b128 v[218:221], v150 offset:50176
	global_load_lds_dwordx4 v[238:239], off
	v_lshl_add_u64 v[238:239], v[240:241], 0, s[24:25]
	s_mov_b32 m0, s86
	s_nop 0
	global_load_lds_dwordx4 v[238:239], off
	s_setprio 1
	s_barrier
; #define STAGE(P, BASE, kt) do { const char* _g = (const char*)(BASE) + (size_t)((kt) * (BK * 2)); \
;     __builtin_amdgcn_global_load_lds((const unsigned*)(_g + (size_t)goff0), (unsigned*)((char*)(P) + tid_ * 16), 16, 0, 0); \
;     __builtin_amdgcn_global_load_lds((const unsigned*)(_g + (size_t)goff1), (unsigned*)((char*)(P) + tid_ * 16 + 8192), 16, 0, 0); } while (0)
; #define STAGEA(P, BASE, kt) do { const char* _g = (const char*)(BASE) + (size_t)((kt) * a_kbytes); \
;     __builtin_amdgcn_global_load_lds((const unsigned*)(_g + (size_t)goffA0), (unsigned*)((char*)(P) + tid_ * 16), 16, 0, 0); \
;     __builtin_amdgcn_global_load_lds((const unsigned*)(_g + (size_t)goffA1), (unsigned*)((char*)(P) + tid_ * 16 + 8192), 16, 0, 0); } while (0)
; #define LDA(dst, b, h) for (int m = 0; m < 4; ++m) for (int k = 0; k < 2; ++k) \
;     dst[m][k] = *reinterpret_cast<const bf16x8*>((char*)SA(b, h) + lds_byte(wr * 64 + m * 16 + fr, k * 32 + fq * 8))
; #define LDB(dst, b, h) for (int n = 0; n < 2; ++n) for (int k = 0; k < 2; ++k) \
;     dst[n][k] = *reinterpret_cast<const bf16x8*>((char*)SB(b, h) + lds_byte(wc * 32 + n * 16 + fr, k * 32 + fq * 8))
; #define MMA(ai, bj, At, Bt) do { __builtin_amdgcn_s_setprio(1); \
;     for (int m = 0; m < 4; ++m) for (int n = 0; n < 2; ++n) for (int k = 0; k < 2; ++k) \
;       acc[ai][bj][m][n] = __builtin_amdgcn_mfma_f32_16x16x32_bf16(At[m][k], Bt[n][k], acc[ai][bj][m][n], 0, 0, 0); \
;     __builtin_amdgcn_s_setprio(0); } while (0)
; #define WAIT_V(n) asm volatile("s_waitcnt vmcnt(" #n ")" ::: "memory")
; #define WAIT_L(n) asm volatile("s_waitcnt lgkmcnt(" #n ")" ::: "memory")
; #define BAR __builtin_amdgcn_s_barrier()
; #define SCHED __builtin_amdgcn_sched_barrier(0)
; template <int EPI> ...
;     ...
;     BAR; WAIT_L(0); MMA(1, 0, At, B0); BAR; SCHED;
;     STAGE(SB(1, 1), B1p, t + 3);
;     WAIT_V(6); BAR; MMA(1, 1, At, B1); BAR;
;   }
;   { LDB(B0, 0, 0); LDA(At, 0, 0); STAGEA(SA(1, 1), A1, nt - 1);
;     BAR; WAIT_L(0); MMA(0, 0, At, B0); BAR;
;     LDB(B1, 0, 1); BAR; WAIT_L(0); MMA(0, 1, At, B1); BAR;
	s_waitcnt lgkmcnt(0)
	v_mfma_f32_16x16x32_bf16 v[60:63], v[190:193], v[174:177], v[60:63]
	v_mfma_f32_16x16x32_bf16 v[56:59], v[190:193], v[182:185], v[56:59]
	v_mfma_f32_16x16x32_bf16 v[52:55], v[198:201], v[174:177], v[52:55]
	v_mfma_f32_16x16x32_bf16 v[48:51], v[198:201], v[182:185], v[48:51]
	v_mfma_f32_16x16x32_bf16 v[44:47], v[206:209], v[174:177], v[44:47]
	v_mfma_f32_16x16x32_bf16 v[40:43], v[206:209], v[182:185], v[40:43]
	v_mfma_f32_16x16x32_bf16 v[36:39], v[214:217], v[174:177], v[36:39]
	v_mfma_f32_16x16x32_bf16 v[32:35], v[214:217], v[182:185], v[32:35]
	v_mfma_f32_16x16x32_bf16 v[60:63], v[194:197], v[178:181], v[60:63]
	v_mfma_f32_16x16x32_bf16 v[56:59], v[194:197], v[186:189], v[56:59]
	v_mfma_f32_16x16x32_bf16 v[52:55], v[202:205], v[178:181], v[52:55]
	v_mfma_f32_16x16x32_bf16 v[48:51], v[202:205], v[186:189], v[48:51]
	v_mfma_f32_16x16x32_bf16 v[44:47], v[210:213], v[178:181], v[44:47]
	v_mfma_f32_16x16x32_bf16 v[40:43], v[210:213], v[186:189], v[40:43]
	v_mfma_f32_16x16x32_bf16 v[36:39], v[218:221], v[178:181], v[36:39]
	v_mfma_f32_16x16x32_bf16 v[32:35], v[218:221], v[186:189], v[32:35]
	s_barrier
	s_setprio 0
	v_readfirstlane_b32 s86, v169
	v_lshl_add_u64 v[174:175], v[242:243], 0, s[42:43]
	s_mov_b32 m0, s86
	v_readfirstlane_b32 s86, v170
	global_load_lds_dwordx4 v[174:175], off
	v_lshl_add_u64 v[174:175], v[244:245], 0, s[42:43]
	s_mov_b32 m0, s86
	s_nop 0
	global_load_lds_dwordx4 v[174:175], off
	s_waitcnt vmcnt(6)
	s_setprio 1
	s_barrier
	v_mfma_f32_16x16x32_bf16 v[28:31], v[190:193], v[222:225], v[28:31]
	v_mfma_f32_16x16x32_bf16 v[24:27], v[190:193], v[230:233], v[24:27]
	v_mfma_f32_16x16x32_bf16 v[20:23], v[198:201], v[222:225], v[20:23]
	v_mfma_f32_16x16x32_bf16 v[16:19], v[198:201], v[230:233], v[16:19]
	v_mfma_f32_16x16x32_bf16 v[12:15], v[206:209], v[222:225], v[12:15]
	v_mfma_f32_16x16x32_bf16 v[8:11], v[206:209], v[230:233], v[8:11]
	v_mfma_f32_16x16x32_bf16 v[4:7], v[214:217], v[222:225], v[4:7]
	v_mfma_f32_16x16x32_bf16 v[0:3], v[214:217], v[230:233], v[0:3]
	v_mfma_f32_16x16x32_bf16 v[28:31], v[194:197], v[226:229], v[28:31]
	v_mfma_f32_16x16x32_bf16 v[24:27], v[194:197], v[234:237], v[24:27]
	v_mfma_f32_16x16x32_bf16 v[20:23], v[202:205], v[226:229], v[20:23]
	v_mfma_f32_16x16x32_bf16 v[16:19], v[202:205], v[234:237], v[16:19]
	v_mfma_f32_16x16x32_bf16 v[12:15], v[210:213], v[226:229], v[12:15]
	v_mfma_f32_16x16x32_bf16 v[8:11], v[210:213], v[234:237], v[8:11]
	v_mfma_f32_16x16x32_bf16 v[4:7], v[218:221], v[226:229], v[4:7]
	v_mfma_f32_16x16x32_bf16 v[0:3], v[218:221], v[234:237], v[0:3]
	s_barrier
	s_setprio 0
	s_add_i32 s85, s85, 2
	s_add_u32 s54, s54, 0x10000
	s_addc_u32 s55, s55, 0
	s_add_u32 s52, s52, 0x100
	s_addc_u32 s53, s53, 0
	s_cmpk_lt_u32 s85, 0x54
	s_cbranch_scc1 .LBB0_782
	s_add_u32 s48, s48, 0x2bc000
	s_addc_u32 s49, s49, 0
	v_readfirstlane_b32 s52, v172
	v_lshl_add_u64 v[210:211], s[48:49], 0, v[130:131]
	s_mov_b32 m0, s52
	ds_read_b128 v[158:161], v171
	ds_read_b128 v[162:165], v171 offset:1024
	ds_read_b128 v[174:177], v171 offset:2048
	ds_read_b128 v[168:171], v171 offset:3072
	ds_read_b128 v[178:181], v153
	ds_read_b128 v[182:185], v153 offset:1024
	ds_read_b128 v[186:189], v152
	ds_read_b128 v[190:193], v152 offset:1024
	ds_read_b128 v[194:197], v151
	ds_read_b128 v[198:201], v151 offset:1024
	ds_read_b128 v[202:205], v150
	ds_read_b128 v[206:209], v150 offset:1024
	global_load_lds_dwordx4 v[210:211], off
	v_lshl_add_u64 v[210:211], s[48:49], 0, v[128:129]
	v_readfirstlane_b32 s48, v173
	s_mov_b32 m0, s48
	s_nop 0
	global_load_lds_dwordx4 v[210:211], off
	s_setprio 1
	s_barrier
	s_waitcnt lgkmcnt(0)
	v_mfma_f32_16x16x32_bf16 v[124:127], v[178:181], v[158:161], v[124:127]
	v_mfma_f32_16x16x32_bf16 v[120:123], v[178:181], v[174:177], v[120:123]
	v_mfma_f32_16x16x32_bf16 v[108:111], v[194:197], v[158:161], v[108:111]
	v_mfma_f32_16x16x32_bf16 v[104:107], v[194:197], v[174:177], v[104:107]
	v_mfma_f32_16x16x32_bf16 v[124:127], v[182:185], v[162:165], v[124:127]
	v_mfma_f32_16x16x32_bf16 v[120:123], v[182:185], v[168:171], v[120:123]
	v_mfma_f32_16x16x32_bf16 v[116:119], v[186:189], v[158:161], v[116:119]
	v_mfma_f32_16x16x32_bf16 v[112:115], v[186:189], v[174:177], v[112:115]
	v_mfma_f32_16x16x32_bf16 v[108:111], v[198:201], v[162:165], v[108:111]
	v_mfma_f32_16x16x32_bf16 v[104:107], v[198:201], v[168:171], v[104:107]
	v_mfma_f32_16x16x32_bf16 v[100:103], v[202:205], v[158:161], v[100:103]
	v_mfma_f32_16x16x32_bf16 v[96:99], v[202:205], v[174:177], v[96:99]
	v_mfma_f32_16x16x32_bf16 v[210:213], v[190:193], v[162:165], v[116:119]
	v_mfma_f32_16x16x32_bf16 v[214:217], v[190:193], v[168:171], v[112:115]
	v_mfma_f32_16x16x32_bf16 v[218:221], v[206:209], v[162:165], v[100:103]
	v_mfma_f32_16x16x32_bf16 v[222:225], v[206:209], v[168:171], v[96:99]
	s_barrier
	s_setprio 0
	s_nop 1
	ds_read_b128 v[96:99], v167
	ds_read_b128 v[100:103], v167 offset:1024
	ds_read_b128 v[112:115], v167 offset:2048
	ds_read_b128 v[116:119], v167 offset:3072
	s_setprio 1
	s_barrier
	s_waitcnt lgkmcnt(0)
	v_mfma_f32_16x16x32_bf16 v[92:95], v[178:181], v[96:99], v[92:95]
	v_mfma_f32_16x16x32_bf16 v[88:91], v[178:181], v[112:115], v[88:91]
	v_mfma_f32_16x16x32_bf16 v[76:79], v[194:197], v[96:99], v[76:79]
	v_mfma_f32_16x16x32_bf16 v[72:75], v[194:197], v[112:115], v[72:75]
	v_mfma_f32_16x16x32_bf16 v[92:95], v[182:185], v[100:103], v[92:95]
	v_mfma_f32_16x16x32_bf16 v[88:91], v[182:185], v[116:119], v[88:91]
	v_mfma_f32_16x16x32_bf16 v[84:87], v[186:189], v[96:99], v[84:87]
	v_mfma_f32_16x16x32_bf16 v[80:83], v[186:189], v[112:115], v[80:83]
	v_mfma_f32_16x16x32_bf16 v[76:79], v[198:201], v[100:103], v[76:79]
	v_mfma_f32_16x16x32_bf16 v[72:75], v[198:201], v[116:119], v[72:75]
	v_mfma_f32_16x16x32_bf16 v[68:71], v[202:205], v[96:99], v[68:71]
	v_mfma_f32_16x16x32_bf16 v[64:67], v[202:205], v[112:115], v[64:67]
	v_mfma_f32_16x16x32_bf16 v[178:181], v[190:193], v[100:103], v[84:87]
	v_mfma_f32_16x16x32_bf16 v[182:185], v[190:193], v[116:119], v[80:83]
	v_mfma_f32_16x16x32_bf16 v[186:189], v[206:209], v[100:103], v[68:71]
	v_mfma_f32_16x16x32_bf16 v[190:193], v[206:209], v[116:119], v[64:67]
	s_barrier
; #define LDA(dst, b, h) for (int m = 0; m < 4; ++m) for (int k = 0; k < 2; ++k) \
;     dst[m][k] = *reinterpret_cast<const bf16x8*>((char*)SA(b, h) + lds_byte(wr * 64 + m * 16 + fr, k * 32 + fq * 8))
; #define LDB(dst, b, h) for (int n = 0; n < 2; ++n) for (int k = 0; k < 2; ++k) \
;     dst[n][k] = *reinterpret_cast<const bf16x8*>((char*)SB(b, h) + lds_byte(wc * 32 + n * 16 + fr, k * 32 + fq * 8))
; #define MMA(ai, bj, At, Bt) do { __builtin_amdgcn_s_setprio(1); \
;     for (int m = 0; m < 4; ++m) for (int n = 0; n < 2; ++n) for (int k = 0; k < 2; ++k) \
;       acc[ai][bj][m][n] = __builtin_amdgcn_mfma_f32_16x16x32_bf16(At[m][k], Bt[n][k], acc[ai][bj][m][n], 0, 0, 0); \
;     __builtin_amdgcn_s_setprio(0); } while (0)
; #define WAIT_V(n) asm volatile("s_waitcnt vmcnt(" #n ")" ::: "memory")
; #define WAIT_L(n) asm volatile("s_waitcnt lgkmcnt(" #n ")" ::: "memory")
; #define BAR __builtin_amdgcn_s_barrier()
; template <int EPI> ...
;     ...
;     LDA(At, 0, 1); WAIT_V(4); BAR; WAIT_L(0); MMA(1, 0, At, B0); MMA(1, 1, At, B1); BAR; }
;   { LDB(B0, 1, 0); LDA(At, 1, 0); WAIT_V(2); BAR; WAIT_L(0); MMA(0, 0, At, B0); BAR;
	s_setprio 0
	s_nop 1
	ds_read_b128 v[64:67], v153 offset:16384
	ds_read_b128 v[68:71], v153 offset:17408
	ds_read_b128 v[80:83], v152 offset:16384
	ds_read_b128 v[84:87], v152 offset:17408
	ds_read_b128 v[194:197], v151 offset:16384
	ds_read_b128 v[198:201], v151 offset:17408
	ds_read_b128 v[202:205], v150 offset:16384
	ds_read_b128 v[206:209], v150 offset:17408
	s_waitcnt vmcnt(4)
	s_setprio 1
	s_barrier
	s_waitcnt lgkmcnt(0)
	v_mfma_f32_16x16x32_bf16 v[60:63], v[64:67], v[158:161], v[60:63]
	v_mfma_f32_16x16x32_bf16 v[56:59], v[64:67], v[174:177], v[56:59]
	v_mfma_f32_16x16x32_bf16 v[44:47], v[194:197], v[158:161], v[44:47]
	v_mfma_f32_16x16x32_bf16 v[40:43], v[194:197], v[174:177], v[40:43]
	v_mfma_f32_16x16x32_bf16 v[60:63], v[68:71], v[162:165], v[60:63]
	v_mfma_f32_16x16x32_bf16 v[56:59], v[68:71], v[168:171], v[56:59]
	v_mfma_f32_16x16x32_bf16 v[52:55], v[80:83], v[158:161], v[52:55]
	v_mfma_f32_16x16x32_bf16 v[48:51], v[80:83], v[174:177], v[48:51]
	v_mfma_f32_16x16x32_bf16 v[44:47], v[198:201], v[162:165], v[44:47]
	v_mfma_f32_16x16x32_bf16 v[40:43], v[198:201], v[168:171], v[40:43]
	v_mfma_f32_16x16x32_bf16 v[36:39], v[202:205], v[158:161], v[36:39]
	v_mfma_f32_16x16x32_bf16 v[32:35], v[202:205], v[174:177], v[32:35]
	v_mfma_f32_16x16x32_bf16 v[226:229], v[84:87], v[162:165], v[52:55]
	v_mfma_f32_16x16x32_bf16 v[230:233], v[84:87], v[168:171], v[48:51]
	v_mfma_f32_16x16x32_bf16 v[158:161], v[206:209], v[162:165], v[36:39]
	v_mfma_f32_16x16x32_bf16 v[162:165], v[206:209], v[168:171], v[32:35]
	s_setprio 0
	s_setprio 1
	v_mfma_f32_16x16x32_bf16 v[28:31], v[64:67], v[96:99], v[28:31]
	v_mfma_f32_16x16x32_bf16 v[24:27], v[64:67], v[112:115], v[24:27]
	v_mfma_f32_16x16x32_bf16 v[12:15], v[194:197], v[96:99], v[12:15]
	v_mfma_f32_16x16x32_bf16 v[8:11], v[194:197], v[112:115], v[8:11]
	v_mfma_f32_16x16x32_bf16 v[28:31], v[68:71], v[100:103], v[28:31]
	v_mfma_f32_16x16x32_bf16 v[24:27], v[68:71], v[116:119], v[24:27]
	v_mfma_f32_16x16x32_bf16 v[20:23], v[80:83], v[96:99], v[20:23]
	v_mfma_f32_16x16x32_bf16 v[16:19], v[80:83], v[112:115], v[16:19]
	v_mfma_f32_16x16x32_bf16 v[12:15], v[198:201], v[100:103], v[12:15]
	v_mfma_f32_16x16x32_bf16 v[8:11], v[198:201], v[116:119], v[8:11]
	v_mfma_f32_16x16x32_bf16 v[4:7], v[202:205], v[96:99], v[4:7]
	v_mfma_f32_16x16x32_bf16 v[0:3], v[202:205], v[112:115], v[0:3]
	v_mfma_f32_16x16x32_bf16 v[166:169], v[84:87], v[100:103], v[20:23]
	v_mfma_f32_16x16x32_bf16 v[170:173], v[84:87], v[116:119], v[16:19]
	v_mfma_f32_16x16x32_bf16 v[174:177], v[206:209], v[100:103], v[4:7]
	v_mfma_f32_16x16x32_bf16 v[194:197], v[206:209], v[116:119], v[0:3]
	s_barrier
	s_setprio 0
	s_nop 1
	ds_read_b128 v[0:3], v156
	ds_read_b128 v[4:7], v156 offset:1024
	ds_read_b128 v[198:201], v156 offset:2048
	ds_read_b128 v[202:205], v156 offset:3072
	ds_read_b128 v[16:19], v153 offset:32768
	ds_read_b128 v[20:23], v153 offset:33792
	ds_read_b128 v[32:35], v152 offset:32768
	ds_read_b128 v[36:39], v152 offset:33792
	ds_read_b128 v[48:51], v151 offset:32768
	ds_read_b128 v[52:55], v151 offset:33792
	ds_read_b128 v[206:209], v150 offset:32768
	ds_read_b128 v[234:237], v150 offset:33792
	s_waitcnt vmcnt(2)
	s_setprio 1
	s_barrier
	s_waitcnt lgkmcnt(0)
	v_mfma_f32_16x16x32_bf16 v[64:67], v[16:19], v[0:3], v[124:127]
	v_mfma_f32_16x16x32_bf16 v[116:119], v[20:23], v[4:7], v[64:67]
	v_mfma_f32_16x16x32_bf16 v[64:67], v[16:19], v[198:201], v[120:123]
	v_mfma_f32_16x16x32_bf16 v[112:115], v[20:23], v[202:205], v[64:67]
	v_mfma_f32_16x16x32_bf16 v[64:67], v[32:35], v[0:3], v[210:213]
	v_mfma_f32_16x16x32_bf16 v[100:103], v[36:39], v[4:7], v[64:67]
	v_mfma_f32_16x16x32_bf16 v[64:67], v[32:35], v[198:201], v[214:217]
	v_mfma_f32_16x16x32_bf16 v[96:99], v[36:39], v[202:205], v[64:67]
	v_mfma_f32_16x16x32_bf16 v[64:67], v[48:51], v[0:3], v[108:111]
	v_mfma_f32_16x16x32_bf16 v[84:87], v[52:55], v[4:7], v[64:67]
	v_mfma_f32_16x16x32_bf16 v[64:67], v[48:51], v[198:201], v[104:107]
	v_mfma_f32_16x16x32_bf16 v[80:83], v[52:55], v[202:205], v[64:67]
	v_mfma_f32_16x16x32_bf16 v[64:67], v[206:209], v[0:3], v[218:221]
	v_mfma_f32_16x16x32_bf16 v[68:71], v[234:237], v[4:7], v[64:67]
	v_mfma_f32_16x16x32_bf16 v[64:67], v[206:209], v[198:201], v[222:225]
	v_mfma_f32_16x16x32_bf16 v[64:67], v[234:237], v[202:205], v[64:67]
	s_barrier
; #define LDA(dst, b, h) for (int m = 0; m < 4; ++m) for (int k = 0; k < 2; ++k) \
;     dst[m][k] = *reinterpret_cast<const bf16x8*>((char*)SA(b, h) + lds_byte(wr * 64 + m * 16 + fr, k * 32 + fq * 8))
; #define LDB(dst, b, h) for (int n = 0; n < 2; ++n) for (int k = 0; k < 2; ++k) \
;     dst[n][k] = *reinterpret_cast<const bf16x8*>((char*)SB(b, h) + lds_byte(wc * 32 + n * 16 + fr, k * 32 + fq * 8))
; #define MMA(ai, bj, At, Bt) do { __builtin_amdgcn_s_setprio(1); \
;     for (int m = 0; m < 4; ++m) for (int n = 0; n < 2; ++n) for (int k = 0; k < 2; ++k) \
;       acc[ai][bj][m][n] = __builtin_amdgcn_mfma_f32_16x16x32_bf16(At[m][k], Bt[n][k], acc[ai][bj][m][n], 0, 0, 0); \
;     __builtin_amdgcn_s_setprio(0); } while (0)
; #define WAIT_V(n) asm volatile("s_waitcnt vmcnt(" #n ")" ::: "memory")
; #define WAIT_L(n) asm volatile("s_waitcnt lgkmcnt(" #n ")" ::: "memory")
; #define BAR __builtin_amdgcn_s_barrier()
; template <int EPI> ...
;     ...
;     LDB(B1, 1, 1); WAIT_V(0); BAR; WAIT_L(0); MMA(0, 1, At, B1); BAR;
;     LDA(At, 1, 1); BAR; WAIT_L(0); MMA(1, 0, At, B0); MMA(1, 1, At, B1); BAR; }
;   if (wr == 0) BAR;
	s_setprio 0
	ds_read_b128 v[210:213], v154
	ds_read_b128 v[214:217], v154 offset:1024
	ds_read_b128 v[218:221], v154 offset:2048
	ds_read_b128 v[154:157], v154 offset:3072
	s_waitcnt vmcnt(0)
	s_setprio 1
	s_barrier
	s_waitcnt lgkmcnt(0)
	v_mfma_f32_16x16x32_bf16 v[92:95], v[16:19], v[210:213], v[92:95]
	v_mfma_f32_16x16x32_bf16 v[16:19], v[16:19], v[218:221], v[88:91]
	v_mfma_f32_16x16x32_bf16 v[120:123], v[20:23], v[154:157], v[16:19]
	v_mfma_f32_16x16x32_bf16 v[16:19], v[32:35], v[210:213], v[178:181]
	v_mfma_f32_16x16x32_bf16 v[108:111], v[36:39], v[214:217], v[16:19]
	v_mfma_f32_16x16x32_bf16 v[16:19], v[32:35], v[218:221], v[182:185]
	v_mfma_f32_16x16x32_bf16 v[104:107], v[36:39], v[154:157], v[16:19]
	v_mfma_f32_16x16x32_bf16 v[16:19], v[48:51], v[210:213], v[76:79]
	v_mfma_f32_16x16x32_bf16 v[124:127], v[20:23], v[214:217], v[92:95]
	v_mfma_f32_16x16x32_bf16 v[92:95], v[52:55], v[214:217], v[16:19]
	v_mfma_f32_16x16x32_bf16 v[16:19], v[48:51], v[218:221], v[72:75]
	v_mfma_f32_16x16x32_bf16 v[88:91], v[52:55], v[154:157], v[16:19]
	v_mfma_f32_16x16x32_bf16 v[16:19], v[206:209], v[210:213], v[186:189]
	v_mfma_f32_16x16x32_bf16 v[76:79], v[234:237], v[214:217], v[16:19]
	v_mfma_f32_16x16x32_bf16 v[16:19], v[206:209], v[218:221], v[190:193]
	v_mfma_f32_16x16x32_bf16 v[72:75], v[234:237], v[154:157], v[16:19]
	s_barrier
	s_setprio 0
	ds_read_b128 v[178:181], v153 offset:49152
	ds_read_b128 v[182:185], v153 offset:50176
	ds_read_b128 v[186:189], v152 offset:49152
	ds_read_b128 v[190:193], v152 offset:50176
	ds_read_b128 v[206:209], v151 offset:49152
	ds_read_b128 v[222:225], v151 offset:50176
	ds_read_b128 v[234:237], v150 offset:49152
	ds_read_b128 v[150:153], v150 offset:50176
	s_setprio 1
	s_barrier
	s_waitcnt lgkmcnt(0)
	v_mfma_f32_16x16x32_bf16 v[16:19], v[178:181], v[0:3], v[60:63]
	v_mfma_f32_16x16x32_bf16 v[52:55], v[182:185], v[4:7], v[16:19]
	v_mfma_f32_16x16x32_bf16 v[16:19], v[178:181], v[198:201], v[56:59]
	v_mfma_f32_16x16x32_bf16 v[48:51], v[182:185], v[202:205], v[16:19]
	v_mfma_f32_16x16x32_bf16 v[16:19], v[186:189], v[0:3], v[226:229]
	v_mfma_f32_16x16x32_bf16 v[36:39], v[190:193], v[4:7], v[16:19]
	v_mfma_f32_16x16x32_bf16 v[16:19], v[186:189], v[198:201], v[230:233]
	v_mfma_f32_16x16x32_bf16 v[32:35], v[190:193], v[202:205], v[16:19]
	v_mfma_f32_16x16x32_bf16 v[16:19], v[206:209], v[0:3], v[44:47]
	v_mfma_f32_16x16x32_bf16 v[0:3], v[234:237], v[0:3], v[158:161]
	v_mfma_f32_16x16x32_bf16 v[20:23], v[222:225], v[4:7], v[16:19]
	v_mfma_f32_16x16x32_bf16 v[16:19], v[206:209], v[198:201], v[40:43]
	v_mfma_f32_16x16x32_bf16 v[4:7], v[150:153], v[4:7], v[0:3]
	v_mfma_f32_16x16x32_bf16 v[0:3], v[234:237], v[198:201], v[162:165]
	v_mfma_f32_16x16x32_bf16 v[16:19], v[222:225], v[202:205], v[16:19]
	v_mfma_f32_16x16x32_bf16 v[0:3], v[150:153], v[202:205], v[0:3]
	s_setprio 0
	s_setprio 1
	v_mfma_f32_16x16x32_bf16 v[24:27], v[178:181], v[218:221], v[24:27]
	v_mfma_f32_16x16x32_bf16 v[56:59], v[182:185], v[154:157], v[24:27]
	v_mfma_f32_16x16x32_bf16 v[24:27], v[186:189], v[210:213], v[166:169]
	v_mfma_f32_16x16x32_bf16 v[44:47], v[190:193], v[214:217], v[24:27]
	v_mfma_f32_16x16x32_bf16 v[24:27], v[186:189], v[218:221], v[170:173]
	v_mfma_f32_16x16x32_bf16 v[8:11], v[206:209], v[218:221], v[8:11]
	v_mfma_f32_16x16x32_bf16 v[28:31], v[178:181], v[210:213], v[28:31]
	v_mfma_f32_16x16x32_bf16 v[40:43], v[190:193], v[154:157], v[24:27]
	v_mfma_f32_16x16x32_bf16 v[12:15], v[206:209], v[210:213], v[12:15]
	v_mfma_f32_16x16x32_bf16 v[24:27], v[222:225], v[154:157], v[8:11]
	v_mfma_f32_16x16x32_bf16 v[8:11], v[234:237], v[210:213], v[174:177]
	v_mfma_f32_16x16x32_bf16 v[60:63], v[182:185], v[214:217], v[28:31]
	v_mfma_f32_16x16x32_bf16 v[28:31], v[222:225], v[214:217], v[12:15]
	v_mfma_f32_16x16x32_bf16 v[12:15], v[150:153], v[214:217], v[8:11]
	v_mfma_f32_16x16x32_bf16 v[8:11], v[234:237], v[218:221], v[194:197]
	v_mfma_f32_16x16x32_bf16 v[8:11], v[150:153], v[154:157], v[8:11]
	s_barrier
	s_setprio 0
	v_cmp_gt_u32_e32 vcc, s67, v144
	s_and_saveexec_b64 s[48:49], vcc
	s_cbranch_execz .LBB0_785
	s_barrier

; #define STAGE(P, BASE, kt) do { const char* _g = (const char*)(BASE) + (size_t)((kt) * (BK * 2)); \
;     __builtin_amdgcn_global_load_lds((const unsigned*)(_g + (size_t)goff0), (unsigned*)((char*)(P) + tid_ * 16), 16, 0, 0); \
;     __builtin_amdgcn_global_load_lds((const unsigned*)(_g + (size_t)goff1), (unsigned*)((char*)(P) + tid_ * 16 + 8192), 16, 0, 0); } while (0)
; #define STAGEA(P, BASE, kt) do { const char* _g = (const char*)(BASE) + (size_t)((kt) * a_kbytes); \
;     __builtin_amdgcn_global_load_lds((const unsigned*)(_g + (size_t)goffA0), (unsigned*)((char*)(P) + tid_ * 16), 16, 0, 0); \
;     __builtin_amdgcn_global_load_lds((const unsigned*)(_g + (size_t)goffA1), (unsigned*)((char*)(P) + tid_ * 16 + 8192), 16, 0, 0); } while (0)
; #define LDA(dst, b, h) for (int m = 0; m < 4; ++m) for (int k = 0; k < 2; ++k) \
;     dst[m][k] = *reinterpret_cast<const bf16x8*>((char*)SA(b, h) + lds_byte(wr * 64 + m * 16 + fr, k * 32 + fq * 8))
; #define LDB(dst, b, h) for (int n = 0; n < 2; ++n) for (int k = 0; k < 2; ++k) \
;     dst[n][k] = *reinterpret_cast<const bf16x8*>((char*)SB(b, h) + lds_byte(wc * 32 + n * 16 + fr, k * 32 + fq * 8))
; #define MMA(ai, bj, At, Bt) do { __builtin_amdgcn_s_setprio(1); \
;     for (int m = 0; m < 4; ++m) for (int n = 0; n < 2; ++n) for (int k = 0; k < 2; ++k) \
;       acc[ai][bj][m][n] = __builtin_amdgcn_mfma_f32_16x16x32_bf16(At[m][k], Bt[n][k], acc[ai][bj][m][n], 0, 0, 0); \
;     __builtin_amdgcn_s_setprio(0); } while (0)
; #define WAIT_L(n) asm volatile("s_waitcnt lgkmcnt(" #n ")" ::: "memory")
; #define BAR __builtin_amdgcn_s_barrier()
; #define SCHED __builtin_amdgcn_sched_barrier(0)
; template <int EPI> ...
;     ...
;     LDB(B0, 0, 0); SCHED; LDA(At, 0, 0); STAGEA(SA(1, 1), A1, t + 1);
;     WAIT_L(8); BAR; WAIT_L(0); MMA(0, 0, At, B0); BAR; SCHED;
;     LDB(B1, 0, 1); STAGE(SB(0, 0), B0p, t + 2);
;     BAR; WAIT_L(0); MMA(0, 1, At, B1); BAR;
;     LDA(At, 0, 1); STAGEA(SA(0, 0), A0, t + 2);
;     BAR; WAIT_L(0); MMA(1, 0, At, B0); BAR; SCHED;
.LBB0_818:
	ds_read_b128 v[174:177], v171
	ds_read_b128 v[178:181], v171 offset:1024
	ds_read_b128 v[182:185], v171 offset:2048
	ds_read_b128 v[186:189], v171 offset:3072
	v_add_u32_e32 v172, 0xc000, v158
	v_lshl_add_u64 v[238:239], s[58:59], 0, v[140:141]
	v_readfirstlane_b32 s55, v172
	v_add_u32_e32 v173, 0xe000, v158
	v_lshl_add_u64 v[222:223], v[238:239], 0, s[6:7]
	s_mov_b32 m0, s55
	v_lshl_add_u64 v[240:241], s[58:59], 0, v[142:143]
	v_readfirstlane_b32 s55, v173
	ds_read_b128 v[190:193], v153
	ds_read_b128 v[194:197], v153 offset:1024
	ds_read_b128 v[198:201], v152
	ds_read_b128 v[202:205], v152 offset:1024
	ds_read_b128 v[206:209], v151
	ds_read_b128 v[210:213], v151 offset:1024
	ds_read_b128 v[214:217], v150
	ds_read_b128 v[218:221], v150 offset:1024
	global_load_lds_dwordx4 v[222:223], off
	v_lshl_add_u64 v[222:223], v[240:241], 0, s[6:7]
	s_mov_b32 m0, s55
	s_nop 0
	global_load_lds_dwordx4 v[222:223], off
	s_waitcnt lgkmcnt(8)
	s_setprio 1
	s_barrier
	s_waitcnt lgkmcnt(0)
	v_mfma_f32_16x16x32_bf16 v[124:127], v[190:193], v[174:177], v[124:127]
	v_mfma_f32_16x16x32_bf16 v[120:123], v[190:193], v[182:185], v[120:123]
	v_mfma_f32_16x16x32_bf16 v[116:119], v[198:201], v[174:177], v[116:119]
	v_mfma_f32_16x16x32_bf16 v[112:115], v[198:201], v[182:185], v[112:115]
	v_mfma_f32_16x16x32_bf16 v[108:111], v[206:209], v[174:177], v[108:111]
	v_mfma_f32_16x16x32_bf16 v[104:107], v[206:209], v[182:185], v[104:107]
	v_mfma_f32_16x16x32_bf16 v[100:103], v[214:217], v[174:177], v[100:103]
	v_mfma_f32_16x16x32_bf16 v[96:99], v[214:217], v[182:185], v[96:99]
	v_mfma_f32_16x16x32_bf16 v[124:127], v[194:197], v[178:181], v[124:127]
	v_mfma_f32_16x16x32_bf16 v[120:123], v[194:197], v[186:189], v[120:123]
	v_mfma_f32_16x16x32_bf16 v[116:119], v[202:205], v[178:181], v[116:119]
	v_mfma_f32_16x16x32_bf16 v[112:115], v[202:205], v[186:189], v[112:115]
	v_mfma_f32_16x16x32_bf16 v[108:111], v[210:213], v[178:181], v[108:111]
	v_mfma_f32_16x16x32_bf16 v[104:107], v[210:213], v[186:189], v[104:107]
	v_mfma_f32_16x16x32_bf16 v[100:103], v[218:221], v[178:181], v[100:103]
	v_mfma_f32_16x16x32_bf16 v[96:99], v[218:221], v[186:189], v[96:99]
	s_barrier
	s_setprio 0
	v_lshl_add_u64 v[242:243], s[58:59], 0, v[136:137]
	v_readfirstlane_b32 s55, v155
	v_lshl_add_u64 v[244:245], v[242:243], 0, s[8:9]
	s_mov_b32 m0, s55
	ds_read_b128 v[222:225], v168
	ds_read_b128 v[226:229], v168 offset:1024
	ds_read_b128 v[230:233], v168 offset:2048
	ds_read_b128 v[234:237], v168 offset:3072
	global_load_lds_dwordx4 v[244:245], off
	v_lshl_add_u64 v[244:245], s[58:59], 0, v[138:139]
	v_readfirstlane_b32 s55, v156
	v_lshl_add_u64 v[246:247], v[244:245], 0, s[8:9]
	s_mov_b32 m0, s55
	s_nop 0
	global_load_lds_dwordx4 v[246:247], off
	s_setprio 1
	s_barrier
	s_waitcnt lgkmcnt(0)
	v_mfma_f32_16x16x32_bf16 v[92:95], v[190:193], v[222:225], v[92:95]
	v_mfma_f32_16x16x32_bf16 v[88:91], v[190:193], v[230:233], v[88:91]
	v_mfma_f32_16x16x32_bf16 v[84:87], v[198:201], v[222:225], v[84:87]
	v_mfma_f32_16x16x32_bf16 v[80:83], v[198:201], v[230:233], v[80:83]
	v_mfma_f32_16x16x32_bf16 v[76:79], v[206:209], v[222:225], v[76:79]
	v_mfma_f32_16x16x32_bf16 v[72:75], v[206:209], v[230:233], v[72:75]
	v_mfma_f32_16x16x32_bf16 v[68:71], v[214:217], v[222:225], v[68:71]
	v_mfma_f32_16x16x32_bf16 v[64:67], v[214:217], v[230:233], v[64:67]
	v_mfma_f32_16x16x32_bf16 v[92:95], v[194:197], v[226:229], v[92:95]
	v_mfma_f32_16x16x32_bf16 v[88:91], v[194:197], v[234:237], v[88:91]
	v_mfma_f32_16x16x32_bf16 v[84:87], v[202:205], v[226:229], v[84:87]
	v_mfma_f32_16x16x32_bf16 v[80:83], v[202:205], v[234:237], v[80:83]
	v_mfma_f32_16x16x32_bf16 v[76:79], v[210:213], v[226:229], v[76:79]
	v_mfma_f32_16x16x32_bf16 v[72:75], v[210:213], v[234:237], v[72:75]
	v_mfma_f32_16x16x32_bf16 v[68:71], v[218:221], v[226:229], v[68:71]
	v_mfma_f32_16x16x32_bf16 v[64:67], v[218:221], v[234:237], v[64:67]
	s_barrier
	s_setprio 0
	v_readfirstlane_b32 s55, v158
	v_lshl_add_u64 v[246:247], v[238:239], 0, s[10:11]
	s_mov_b32 m0, s55
	v_readfirstlane_b32 s55, v159
	ds_read_b128 v[190:193], v153 offset:16384
	ds_read_b128 v[194:197], v153 offset:17408
	ds_read_b128 v[198:201], v152 offset:16384
	ds_read_b128 v[202:205], v152 offset:17408
	ds_read_b128 v[206:209], v151 offset:16384
	ds_read_b128 v[210:213], v151 offset:17408
	ds_read_b128 v[214:217], v150 offset:16384
	ds_read_b128 v[218:221], v150 offset:17408
	global_load_lds_dwordx4 v[246:247], off
	v_lshl_add_u64 v[246:247], v[240:241], 0, s[10:11]
	s_mov_b32 m0, s55
	s_nop 0
	global_load_lds_dwordx4 v[246:247], off
	s_setprio 1
	s_barrier
	s_waitcnt lgkmcnt(0)
	v_mfma_f32_16x16x32_bf16 v[60:63], v[190:193], v[174:177], v[60:63]
	v_mfma_f32_16x16x32_bf16 v[56:59], v[190:193], v[182:185], v[56:59]
	v_mfma_f32_16x16x32_bf16 v[52:55], v[198:201], v[174:177], v[52:55]
	v_mfma_f32_16x16x32_bf16 v[48:51], v[198:201], v[182:185], v[48:51]
	v_mfma_f32_16x16x32_bf16 v[44:47], v[206:209], v[174:177], v[44:47]
	v_mfma_f32_16x16x32_bf16 v[40:43], v[206:209], v[182:185], v[40:43]
	v_mfma_f32_16x16x32_bf16 v[36:39], v[214:217], v[174:177], v[36:39]
	v_mfma_f32_16x16x32_bf16 v[32:35], v[214:217], v[182:185], v[32:35]
	v_mfma_f32_16x16x32_bf16 v[60:63], v[194:197], v[178:181], v[60:63]
	v_mfma_f32_16x16x32_bf16 v[56:59], v[194:197], v[186:189], v[56:59]
	v_mfma_f32_16x16x32_bf16 v[52:55], v[202:205], v[178:181], v[52:55]
	v_mfma_f32_16x16x32_bf16 v[48:51], v[202:205], v[186:189], v[48:51]
	v_mfma_f32_16x16x32_bf16 v[44:47], v[210:213], v[178:181], v[44:47]
	v_mfma_f32_16x16x32_bf16 v[40:43], v[210:213], v[186:189], v[40:43]
	v_mfma_f32_16x16x32_bf16 v[36:39], v[218:221], v[178:181], v[36:39]
	v_mfma_f32_16x16x32_bf16 v[32:35], v[218:221], v[186:189], v[32:35]
	s_barrier
; #define STAGE(P, BASE, kt) do { const char* _g = (const char*)(BASE) + (size_t)((kt) * (BK * 2)); \
;     __builtin_amdgcn_global_load_lds((const unsigned*)(_g + (size_t)goff0), (unsigned*)((char*)(P) + tid_ * 16), 16, 0, 0); \
;     __builtin_amdgcn_global_load_lds((const unsigned*)(_g + (size_t)goff1), (unsigned*)((char*)(P) + tid_ * 16 + 8192), 16, 0, 0); } while (0)
; #define STAGEA(P, BASE, kt) do { const char* _g = (const char*)(BASE) + (size_t)((kt) * a_kbytes); \
;     __builtin_amdgcn_global_load_lds((const unsigned*)(_g + (size_t)goffA0), (unsigned*)((char*)(P) + tid_ * 16), 16, 0, 0); \
;     __builtin_amdgcn_global_load_lds((const unsigned*)(_g + (size_t)goffA1), (unsigned*)((char*)(P) + tid_ * 16 + 8192), 16, 0, 0); } while (0)
; #define LDA(dst, b, h) for (int m = 0; m < 4; ++m) for (int k = 0; k < 2; ++k) \
;     dst[m][k] = *reinterpret_cast<const bf16x8*>((char*)SA(b, h) + lds_byte(wr * 64 + m * 16 + fr, k * 32 + fq * 8))
; #define LDB(dst, b, h) for (int n = 0; n < 2; ++n) for (int k = 0; k < 2; ++k) \
;     dst[n][k] = *reinterpret_cast<const bf16x8*>((char*)SB(b, h) + lds_byte(wc * 32 + n * 16 + fr, k * 32 + fq * 8))
; #define MMA(ai, bj, At, Bt) do { __builtin_amdgcn_s_setprio(1); \
;     for (int m = 0; m < 4; ++m) for (int n = 0; n < 2; ++n) for (int k = 0; k < 2; ++k) \
;       acc[ai][bj][m][n] = __builtin_amdgcn_mfma_f32_16x16x32_bf16(At[m][k], Bt[n][k], acc[ai][bj][m][n], 0, 0, 0); \
;     __builtin_amdgcn_s_setprio(0); } while (0)
; #define WAIT_V(n) asm volatile("s_waitcnt vmcnt(" #n ")" ::: "memory")
; #define WAIT_L(n) asm volatile("s_waitcnt lgkmcnt(" #n ")" ::: "memory")
; #define BAR __builtin_amdgcn_s_barrier()
; #define SCHED __builtin_amdgcn_sched_barrier(0)
; template <int EPI> ...
;     ...
;     STAGE(SB(0, 1), B1p, t + 2);
;     WAIT_V(6); BAR; MMA(1, 1, At, B1); BAR;
;     LDB(B0, 1, 0); SCHED; LDA(At, 1, 0); STAGEA(SA(0, 1), A1, t + 2);
;     WAIT_L(8); BAR; WAIT_L(0); MMA(0, 0, At, B0); BAR; SCHED;
;     LDB(B1, 1, 1); STAGE(SB(1, 0), B0p, t + 3);
;     BAR; WAIT_L(0); MMA(0, 1, At, B1); BAR;
;     LDA(At, 1, 1); STAGEA(SA(1, 0), A0, t + 3);
	s_setprio 0
	v_readfirstlane_b32 s55, v160
	v_lshl_add_u64 v[174:175], v[242:243], 0, s[12:13]
	s_mov_b32 m0, s55
	v_readfirstlane_b32 s55, v161
	global_load_lds_dwordx4 v[174:175], off
	v_lshl_add_u64 v[174:175], v[244:245], 0, s[12:13]
	s_mov_b32 m0, s55
	s_nop 0
	global_load_lds_dwordx4 v[174:175], off
	s_waitcnt vmcnt(6)
	s_setprio 1
	s_barrier
	v_mfma_f32_16x16x32_bf16 v[28:31], v[190:193], v[222:225], v[28:31]
	v_mfma_f32_16x16x32_bf16 v[24:27], v[190:193], v[230:233], v[24:27]
	v_mfma_f32_16x16x32_bf16 v[20:23], v[198:201], v[222:225], v[20:23]
	v_mfma_f32_16x16x32_bf16 v[16:19], v[198:201], v[230:233], v[16:19]
	v_mfma_f32_16x16x32_bf16 v[12:15], v[206:209], v[222:225], v[12:15]
	v_mfma_f32_16x16x32_bf16 v[8:11], v[206:209], v[230:233], v[8:11]
	v_mfma_f32_16x16x32_bf16 v[4:7], v[214:217], v[222:225], v[4:7]
	v_mfma_f32_16x16x32_bf16 v[0:3], v[214:217], v[230:233], v[0:3]
	v_mfma_f32_16x16x32_bf16 v[28:31], v[194:197], v[226:229], v[28:31]
	v_mfma_f32_16x16x32_bf16 v[24:27], v[194:197], v[234:237], v[24:27]
	v_mfma_f32_16x16x32_bf16 v[20:23], v[202:205], v[226:229], v[20:23]
	v_mfma_f32_16x16x32_bf16 v[16:19], v[202:205], v[234:237], v[16:19]
	v_mfma_f32_16x16x32_bf16 v[12:15], v[210:213], v[226:229], v[12:15]
	v_mfma_f32_16x16x32_bf16 v[8:11], v[210:213], v[234:237], v[8:11]
	v_mfma_f32_16x16x32_bf16 v[4:7], v[218:221], v[226:229], v[4:7]
	v_mfma_f32_16x16x32_bf16 v[0:3], v[218:221], v[234:237], v[0:3]
	s_barrier
	s_setprio 0
	ds_read_b128 v[174:177], v157
	ds_read_b128 v[178:181], v157 offset:1024
	ds_read_b128 v[182:185], v157 offset:2048
	ds_read_b128 v[186:189], v157 offset:3072
	v_readfirstlane_b32 s55, v162
	v_lshl_add_u64 v[222:223], v[238:239], 0, s[14:15]
	s_mov_b32 m0, s55
	v_readfirstlane_b32 s55, v163
	ds_read_b128 v[190:193], v153 offset:32768
	ds_read_b128 v[194:197], v153 offset:33792
	ds_read_b128 v[198:201], v152 offset:32768
	ds_read_b128 v[202:205], v152 offset:33792
	ds_read_b128 v[206:209], v151 offset:32768
	ds_read_b128 v[210:213], v151 offset:33792
	ds_read_b128 v[214:217], v150 offset:32768
	ds_read_b128 v[218:221], v150 offset:33792
	global_load_lds_dwordx4 v[222:223], off
	v_lshl_add_u64 v[222:223], v[240:241], 0, s[14:15]
	s_mov_b32 m0, s55
	s_nop 0
	global_load_lds_dwordx4 v[222:223], off
	s_waitcnt lgkmcnt(8)
	s_setprio 1
	s_barrier
	s_waitcnt lgkmcnt(0)
	v_mfma_f32_16x16x32_bf16 v[124:127], v[190:193], v[174:177], v[124:127]
	v_mfma_f32_16x16x32_bf16 v[120:123], v[190:193], v[182:185], v[120:123]
	v_mfma_f32_16x16x32_bf16 v[116:119], v[198:201], v[174:177], v[116:119]
	v_mfma_f32_16x16x32_bf16 v[112:115], v[198:201], v[182:185], v[112:115]
	v_mfma_f32_16x16x32_bf16 v[108:111], v[206:209], v[174:177], v[108:111]
	v_mfma_f32_16x16x32_bf16 v[104:107], v[206:209], v[182:185], v[104:107]
	v_mfma_f32_16x16x32_bf16 v[100:103], v[214:217], v[174:177], v[100:103]
	v_mfma_f32_16x16x32_bf16 v[96:99], v[214:217], v[182:185], v[96:99]
	v_mfma_f32_16x16x32_bf16 v[124:127], v[194:197], v[178:181], v[124:127]
	v_mfma_f32_16x16x32_bf16 v[120:123], v[194:197], v[186:189], v[120:123]
	v_mfma_f32_16x16x32_bf16 v[116:119], v[202:205], v[178:181], v[116:119]
	v_mfma_f32_16x16x32_bf16 v[112:115], v[202:205], v[186:189], v[112:115]
	v_mfma_f32_16x16x32_bf16 v[108:111], v[210:213], v[178:181], v[108:111]
	v_mfma_f32_16x16x32_bf16 v[104:107], v[210:213], v[186:189], v[104:107]
	v_mfma_f32_16x16x32_bf16 v[100:103], v[218:221], v[178:181], v[100:103]
	v_mfma_f32_16x16x32_bf16 v[96:99], v[218:221], v[186:189], v[96:99]
	s_barrier
	s_setprio 0
	v_readfirstlane_b32 s55, v164
	v_lshl_add_u64 v[246:247], v[242:243], 0, s[24:25]
	s_mov_b32 m0, s55
	v_readfirstlane_b32 s55, v165
	ds_read_b128 v[222:225], v154
	ds_read_b128 v[226:229], v154 offset:1024
	ds_read_b128 v[230:233], v154 offset:2048
	ds_read_b128 v[234:237], v154 offset:3072
	global_load_lds_dwordx4 v[246:247], off
	v_lshl_add_u64 v[246:247], v[244:245], 0, s[24:25]
	s_mov_b32 m0, s55
	s_nop 0
	global_load_lds_dwordx4 v[246:247], off
	s_setprio 1
	s_barrier
	s_waitcnt lgkmcnt(0)
	v_mfma_f32_16x16x32_bf16 v[92:95], v[190:193], v[222:225], v[92:95]
	v_mfma_f32_16x16x32_bf16 v[88:91], v[190:193], v[230:233], v[88:91]
	v_mfma_f32_16x16x32_bf16 v[84:87], v[198:201], v[222:225], v[84:87]
	v_mfma_f32_16x16x32_bf16 v[80:83], v[198:201], v[230:233], v[80:83]
	v_mfma_f32_16x16x32_bf16 v[76:79], v[206:209], v[222:225], v[76:79]
	v_mfma_f32_16x16x32_bf16 v[72:75], v[206:209], v[230:233], v[72:75]
	v_mfma_f32_16x16x32_bf16 v[68:71], v[214:217], v[222:225], v[68:71]
	v_mfma_f32_16x16x32_bf16 v[64:67], v[214:217], v[230:233], v[64:67]
	v_mfma_f32_16x16x32_bf16 v[92:95], v[194:197], v[226:229], v[92:95]
	v_mfma_f32_16x16x32_bf16 v[88:91], v[194:197], v[234:237], v[88:91]
	v_mfma_f32_16x16x32_bf16 v[84:87], v[202:205], v[226:229], v[84:87]
	v_mfma_f32_16x16x32_bf16 v[80:83], v[202:205], v[234:237], v[80:83]
	v_mfma_f32_16x16x32_bf16 v[76:79], v[210:213], v[226:229], v[76:79]
	v_mfma_f32_16x16x32_bf16 v[72:75], v[210:213], v[234:237], v[72:75]
	v_mfma_f32_16x16x32_bf16 v[68:71], v[218:221], v[226:229], v[68:71]
	v_mfma_f32_16x16x32_bf16 v[64:67], v[218:221], v[234:237], v[64:67]
	s_barrier
	s_setprio 0
	v_readfirstlane_b32 s55, v166
	v_lshl_add_u64 v[238:239], v[238:239], 0, s[42:43]
	s_mov_b32 m0, s55
	v_readfirstlane_b32 s55, v167
	ds_read_b128 v[190:193], v153 offset:49152
	ds_read_b128 v[194:197], v153 offset:50176
	ds_read_b128 v[198:201], v152 offset:49152
	ds_read_b128 v[202:205], v152 offset:50176
	ds_read_b128 v[206:209], v151 offset:49152
	ds_read_b128 v[210:213], v151 offset:50176
	ds_read_b128 v[214:217], v150 offset:49152
	ds_read_b128 v[218:221], v150 offset:50176
	global_load_lds_dwordx4 v[238:239], off
	v_lshl_add_u64 v[238:239], v[240:241], 0, s[42:43]
	s_mov_b32 m0, s55
	s_nop 0
	global_load_lds_dwordx4 v[238:239], off
	s_setprio 1
	s_barrier
; #define STAGE(P, BASE, kt) do { const char* _g = (const char*)(BASE) + (size_t)((kt) * (BK * 2)); \
;     __builtin_amdgcn_global_load_lds((const unsigned*)(_g + (size_t)goff0), (unsigned*)((char*)(P) + tid_ * 16), 16, 0, 0); \
;     __builtin_amdgcn_global_load_lds((const unsigned*)(_g + (size_t)goff1), (unsigned*)((char*)(P) + tid_ * 16 + 8192), 16, 0, 0); } while (0)
; #define STAGEA(P, BASE, kt) do { const char* _g = (const char*)(BASE) + (size_t)((kt) * a_kbytes); \
;     __builtin_amdgcn_global_load_lds((const unsigned*)(_g + (size_t)goffA0), (unsigned*)((char*)(P) + tid_ * 16), 16, 0, 0); \
;     __builtin_amdgcn_global_load_lds((const unsigned*)(_g + (size_t)goffA1), (unsigned*)((char*)(P) + tid_ * 16 + 8192), 16, 0, 0); } while (0)
; #define LDA(dst, b, h) for (int m = 0; m < 4; ++m) for (int k = 0; k < 2; ++k) \
;     dst[m][k] = *reinterpret_cast<const bf16x8*>((char*)SA(b, h) + lds_byte(wr * 64 + m * 16 + fr, k * 32 + fq * 8))
; #define LDB(dst, b, h) for (int n = 0; n < 2; ++n) for (int k = 0; k < 2; ++k) \
;     dst[n][k] = *reinterpret_cast<const bf16x8*>((char*)SB(b, h) + lds_byte(wc * 32 + n * 16 + fr, k * 32 + fq * 8))
; #define MMA(ai, bj, At, Bt) do { __builtin_amdgcn_s_setprio(1); \
;     for (int m = 0; m < 4; ++m) for (int n = 0; n < 2; ++n) for (int k = 0; k < 2; ++k) \
;       acc[ai][bj][m][n] = __builtin_amdgcn_mfma_f32_16x16x32_bf16(At[m][k], Bt[n][k], acc[ai][bj][m][n], 0, 0, 0); \
;     __builtin_amdgcn_s_setprio(0); } while (0)
; #define WAIT_V(n) asm volatile("s_waitcnt vmcnt(" #n ")" ::: "memory")
; #define WAIT_L(n) asm volatile("s_waitcnt lgkmcnt(" #n ")" ::: "memory")
; #define BAR __builtin_amdgcn_s_barrier()
; #define SCHED __builtin_amdgcn_sched_barrier(0)
; template <int EPI> ...
;     ...
;     BAR; WAIT_L(0); MMA(1, 0, At, B0); BAR; SCHED;
;     STAGE(SB(1, 1), B1p, t + 3);
;     WAIT_V(6); BAR; MMA(1, 1, At, B1); BAR;
;   }
;   { LDB(B0, 0, 0); LDA(At, 0, 0); STAGEA(SA(1, 1), A1, nt - 1);
;     BAR; WAIT_L(0); MMA(0, 0, At, B0); BAR;
;     LDB(B1, 0, 1); BAR; WAIT_L(0); MMA(0, 1, At, B1); BAR;
	s_waitcnt lgkmcnt(0)
	v_mfma_f32_16x16x32_bf16 v[60:63], v[190:193], v[174:177], v[60:63]
	v_mfma_f32_16x16x32_bf16 v[56:59], v[190:193], v[182:185], v[56:59]
	v_mfma_f32_16x16x32_bf16 v[52:55], v[198:201], v[174:177], v[52:55]
	v_mfma_f32_16x16x32_bf16 v[48:51], v[198:201], v[182:185], v[48:51]
	v_mfma_f32_16x16x32_bf16 v[44:47], v[206:209], v[174:177], v[44:47]
	v_mfma_f32_16x16x32_bf16 v[40:43], v[206:209], v[182:185], v[40:43]
	v_mfma_f32_16x16x32_bf16 v[36:39], v[214:217], v[174:177], v[36:39]
	v_mfma_f32_16x16x32_bf16 v[32:35], v[214:217], v[182:185], v[32:35]
	v_mfma_f32_16x16x32_bf16 v[60:63], v[194:197], v[178:181], v[60:63]
	v_mfma_f32_16x16x32_bf16 v[56:59], v[194:197], v[186:189], v[56:59]
	v_mfma_f32_16x16x32_bf16 v[52:55], v[202:205], v[178:181], v[52:55]
	v_mfma_f32_16x16x32_bf16 v[48:51], v[202:205], v[186:189], v[48:51]
	v_mfma_f32_16x16x32_bf16 v[44:47], v[210:213], v[178:181], v[44:47]
	v_mfma_f32_16x16x32_bf16 v[40:43], v[210:213], v[186:189], v[40:43]
	v_mfma_f32_16x16x32_bf16 v[36:39], v[218:221], v[178:181], v[36:39]
	v_mfma_f32_16x16x32_bf16 v[32:35], v[218:221], v[186:189], v[32:35]
	s_barrier
	s_setprio 0
	v_readfirstlane_b32 s55, v169
	v_lshl_add_u64 v[174:175], v[242:243], 0, s[46:47]
	s_mov_b32 m0, s55
	v_readfirstlane_b32 s55, v170
	global_load_lds_dwordx4 v[174:175], off
	v_lshl_add_u64 v[174:175], v[244:245], 0, s[46:47]
	s_mov_b32 m0, s55
	s_nop 0
	global_load_lds_dwordx4 v[174:175], off
	s_waitcnt vmcnt(6)
	s_setprio 1
	s_barrier
	v_mfma_f32_16x16x32_bf16 v[28:31], v[190:193], v[222:225], v[28:31]
	v_mfma_f32_16x16x32_bf16 v[24:27], v[190:193], v[230:233], v[24:27]
	v_mfma_f32_16x16x32_bf16 v[20:23], v[198:201], v[222:225], v[20:23]
	v_mfma_f32_16x16x32_bf16 v[16:19], v[198:201], v[230:233], v[16:19]
	v_mfma_f32_16x16x32_bf16 v[12:15], v[206:209], v[222:225], v[12:15]
	v_mfma_f32_16x16x32_bf16 v[8:11], v[206:209], v[230:233], v[8:11]
	v_mfma_f32_16x16x32_bf16 v[4:7], v[214:217], v[222:225], v[4:7]
	v_mfma_f32_16x16x32_bf16 v[0:3], v[214:217], v[230:233], v[0:3]
	v_mfma_f32_16x16x32_bf16 v[28:31], v[194:197], v[226:229], v[28:31]
	v_mfma_f32_16x16x32_bf16 v[24:27], v[194:197], v[234:237], v[24:27]
	v_mfma_f32_16x16x32_bf16 v[20:23], v[202:205], v[226:229], v[20:23]
	v_mfma_f32_16x16x32_bf16 v[16:19], v[202:205], v[234:237], v[16:19]
	v_mfma_f32_16x16x32_bf16 v[12:15], v[210:213], v[226:229], v[12:15]
	v_mfma_f32_16x16x32_bf16 v[8:11], v[210:213], v[234:237], v[8:11]
	v_mfma_f32_16x16x32_bf16 v[4:7], v[218:221], v[226:229], v[4:7]
	v_mfma_f32_16x16x32_bf16 v[0:3], v[218:221], v[234:237], v[0:3]
	s_barrier
	s_setprio 0
	s_add_i32 s53, s53, 2
	s_add_u32 s58, s58, 0x100
	s_addc_u32 s59, s59, 0
	s_cmp_lt_u32 s53, 28
	s_cbranch_scc1 .LBB0_818
	s_add_u32 s56, s56, 0x80f80
	s_addc_u32 s57, s57, 0
	v_readfirstlane_b32 s53, v172
	v_lshl_add_u64 v[166:167], s[56:57], 0, v[130:131]
	s_mov_b32 m0, s53
	v_readfirstlane_b32 s53, v173
	ds_read_b128 v[136:139], v171
	ds_read_b128 v[140:143], v171 offset:1024
	ds_read_b128 v[158:161], v171 offset:2048
	ds_read_b128 v[162:165], v171 offset:3072
	ds_read_b128 v[174:177], v153
	ds_read_b128 v[178:181], v153 offset:1024
	ds_read_b128 v[182:185], v152
	ds_read_b128 v[186:189], v152 offset:1024
	ds_read_b128 v[190:193], v151
	ds_read_b128 v[194:197], v151 offset:1024
	ds_read_b128 v[198:201], v150
	ds_read_b128 v[202:205], v150 offset:1024
	global_load_lds_dwordx4 v[166:167], off
	v_lshl_add_u64 v[166:167], s[56:57], 0, v[128:129]
	s_mov_b32 m0, s53
	s_nop 0
	global_load_lds_dwordx4 v[166:167], off
	s_setprio 1
	s_barrier
	s_waitcnt lgkmcnt(0)
	v_mfma_f32_16x16x32_bf16 v[124:127], v[174:177], v[136:139], v[124:127]
	v_mfma_f32_16x16x32_bf16 v[120:123], v[174:177], v[158:161], v[120:123]
	v_mfma_f32_16x16x32_bf16 v[108:111], v[190:193], v[136:139], v[108:111]
	v_mfma_f32_16x16x32_bf16 v[104:107], v[190:193], v[158:161], v[104:107]
	v_mfma_f32_16x16x32_bf16 v[124:127], v[178:181], v[140:143], v[124:127]
	v_mfma_f32_16x16x32_bf16 v[120:123], v[178:181], v[162:165], v[120:123]
	v_mfma_f32_16x16x32_bf16 v[116:119], v[182:185], v[136:139], v[116:119]
	v_mfma_f32_16x16x32_bf16 v[112:115], v[182:185], v[158:161], v[112:115]
	v_mfma_f32_16x16x32_bf16 v[108:111], v[194:197], v[140:143], v[108:111]
	v_mfma_f32_16x16x32_bf16 v[104:107], v[194:197], v[162:165], v[104:107]
	v_mfma_f32_16x16x32_bf16 v[100:103], v[198:201], v[136:139], v[100:103]
	v_mfma_f32_16x16x32_bf16 v[96:99], v[198:201], v[158:161], v[96:99]
	v_mfma_f32_16x16x32_bf16 v[170:173], v[186:189], v[140:143], v[116:119]
	v_mfma_f32_16x16x32_bf16 v[206:209], v[186:189], v[162:165], v[112:115]
	v_mfma_f32_16x16x32_bf16 v[210:213], v[202:205], v[140:143], v[100:103]
	v_mfma_f32_16x16x32_bf16 v[214:217], v[202:205], v[162:165], v[96:99]
	s_barrier
	s_setprio 0
	s_nop 1
	ds_read_b128 v[96:99], v168
	ds_read_b128 v[100:103], v168 offset:1024
	ds_read_b128 v[112:115], v168 offset:2048
	ds_read_b128 v[116:119], v168 offset:3072
	s_setprio 1
	s_barrier
	s_waitcnt lgkmcnt(0)
	v_mfma_f32_16x16x32_bf16 v[92:95], v[174:177], v[96:99], v[92:95]
	v_mfma_f32_16x16x32_bf16 v[88:91], v[174:177], v[112:115], v[88:91]
	v_mfma_f32_16x16x32_bf16 v[76:79], v[190:193], v[96:99], v[76:79]
	v_mfma_f32_16x16x32_bf16 v[72:75], v[190:193], v[112:115], v[72:75]
	v_mfma_f32_16x16x32_bf16 v[92:95], v[178:181], v[100:103], v[92:95]
	v_mfma_f32_16x16x32_bf16 v[88:91], v[178:181], v[116:119], v[88:91]
	v_mfma_f32_16x16x32_bf16 v[84:87], v[182:185], v[96:99], v[84:87]
	v_mfma_f32_16x16x32_bf16 v[80:83], v[182:185], v[112:115], v[80:83]
	v_mfma_f32_16x16x32_bf16 v[76:79], v[194:197], v[100:103], v[76:79]
	v_mfma_f32_16x16x32_bf16 v[72:75], v[194:197], v[116:119], v[72:75]
	v_mfma_f32_16x16x32_bf16 v[68:71], v[198:201], v[96:99], v[68:71]
	v_mfma_f32_16x16x32_bf16 v[64:67], v[198:201], v[112:115], v[64:67]
	v_mfma_f32_16x16x32_bf16 v[166:169], v[186:189], v[100:103], v[84:87]
	v_mfma_f32_16x16x32_bf16 v[174:177], v[186:189], v[116:119], v[80:83]
	v_mfma_f32_16x16x32_bf16 v[178:181], v[202:205], v[100:103], v[68:71]
	v_mfma_f32_16x16x32_bf16 v[182:185], v[202:205], v[116:119], v[64:67]
	s_barrier
; #define LDA(dst, b, h) for (int m = 0; m < 4; ++m) for (int k = 0; k < 2; ++k) \
;     dst[m][k] = *reinterpret_cast<const bf16x8*>((char*)SA(b, h) + lds_byte(wr * 64 + m * 16 + fr, k * 32 + fq * 8))
; #define LDB(dst, b, h) for (int n = 0; n < 2; ++n) for (int k = 0; k < 2; ++k) \
;     dst[n][k] = *reinterpret_cast<const bf16x8*>((char*)SB(b, h) + lds_byte(wc * 32 + n * 16 + fr, k * 32 + fq * 8))
; #define MMA(ai, bj, At, Bt) do { __builtin_amdgcn_s_setprio(1); \
;     for (int m = 0; m < 4; ++m) for (int n = 0; n < 2; ++n) for (int k = 0; k < 2; ++k) \
;       acc[ai][bj][m][n] = __builtin_amdgcn_mfma_f32_16x16x32_bf16(At[m][k], Bt[n][k], acc[ai][bj][m][n], 0, 0, 0); \
;     __builtin_amdgcn_s_setprio(0); } while (0)
; #define WAIT_V(n) asm volatile("s_waitcnt vmcnt(" #n ")" ::: "memory")
; #define WAIT_L(n) asm volatile("s_waitcnt lgkmcnt(" #n ")" ::: "memory")
; #define BAR __builtin_amdgcn_s_barrier()
; template <int EPI> ...
;     ...
;     LDA(At, 0, 1); WAIT_V(4); BAR; WAIT_L(0); MMA(1, 0, At, B0); MMA(1, 1, At, B1); BAR; }
;   { LDB(B0, 1, 0); LDA(At, 1, 0); WAIT_V(2); BAR; WAIT_L(0); MMA(0, 0, At, B0); BAR;
	s_setprio 0
	s_nop 1
	ds_read_b128 v[64:67], v153 offset:16384
	ds_read_b128 v[68:71], v153 offset:17408
	ds_read_b128 v[80:83], v152 offset:16384
	ds_read_b128 v[84:87], v152 offset:17408
	ds_read_b128 v[186:189], v151 offset:16384
	ds_read_b128 v[190:193], v151 offset:17408
	ds_read_b128 v[194:197], v150 offset:16384
	ds_read_b128 v[198:201], v150 offset:17408
	s_waitcnt vmcnt(4)
	s_setprio 1
	s_barrier
	s_waitcnt lgkmcnt(0)
	v_mfma_f32_16x16x32_bf16 v[60:63], v[64:67], v[136:139], v[60:63]
	v_mfma_f32_16x16x32_bf16 v[56:59], v[64:67], v[158:161], v[56:59]
	v_mfma_f32_16x16x32_bf16 v[44:47], v[186:189], v[136:139], v[44:47]
	v_mfma_f32_16x16x32_bf16 v[40:43], v[186:189], v[158:161], v[40:43]
	v_mfma_f32_16x16x32_bf16 v[60:63], v[68:71], v[140:143], v[60:63]
	v_mfma_f32_16x16x32_bf16 v[56:59], v[68:71], v[162:165], v[56:59]
	v_mfma_f32_16x16x32_bf16 v[52:55], v[80:83], v[136:139], v[52:55]
	v_mfma_f32_16x16x32_bf16 v[48:51], v[80:83], v[158:161], v[48:51]
	v_mfma_f32_16x16x32_bf16 v[44:47], v[190:193], v[140:143], v[44:47]
	v_mfma_f32_16x16x32_bf16 v[40:43], v[190:193], v[162:165], v[40:43]
	v_mfma_f32_16x16x32_bf16 v[36:39], v[194:197], v[136:139], v[36:39]
	v_mfma_f32_16x16x32_bf16 v[32:35], v[194:197], v[158:161], v[32:35]
	v_mfma_f32_16x16x32_bf16 v[202:205], v[84:87], v[140:143], v[52:55]
	v_mfma_f32_16x16x32_bf16 v[218:221], v[84:87], v[162:165], v[48:51]
	v_mfma_f32_16x16x32_bf16 v[136:139], v[198:201], v[140:143], v[36:39]
	v_mfma_f32_16x16x32_bf16 v[140:143], v[198:201], v[162:165], v[32:35]
	s_setprio 0
	s_setprio 1
	v_mfma_f32_16x16x32_bf16 v[28:31], v[64:67], v[96:99], v[28:31]
	v_mfma_f32_16x16x32_bf16 v[24:27], v[64:67], v[112:115], v[24:27]
	v_mfma_f32_16x16x32_bf16 v[12:15], v[186:189], v[96:99], v[12:15]
	v_mfma_f32_16x16x32_bf16 v[8:11], v[186:189], v[112:115], v[8:11]
	v_mfma_f32_16x16x32_bf16 v[28:31], v[68:71], v[100:103], v[28:31]
	v_mfma_f32_16x16x32_bf16 v[24:27], v[68:71], v[116:119], v[24:27]
	v_mfma_f32_16x16x32_bf16 v[20:23], v[80:83], v[96:99], v[20:23]
	v_mfma_f32_16x16x32_bf16 v[16:19], v[80:83], v[112:115], v[16:19]
	v_mfma_f32_16x16x32_bf16 v[12:15], v[190:193], v[100:103], v[12:15]
	v_mfma_f32_16x16x32_bf16 v[8:11], v[190:193], v[116:119], v[8:11]
	v_mfma_f32_16x16x32_bf16 v[4:7], v[194:197], v[96:99], v[4:7]
	v_mfma_f32_16x16x32_bf16 v[0:3], v[194:197], v[112:115], v[0:3]
	v_mfma_f32_16x16x32_bf16 v[158:161], v[84:87], v[100:103], v[20:23]
	v_mfma_f32_16x16x32_bf16 v[162:165], v[84:87], v[116:119], v[16:19]
	v_mfma_f32_16x16x32_bf16 v[186:189], v[198:201], v[100:103], v[4:7]
	v_mfma_f32_16x16x32_bf16 v[190:193], v[198:201], v[116:119], v[0:3]
	s_barrier
	s_setprio 0
	s_nop 1
	ds_read_b128 v[0:3], v157
	ds_read_b128 v[4:7], v157 offset:1024
	ds_read_b128 v[194:197], v157 offset:2048
	ds_read_b128 v[198:201], v157 offset:3072
	ds_read_b128 v[16:19], v153 offset:32768
	ds_read_b128 v[20:23], v153 offset:33792
	ds_read_b128 v[32:35], v152 offset:32768
	ds_read_b128 v[36:39], v152 offset:33792
	ds_read_b128 v[48:51], v151 offset:32768
	ds_read_b128 v[52:55], v151 offset:33792
	ds_read_b128 v[222:225], v150 offset:32768
	ds_read_b128 v[226:229], v150 offset:33792
	s_waitcnt vmcnt(2)
	s_setprio 1
	s_barrier
	s_waitcnt lgkmcnt(0)
	v_mfma_f32_16x16x32_bf16 v[64:67], v[16:19], v[0:3], v[124:127]
	v_mfma_f32_16x16x32_bf16 v[116:119], v[20:23], v[4:7], v[64:67]
	v_mfma_f32_16x16x32_bf16 v[64:67], v[16:19], v[194:197], v[120:123]
	v_mfma_f32_16x16x32_bf16 v[112:115], v[20:23], v[198:201], v[64:67]
	v_mfma_f32_16x16x32_bf16 v[64:67], v[32:35], v[0:3], v[170:173]
	v_mfma_f32_16x16x32_bf16 v[100:103], v[36:39], v[4:7], v[64:67]
	v_mfma_f32_16x16x32_bf16 v[64:67], v[32:35], v[194:197], v[206:209]
	v_mfma_f32_16x16x32_bf16 v[96:99], v[36:39], v[198:201], v[64:67]
	v_mfma_f32_16x16x32_bf16 v[64:67], v[48:51], v[0:3], v[108:111]
	v_mfma_f32_16x16x32_bf16 v[84:87], v[52:55], v[4:7], v[64:67]
	v_mfma_f32_16x16x32_bf16 v[64:67], v[48:51], v[194:197], v[104:107]
	v_mfma_f32_16x16x32_bf16 v[80:83], v[52:55], v[198:201], v[64:67]
	v_mfma_f32_16x16x32_bf16 v[64:67], v[222:225], v[0:3], v[210:213]
	v_mfma_f32_16x16x32_bf16 v[68:71], v[226:229], v[4:7], v[64:67]
	v_mfma_f32_16x16x32_bf16 v[64:67], v[222:225], v[194:197], v[214:217]
	v_mfma_f32_16x16x32_bf16 v[64:67], v[226:229], v[198:201], v[64:67]
	s_barrier
; #define LDA(dst, b, h) for (int m = 0; m < 4; ++m) for (int k = 0; k < 2; ++k) \
;     dst[m][k] = *reinterpret_cast<const bf16x8*>((char*)SA(b, h) + lds_byte(wr * 64 + m * 16 + fr, k * 32 + fq * 8))
; #define LDB(dst, b, h) for (int n = 0; n < 2; ++n) for (int k = 0; k < 2; ++k) \
;     dst[n][k] = *reinterpret_cast<const bf16x8*>((char*)SB(b, h) + lds_byte(wc * 32 + n * 16 + fr, k * 32 + fq * 8))
; #define MMA(ai, bj, At, Bt) do { __builtin_amdgcn_s_setprio(1); \
;     for (int m = 0; m < 4; ++m) for (int n = 0; n < 2; ++n) for (int k = 0; k < 2; ++k) \
;       acc[ai][bj][m][n] = __builtin_amdgcn_mfma_f32_16x16x32_bf16(At[m][k], Bt[n][k], acc[ai][bj][m][n], 0, 0, 0); \
;     __builtin_amdgcn_s_setprio(0); } while (0)
; #define WAIT_V(n) asm volatile("s_waitcnt vmcnt(" #n ")" ::: "memory")
; #define WAIT_L(n) asm volatile("s_waitcnt lgkmcnt(" #n ")" ::: "memory")
; #define BAR __builtin_amdgcn_s_barrier()
; template <int EPI> ...
;     ...
;     LDB(B1, 1, 1); WAIT_V(0); BAR; WAIT_L(0); MMA(0, 1, At, B1); BAR;
;     LDA(At, 1, 1); BAR; WAIT_L(0); MMA(1, 0, At, B0); MMA(1, 1, At, B1); BAR; }
;   if (wr == 0) BAR;
	s_setprio 0
	ds_read_b128 v[170:173], v154
	ds_read_b128 v[206:209], v154 offset:1024
	ds_read_b128 v[210:213], v154 offset:2048
	ds_read_b128 v[154:157], v154 offset:3072
	s_waitcnt vmcnt(0)
	s_setprio 1
	s_barrier
	s_waitcnt lgkmcnt(0)
	v_mfma_f32_16x16x32_bf16 v[92:95], v[16:19], v[170:173], v[92:95]
	v_mfma_f32_16x16x32_bf16 v[16:19], v[16:19], v[210:213], v[88:91]
	v_mfma_f32_16x16x32_bf16 v[120:123], v[20:23], v[154:157], v[16:19]
	v_mfma_f32_16x16x32_bf16 v[16:19], v[32:35], v[170:173], v[166:169]
	v_mfma_f32_16x16x32_bf16 v[108:111], v[36:39], v[206:209], v[16:19]
	v_mfma_f32_16x16x32_bf16 v[16:19], v[32:35], v[210:213], v[174:177]
	v_mfma_f32_16x16x32_bf16 v[104:107], v[36:39], v[154:157], v[16:19]
	v_mfma_f32_16x16x32_bf16 v[16:19], v[48:51], v[170:173], v[76:79]
	v_mfma_f32_16x16x32_bf16 v[124:127], v[20:23], v[206:209], v[92:95]
	v_mfma_f32_16x16x32_bf16 v[92:95], v[52:55], v[206:209], v[16:19]
	v_mfma_f32_16x16x32_bf16 v[16:19], v[48:51], v[210:213], v[72:75]
	v_mfma_f32_16x16x32_bf16 v[88:91], v[52:55], v[154:157], v[16:19]
	v_mfma_f32_16x16x32_bf16 v[16:19], v[222:225], v[170:173], v[178:181]
	v_mfma_f32_16x16x32_bf16 v[76:79], v[226:229], v[206:209], v[16:19]
	v_mfma_f32_16x16x32_bf16 v[16:19], v[222:225], v[210:213], v[182:185]
	v_mfma_f32_16x16x32_bf16 v[72:75], v[226:229], v[154:157], v[16:19]
	s_barrier
	s_setprio 0
	ds_read_b128 v[166:169], v153 offset:49152
	ds_read_b128 v[174:177], v153 offset:50176
	ds_read_b128 v[178:181], v152 offset:49152
	ds_read_b128 v[182:185], v152 offset:50176
	ds_read_b128 v[214:217], v151 offset:49152
	ds_read_b128 v[222:225], v151 offset:50176
	ds_read_b128 v[226:229], v150 offset:49152
	ds_read_b128 v[150:153], v150 offset:50176
	s_setprio 1
	s_barrier
	s_waitcnt lgkmcnt(0)
	v_mfma_f32_16x16x32_bf16 v[16:19], v[166:169], v[0:3], v[60:63]
	v_mfma_f32_16x16x32_bf16 v[52:55], v[174:177], v[4:7], v[16:19]
	v_mfma_f32_16x16x32_bf16 v[16:19], v[166:169], v[194:197], v[56:59]
	v_mfma_f32_16x16x32_bf16 v[48:51], v[174:177], v[198:201], v[16:19]
	v_mfma_f32_16x16x32_bf16 v[16:19], v[178:181], v[0:3], v[202:205]
	v_mfma_f32_16x16x32_bf16 v[36:39], v[182:185], v[4:7], v[16:19]
	v_mfma_f32_16x16x32_bf16 v[16:19], v[178:181], v[194:197], v[218:221]
	v_mfma_f32_16x16x32_bf16 v[32:35], v[182:185], v[198:201], v[16:19]
	v_mfma_f32_16x16x32_bf16 v[16:19], v[214:217], v[0:3], v[44:47]
	v_mfma_f32_16x16x32_bf16 v[0:3], v[226:229], v[0:3], v[136:139]
	v_mfma_f32_16x16x32_bf16 v[20:23], v[222:225], v[4:7], v[16:19]
	v_mfma_f32_16x16x32_bf16 v[16:19], v[214:217], v[194:197], v[40:43]
	v_mfma_f32_16x16x32_bf16 v[4:7], v[150:153], v[4:7], v[0:3]
	v_mfma_f32_16x16x32_bf16 v[0:3], v[226:229], v[194:197], v[140:143]
	v_mfma_f32_16x16x32_bf16 v[16:19], v[222:225], v[198:201], v[16:19]
	v_mfma_f32_16x16x32_bf16 v[0:3], v[150:153], v[198:201], v[0:3]
	s_setprio 0
	s_setprio 1
	v_mfma_f32_16x16x32_bf16 v[24:27], v[166:169], v[210:213], v[24:27]
	v_mfma_f32_16x16x32_bf16 v[56:59], v[174:177], v[154:157], v[24:27]
	v_mfma_f32_16x16x32_bf16 v[24:27], v[178:181], v[170:173], v[158:161]
	v_mfma_f32_16x16x32_bf16 v[44:47], v[182:185], v[206:209], v[24:27]
	v_mfma_f32_16x16x32_bf16 v[24:27], v[178:181], v[210:213], v[162:165]
	v_mfma_f32_16x16x32_bf16 v[8:11], v[214:217], v[210:213], v[8:11]
	v_mfma_f32_16x16x32_bf16 v[28:31], v[166:169], v[170:173], v[28:31]
	v_mfma_f32_16x16x32_bf16 v[40:43], v[182:185], v[154:157], v[24:27]
	v_mfma_f32_16x16x32_bf16 v[12:15], v[214:217], v[170:173], v[12:15]
	v_mfma_f32_16x16x32_bf16 v[24:27], v[222:225], v[154:157], v[8:11]
	v_mfma_f32_16x16x32_bf16 v[8:11], v[226:229], v[170:173], v[186:189]
	v_mfma_f32_16x16x32_bf16 v[60:63], v[174:177], v[206:209], v[28:31]
	v_mfma_f32_16x16x32_bf16 v[28:31], v[222:225], v[206:209], v[12:15]
	v_mfma_f32_16x16x32_bf16 v[12:15], v[150:153], v[206:209], v[8:11]
	v_mfma_f32_16x16x32_bf16 v[8:11], v[226:229], v[210:213], v[190:193]
	v_mfma_f32_16x16x32_bf16 v[8:11], v[150:153], v[154:157], v[8:11]
	s_barrier
	s_setprio 0
	v_cmp_gt_u32_e32 vcc, s84, v144
	s_and_saveexec_b64 s[56:57], vcc
	s_cbranch_execz .LBB0_821
	s_barrier

; #define STAGE(P, BASE, kt) do { const char* _g = (const char*)(BASE) + (size_t)((kt) * (BK * 2)); \
;     __builtin_amdgcn_global_load_lds((const unsigned*)(_g + (size_t)goff0), (unsigned*)((char*)(P) + tid_ * 16), 16, 0, 0); \
;     __builtin_amdgcn_global_load_lds((const unsigned*)(_g + (size_t)goff1), (unsigned*)((char*)(P) + tid_ * 16 + 8192), 16, 0, 0); } while (0)
; #define STAGEA(P, BASE, kt) do { const char* _g = (const char*)(BASE) + (size_t)((kt) * a_kbytes); \
;     __builtin_amdgcn_global_load_lds((const unsigned*)(_g + (size_t)goffA0), (unsigned*)((char*)(P) + tid_ * 16), 16, 0, 0); \
;     __builtin_amdgcn_global_load_lds((const unsigned*)(_g + (size_t)goffA1), (unsigned*)((char*)(P) + tid_ * 16 + 8192), 16, 0, 0); } while (0)
; #define LDA(dst, b, h) for (int m = 0; m < 4; ++m) for (int k = 0; k < 2; ++k) \
;     dst[m][k] = *reinterpret_cast<const bf16x8*>((char*)SA(b, h) + lds_byte(wr * 64 + m * 16 + fr, k * 32 + fq * 8))
; #define LDB(dst, b, h) for (int n = 0; n < 2; ++n) for (int k = 0; k < 2; ++k) \
;     dst[n][k] = *reinterpret_cast<const bf16x8*>((char*)SB(b, h) + lds_byte(wc * 32 + n * 16 + fr, k * 32 + fq * 8))
; #define MMA(ai, bj, At, Bt) do { __builtin_amdgcn_s_setprio(1); \
;     for (int m = 0; m < 4; ++m) for (int n = 0; n < 2; ++n) for (int k = 0; k < 2; ++k) \
;       acc[ai][bj][m][n] = __builtin_amdgcn_mfma_f32_16x16x32_bf16(At[m][k], Bt[n][k], acc[ai][bj][m][n], 0, 0, 0); \
;     __builtin_amdgcn_s_setprio(0); } while (0)
; #define WAIT_L(n) asm volatile("s_waitcnt lgkmcnt(" #n ")" ::: "memory")
; #define BAR __builtin_amdgcn_s_barrier()
; #define SCHED __builtin_amdgcn_sched_barrier(0)
; template <int EPI> ...
;     ...
;     LDB(B0, 0, 0); SCHED; LDA(At, 0, 0); STAGEA(SA(1, 1), A1, t + 1);
;     WAIT_L(8); BAR; WAIT_L(0); MMA(0, 0, At, B0); BAR; SCHED;
;     LDB(B1, 0, 1); STAGE(SB(0, 0), B0p, t + 2);
;     BAR; WAIT_L(0); MMA(0, 1, At, B1); BAR;
;     LDA(At, 0, 1); STAGEA(SA(0, 0), A0, t + 2);
;     BAR; WAIT_L(0); MMA(1, 0, At, B0); BAR; SCHED;
.LBB0_856:
	ds_read_b128 v[174:177], v171
	ds_read_b128 v[178:181], v171 offset:1024
	ds_read_b128 v[182:185], v171 offset:2048
	ds_read_b128 v[186:189], v171 offset:3072
	v_add_u32_e32 v172, 0xc000, v158
	v_lshl_add_u64 v[238:239], s[56:57], 0, v[140:141]
	v_readfirstlane_b32 s53, v172
	v_add_u32_e32 v173, 0xe000, v158
	v_lshl_add_u64 v[222:223], v[238:239], 0, s[6:7]
	s_mov_b32 m0, s53
	v_lshl_add_u64 v[240:241], s[56:57], 0, v[142:143]
	v_readfirstlane_b32 s53, v173
	ds_read_b128 v[190:193], v153
	ds_read_b128 v[194:197], v153 offset:1024
	ds_read_b128 v[198:201], v152
	ds_read_b128 v[202:205], v152 offset:1024
	ds_read_b128 v[206:209], v151
	ds_read_b128 v[210:213], v151 offset:1024
	ds_read_b128 v[214:217], v150
	ds_read_b128 v[218:221], v150 offset:1024
	global_load_lds_dwordx4 v[222:223], off
	v_lshl_add_u64 v[222:223], v[240:241], 0, s[6:7]
	s_mov_b32 m0, s53
	s_nop 0
	global_load_lds_dwordx4 v[222:223], off
	s_waitcnt lgkmcnt(8)
	s_setprio 1
	s_barrier
	s_waitcnt lgkmcnt(0)
	v_mfma_f32_16x16x32_bf16 v[124:127], v[190:193], v[174:177], v[124:127]
	v_mfma_f32_16x16x32_bf16 v[120:123], v[190:193], v[182:185], v[120:123]
	v_mfma_f32_16x16x32_bf16 v[116:119], v[198:201], v[174:177], v[116:119]
	v_mfma_f32_16x16x32_bf16 v[112:115], v[198:201], v[182:185], v[112:115]
	v_mfma_f32_16x16x32_bf16 v[108:111], v[206:209], v[174:177], v[108:111]
	v_mfma_f32_16x16x32_bf16 v[104:107], v[206:209], v[182:185], v[104:107]
	v_mfma_f32_16x16x32_bf16 v[100:103], v[214:217], v[174:177], v[100:103]
	v_mfma_f32_16x16x32_bf16 v[96:99], v[214:217], v[182:185], v[96:99]
	v_mfma_f32_16x16x32_bf16 v[124:127], v[194:197], v[178:181], v[124:127]
	v_mfma_f32_16x16x32_bf16 v[120:123], v[194:197], v[186:189], v[120:123]
	v_mfma_f32_16x16x32_bf16 v[116:119], v[202:205], v[178:181], v[116:119]
	v_mfma_f32_16x16x32_bf16 v[112:115], v[202:205], v[186:189], v[112:115]
	v_mfma_f32_16x16x32_bf16 v[108:111], v[210:213], v[178:181], v[108:111]
	v_mfma_f32_16x16x32_bf16 v[104:107], v[210:213], v[186:189], v[104:107]
	v_mfma_f32_16x16x32_bf16 v[100:103], v[218:221], v[178:181], v[100:103]
	v_mfma_f32_16x16x32_bf16 v[96:99], v[218:221], v[186:189], v[96:99]
	s_barrier
	s_setprio 0
	v_lshl_add_u64 v[242:243], s[56:57], 0, v[136:137]
	v_readfirstlane_b32 s53, v155
	v_lshl_add_u64 v[244:245], v[242:243], 0, s[8:9]
	s_mov_b32 m0, s53
	ds_read_b128 v[222:225], v168
	ds_read_b128 v[226:229], v168 offset:1024
	ds_read_b128 v[230:233], v168 offset:2048
	ds_read_b128 v[234:237], v168 offset:3072
	global_load_lds_dwordx4 v[244:245], off
	v_lshl_add_u64 v[244:245], s[56:57], 0, v[138:139]
	v_readfirstlane_b32 s53, v156
	v_lshl_add_u64 v[246:247], v[244:245], 0, s[8:9]
	s_mov_b32 m0, s53
	s_nop 0
	global_load_lds_dwordx4 v[246:247], off
	s_setprio 1
	s_barrier
	s_waitcnt lgkmcnt(0)
	v_mfma_f32_16x16x32_bf16 v[92:95], v[190:193], v[222:225], v[92:95]
	v_mfma_f32_16x16x32_bf16 v[88:91], v[190:193], v[230:233], v[88:91]
	v_mfma_f32_16x16x32_bf16 v[84:87], v[198:201], v[222:225], v[84:87]
	v_mfma_f32_16x16x32_bf16 v[80:83], v[198:201], v[230:233], v[80:83]
	v_mfma_f32_16x16x32_bf16 v[76:79], v[206:209], v[222:225], v[76:79]
	v_mfma_f32_16x16x32_bf16 v[72:75], v[206:209], v[230:233], v[72:75]
	v_mfma_f32_16x16x32_bf16 v[68:71], v[214:217], v[222:225], v[68:71]
	v_mfma_f32_16x16x32_bf16 v[64:67], v[214:217], v[230:233], v[64:67]
	v_mfma_f32_16x16x32_bf16 v[92:95], v[194:197], v[226:229], v[92:95]
	v_mfma_f32_16x16x32_bf16 v[88:91], v[194:197], v[234:237], v[88:91]
	v_mfma_f32_16x16x32_bf16 v[84:87], v[202:205], v[226:229], v[84:87]
	v_mfma_f32_16x16x32_bf16 v[80:83], v[202:205], v[234:237], v[80:83]
	v_mfma_f32_16x16x32_bf16 v[76:79], v[210:213], v[226:229], v[76:79]
	v_mfma_f32_16x16x32_bf16 v[72:75], v[210:213], v[234:237], v[72:75]
	v_mfma_f32_16x16x32_bf16 v[68:71], v[218:221], v[226:229], v[68:71]
	v_mfma_f32_16x16x32_bf16 v[64:67], v[218:221], v[234:237], v[64:67]
	s_barrier
	s_setprio 0
	v_readfirstlane_b32 s53, v158
	v_lshl_add_u64 v[246:247], v[238:239], 0, s[10:11]
	s_mov_b32 m0, s53
	v_readfirstlane_b32 s53, v159
	ds_read_b128 v[190:193], v153 offset:16384
	ds_read_b128 v[194:197], v153 offset:17408
	ds_read_b128 v[198:201], v152 offset:16384
	ds_read_b128 v[202:205], v152 offset:17408
	ds_read_b128 v[206:209], v151 offset:16384
	ds_read_b128 v[210:213], v151 offset:17408
	ds_read_b128 v[214:217], v150 offset:16384
	ds_read_b128 v[218:221], v150 offset:17408
	global_load_lds_dwordx4 v[246:247], off
	v_lshl_add_u64 v[246:247], v[240:241], 0, s[10:11]
	s_mov_b32 m0, s53
	s_nop 0
	global_load_lds_dwordx4 v[246:247], off
	s_setprio 1
	s_barrier
	s_waitcnt lgkmcnt(0)
	v_mfma_f32_16x16x32_bf16 v[60:63], v[190:193], v[174:177], v[60:63]
	v_mfma_f32_16x16x32_bf16 v[56:59], v[190:193], v[182:185], v[56:59]
	v_mfma_f32_16x16x32_bf16 v[52:55], v[198:201], v[174:177], v[52:55]
	v_mfma_f32_16x16x32_bf16 v[48:51], v[198:201], v[182:185], v[48:51]
	v_mfma_f32_16x16x32_bf16 v[44:47], v[206:209], v[174:177], v[44:47]
	v_mfma_f32_16x16x32_bf16 v[40:43], v[206:209], v[182:185], v[40:43]
	v_mfma_f32_16x16x32_bf16 v[36:39], v[214:217], v[174:177], v[36:39]
	v_mfma_f32_16x16x32_bf16 v[32:35], v[214:217], v[182:185], v[32:35]
	v_mfma_f32_16x16x32_bf16 v[60:63], v[194:197], v[178:181], v[60:63]
	v_mfma_f32_16x16x32_bf16 v[56:59], v[194:197], v[186:189], v[56:59]
	v_mfma_f32_16x16x32_bf16 v[52:55], v[202:205], v[178:181], v[52:55]
	v_mfma_f32_16x16x32_bf16 v[48:51], v[202:205], v[186:189], v[48:51]
	v_mfma_f32_16x16x32_bf16 v[44:47], v[210:213], v[178:181], v[44:47]
	v_mfma_f32_16x16x32_bf16 v[40:43], v[210:213], v[186:189], v[40:43]
	v_mfma_f32_16x16x32_bf16 v[36:39], v[218:221], v[178:181], v[36:39]
	v_mfma_f32_16x16x32_bf16 v[32:35], v[218:221], v[186:189], v[32:35]
	s_barrier
; #define STAGE(P, BASE, kt) do { const char* _g = (const char*)(BASE) + (size_t)((kt) * (BK * 2)); \
;     __builtin_amdgcn_global_load_lds((const unsigned*)(_g + (size_t)goff0), (unsigned*)((char*)(P) + tid_ * 16), 16, 0, 0); \
;     __builtin_amdgcn_global_load_lds((const unsigned*)(_g + (size_t)goff1), (unsigned*)((char*)(P) + tid_ * 16 + 8192), 16, 0, 0); } while (0)
; #define STAGEA(P, BASE, kt) do { const char* _g = (const char*)(BASE) + (size_t)((kt) * a_kbytes); \
;     __builtin_amdgcn_global_load_lds((const unsigned*)(_g + (size_t)goffA0), (unsigned*)((char*)(P) + tid_ * 16), 16, 0, 0); \
;     __builtin_amdgcn_global_load_lds((const unsigned*)(_g + (size_t)goffA1), (unsigned*)((char*)(P) + tid_ * 16 + 8192), 16, 0, 0); } while (0)
; #define LDA(dst, b, h) for (int m = 0; m < 4; ++m) for (int k = 0; k < 2; ++k) \
;     dst[m][k] = *reinterpret_cast<const bf16x8*>((char*)SA(b, h) + lds_byte(wr * 64 + m * 16 + fr, k * 32 + fq * 8))
; #define LDB(dst, b, h) for (int n = 0; n < 2; ++n) for (int k = 0; k < 2; ++k) \
;     dst[n][k] = *reinterpret_cast<const bf16x8*>((char*)SB(b, h) + lds_byte(wc * 32 + n * 16 + fr, k * 32 + fq * 8))
; #define MMA(ai, bj, At, Bt) do { __builtin_amdgcn_s_setprio(1); \
;     for (int m = 0; m < 4; ++m) for (int n = 0; n < 2; ++n) for (int k = 0; k < 2; ++k) \
;       acc[ai][bj][m][n] = __builtin_amdgcn_mfma_f32_16x16x32_bf16(At[m][k], Bt[n][k], acc[ai][bj][m][n], 0, 0, 0); \
;     __builtin_amdgcn_s_setprio(0); } while (0)
; #define WAIT_V(n) asm volatile("s_waitcnt vmcnt(" #n ")" ::: "memory")
; #define WAIT_L(n) asm volatile("s_waitcnt lgkmcnt(" #n ")" ::: "memory")
; #define BAR __builtin_amdgcn_s_barrier()
; #define SCHED __builtin_amdgcn_sched_barrier(0)
; template <int EPI> ...
;     ...
;     STAGE(SB(0, 1), B1p, t + 2);
;     WAIT_V(6); BAR; MMA(1, 1, At, B1); BAR;
;     LDB(B0, 1, 0); SCHED; LDA(At, 1, 0); STAGEA(SA(0, 1), A1, t + 2);
;     WAIT_L(8); BAR; WAIT_L(0); MMA(0, 0, At, B0); BAR; SCHED;
;     LDB(B1, 1, 1); STAGE(SB(1, 0), B0p, t + 3);
;     BAR; WAIT_L(0); MMA(0, 1, At, B1); BAR;
;     LDA(At, 1, 1); STAGEA(SA(1, 0), A0, t + 3);
	s_setprio 0
	v_readfirstlane_b32 s53, v160
	v_lshl_add_u64 v[174:175], v[242:243], 0, s[12:13]
	s_mov_b32 m0, s53
	v_readfirstlane_b32 s53, v161
	global_load_lds_dwordx4 v[174:175], off
	v_lshl_add_u64 v[174:175], v[244:245], 0, s[12:13]
	s_mov_b32 m0, s53
	s_nop 0
	global_load_lds_dwordx4 v[174:175], off
	s_waitcnt vmcnt(6)
	s_setprio 1
	s_barrier
	v_mfma_f32_16x16x32_bf16 v[28:31], v[190:193], v[222:225], v[28:31]
	v_mfma_f32_16x16x32_bf16 v[24:27], v[190:193], v[230:233], v[24:27]
	v_mfma_f32_16x16x32_bf16 v[20:23], v[198:201], v[222:225], v[20:23]
	v_mfma_f32_16x16x32_bf16 v[16:19], v[198:201], v[230:233], v[16:19]
	v_mfma_f32_16x16x32_bf16 v[12:15], v[206:209], v[222:225], v[12:15]
	v_mfma_f32_16x16x32_bf16 v[8:11], v[206:209], v[230:233], v[8:11]
	v_mfma_f32_16x16x32_bf16 v[4:7], v[214:217], v[222:225], v[4:7]
	v_mfma_f32_16x16x32_bf16 v[0:3], v[214:217], v[230:233], v[0:3]
	v_mfma_f32_16x16x32_bf16 v[28:31], v[194:197], v[226:229], v[28:31]
	v_mfma_f32_16x16x32_bf16 v[24:27], v[194:197], v[234:237], v[24:27]
	v_mfma_f32_16x16x32_bf16 v[20:23], v[202:205], v[226:229], v[20:23]
	v_mfma_f32_16x16x32_bf16 v[16:19], v[202:205], v[234:237], v[16:19]
	v_mfma_f32_16x16x32_bf16 v[12:15], v[210:213], v[226:229], v[12:15]
	v_mfma_f32_16x16x32_bf16 v[8:11], v[210:213], v[234:237], v[8:11]
	v_mfma_f32_16x16x32_bf16 v[4:7], v[218:221], v[226:229], v[4:7]
	v_mfma_f32_16x16x32_bf16 v[0:3], v[218:221], v[234:237], v[0:3]
	s_barrier
	s_setprio 0
	ds_read_b128 v[174:177], v157
	ds_read_b128 v[178:181], v157 offset:1024
	ds_read_b128 v[182:185], v157 offset:2048
	ds_read_b128 v[186:189], v157 offset:3072
	v_readfirstlane_b32 s53, v162
	v_lshl_add_u64 v[222:223], v[238:239], 0, s[14:15]
	s_mov_b32 m0, s53
	v_readfirstlane_b32 s53, v163
	ds_read_b128 v[190:193], v153 offset:32768
	ds_read_b128 v[194:197], v153 offset:33792
	ds_read_b128 v[198:201], v152 offset:32768
	ds_read_b128 v[202:205], v152 offset:33792
	ds_read_b128 v[206:209], v151 offset:32768
	ds_read_b128 v[210:213], v151 offset:33792
	ds_read_b128 v[214:217], v150 offset:32768
	ds_read_b128 v[218:221], v150 offset:33792
	global_load_lds_dwordx4 v[222:223], off
	v_lshl_add_u64 v[222:223], v[240:241], 0, s[14:15]
	s_mov_b32 m0, s53
	s_nop 0
	global_load_lds_dwordx4 v[222:223], off
	s_waitcnt lgkmcnt(8)
	s_setprio 1
	s_barrier
	s_waitcnt lgkmcnt(0)
	v_mfma_f32_16x16x32_bf16 v[124:127], v[190:193], v[174:177], v[124:127]
	v_mfma_f32_16x16x32_bf16 v[120:123], v[190:193], v[182:185], v[120:123]
	v_mfma_f32_16x16x32_bf16 v[116:119], v[198:201], v[174:177], v[116:119]
	v_mfma_f32_16x16x32_bf16 v[112:115], v[198:201], v[182:185], v[112:115]
	v_mfma_f32_16x16x32_bf16 v[108:111], v[206:209], v[174:177], v[108:111]
	v_mfma_f32_16x16x32_bf16 v[104:107], v[206:209], v[182:185], v[104:107]
	v_mfma_f32_16x16x32_bf16 v[100:103], v[214:217], v[174:177], v[100:103]
	v_mfma_f32_16x16x32_bf16 v[96:99], v[214:217], v[182:185], v[96:99]
	v_mfma_f32_16x16x32_bf16 v[124:127], v[194:197], v[178:181], v[124:127]
	v_mfma_f32_16x16x32_bf16 v[120:123], v[194:197], v[186:189], v[120:123]
	v_mfma_f32_16x16x32_bf16 v[116:119], v[202:205], v[178:181], v[116:119]
	v_mfma_f32_16x16x32_bf16 v[112:115], v[202:205], v[186:189], v[112:115]
	v_mfma_f32_16x16x32_bf16 v[108:111], v[210:213], v[178:181], v[108:111]
	v_mfma_f32_16x16x32_bf16 v[104:107], v[210:213], v[186:189], v[104:107]
	v_mfma_f32_16x16x32_bf16 v[100:103], v[218:221], v[178:181], v[100:103]
	v_mfma_f32_16x16x32_bf16 v[96:99], v[218:221], v[186:189], v[96:99]
	s_barrier
	s_setprio 0
	v_readfirstlane_b32 s53, v164
	v_lshl_add_u64 v[246:247], v[242:243], 0, s[24:25]
	s_mov_b32 m0, s53
	v_readfirstlane_b32 s53, v165
	ds_read_b128 v[222:225], v154
	ds_read_b128 v[226:229], v154 offset:1024
	ds_read_b128 v[230:233], v154 offset:2048
	ds_read_b128 v[234:237], v154 offset:3072
	global_load_lds_dwordx4 v[246:247], off
	v_lshl_add_u64 v[246:247], v[244:245], 0, s[24:25]
	s_mov_b32 m0, s53
	s_nop 0
	global_load_lds_dwordx4 v[246:247], off
	s_setprio 1
	s_barrier
	s_waitcnt lgkmcnt(0)
	v_mfma_f32_16x16x32_bf16 v[92:95], v[190:193], v[222:225], v[92:95]
	v_mfma_f32_16x16x32_bf16 v[88:91], v[190:193], v[230:233], v[88:91]
	v_mfma_f32_16x16x32_bf16 v[84:87], v[198:201], v[222:225], v[84:87]
	v_mfma_f32_16x16x32_bf16 v[80:83], v[198:201], v[230:233], v[80:83]
	v_mfma_f32_16x16x32_bf16 v[76:79], v[206:209], v[222:225], v[76:79]
	v_mfma_f32_16x16x32_bf16 v[72:75], v[206:209], v[230:233], v[72:75]
	v_mfma_f32_16x16x32_bf16 v[68:71], v[214:217], v[222:225], v[68:71]
	v_mfma_f32_16x16x32_bf16 v[64:67], v[214:217], v[230:233], v[64:67]
	v_mfma_f32_16x16x32_bf16 v[92:95], v[194:197], v[226:229], v[92:95]
	v_mfma_f32_16x16x32_bf16 v[88:91], v[194:197], v[234:237], v[88:91]
	v_mfma_f32_16x16x32_bf16 v[84:87], v[202:205], v[226:229], v[84:87]
	v_mfma_f32_16x16x32_bf16 v[80:83], v[202:205], v[234:237], v[80:83]
	v_mfma_f32_16x16x32_bf16 v[76:79], v[210:213], v[226:229], v[76:79]
	v_mfma_f32_16x16x32_bf16 v[72:75], v[210:213], v[234:237], v[72:75]
	v_mfma_f32_16x16x32_bf16 v[68:71], v[218:221], v[226:229], v[68:71]
	v_mfma_f32_16x16x32_bf16 v[64:67], v[218:221], v[234:237], v[64:67]
	s_barrier
	s_setprio 0
	v_readfirstlane_b32 s53, v166
	v_lshl_add_u64 v[238:239], v[238:239], 0, s[36:37]
	s_mov_b32 m0, s53
	v_readfirstlane_b32 s53, v167
	ds_read_b128 v[190:193], v153 offset:49152
	ds_read_b128 v[194:197], v153 offset:50176
	ds_read_b128 v[198:201], v152 offset:49152
	ds_read_b128 v[202:205], v152 offset:50176
	ds_read_b128 v[206:209], v151 offset:49152
	ds_read_b128 v[210:213], v151 offset:50176
	ds_read_b128 v[214:217], v150 offset:49152
	ds_read_b128 v[218:221], v150 offset:50176
	global_load_lds_dwordx4 v[238:239], off
	v_lshl_add_u64 v[238:239], v[240:241], 0, s[36:37]
	s_mov_b32 m0, s53
	s_nop 0
	global_load_lds_dwordx4 v[238:239], off
	s_setprio 1
	s_barrier
; #define STAGE(P, BASE, kt) do { const char* _g = (const char*)(BASE) + (size_t)((kt) * (BK * 2)); \
;     __builtin_amdgcn_global_load_lds((const unsigned*)(_g + (size_t)goff0), (unsigned*)((char*)(P) + tid_ * 16), 16, 0, 0); \
;     __builtin_amdgcn_global_load_lds((const unsigned*)(_g + (size_t)goff1), (unsigned*)((char*)(P) + tid_ * 16 + 8192), 16, 0, 0); } while (0)
; #define STAGEA(P, BASE, kt) do { const char* _g = (const char*)(BASE) + (size_t)((kt) * a_kbytes); \
;     __builtin_amdgcn_global_load_lds((const unsigned*)(_g + (size_t)goffA0), (unsigned*)((char*)(P) + tid_ * 16), 16, 0, 0); \
;     __builtin_amdgcn_global_load_lds((const unsigned*)(_g + (size_t)goffA1), (unsigned*)((char*)(P) + tid_ * 16 + 8192), 16, 0, 0); } while (0)
; #define LDA(dst, b, h) for (int m = 0; m < 4; ++m) for (int k = 0; k < 2; ++k) \
;     dst[m][k] = *reinterpret_cast<const bf16x8*>((char*)SA(b, h) + lds_byte(wr * 64 + m * 16 + fr, k * 32 + fq * 8))
; #define LDB(dst, b, h) for (int n = 0; n < 2; ++n) for (int k = 0; k < 2; ++k) \
;     dst[n][k] = *reinterpret_cast<const bf16x8*>((char*)SB(b, h) + lds_byte(wc * 32 + n * 16 + fr, k * 32 + fq * 8))
; #define MMA(ai, bj, At, Bt) do { __builtin_amdgcn_s_setprio(1); \
;     for (int m = 0; m < 4; ++m) for (int n = 0; n < 2; ++n) for (int k = 0; k < 2; ++k) \
;       acc[ai][bj][m][n] = __builtin_amdgcn_mfma_f32_16x16x32_bf16(At[m][k], Bt[n][k], acc[ai][bj][m][n], 0, 0, 0); \
;     __builtin_amdgcn_s_setprio(0); } while (0)
; #define WAIT_V(n) asm volatile("s_waitcnt vmcnt(" #n ")" ::: "memory")
; #define WAIT_L(n) asm volatile("s_waitcnt lgkmcnt(" #n ")" ::: "memory")
; #define BAR __builtin_amdgcn_s_barrier()
; #define SCHED __builtin_amdgcn_sched_barrier(0)
; template <int EPI> ...
;     ...
;     BAR; WAIT_L(0); MMA(1, 0, At, B0); BAR; SCHED;
;     STAGE(SB(1, 1), B1p, t + 3);
;     WAIT_V(6); BAR; MMA(1, 1, At, B1); BAR;
;   }
;   { LDB(B0, 0, 0); LDA(At, 0, 0); STAGEA(SA(1, 1), A1, nt - 1);
;     BAR; WAIT_L(0); MMA(0, 0, At, B0); BAR;
;     LDB(B1, 0, 1); BAR; WAIT_L(0); MMA(0, 1, At, B1); BAR;
	s_waitcnt lgkmcnt(0)
	v_mfma_f32_16x16x32_bf16 v[60:63], v[190:193], v[174:177], v[60:63]
	v_mfma_f32_16x16x32_bf16 v[56:59], v[190:193], v[182:185], v[56:59]
	v_mfma_f32_16x16x32_bf16 v[52:55], v[198:201], v[174:177], v[52:55]
	v_mfma_f32_16x16x32_bf16 v[48:51], v[198:201], v[182:185], v[48:51]
	v_mfma_f32_16x16x32_bf16 v[44:47], v[206:209], v[174:177], v[44:47]
	v_mfma_f32_16x16x32_bf16 v[40:43], v[206:209], v[182:185], v[40:43]
	v_mfma_f32_16x16x32_bf16 v[36:39], v[214:217], v[174:177], v[36:39]
	v_mfma_f32_16x16x32_bf16 v[32:35], v[214:217], v[182:185], v[32:35]
	v_mfma_f32_16x16x32_bf16 v[60:63], v[194:197], v[178:181], v[60:63]
	v_mfma_f32_16x16x32_bf16 v[56:59], v[194:197], v[186:189], v[56:59]
	v_mfma_f32_16x16x32_bf16 v[52:55], v[202:205], v[178:181], v[52:55]
	v_mfma_f32_16x16x32_bf16 v[48:51], v[202:205], v[186:189], v[48:51]
	v_mfma_f32_16x16x32_bf16 v[44:47], v[210:213], v[178:181], v[44:47]
	v_mfma_f32_16x16x32_bf16 v[40:43], v[210:213], v[186:189], v[40:43]
	v_mfma_f32_16x16x32_bf16 v[36:39], v[218:221], v[178:181], v[36:39]
	v_mfma_f32_16x16x32_bf16 v[32:35], v[218:221], v[186:189], v[32:35]
	s_barrier
	s_setprio 0
	v_readfirstlane_b32 s53, v169
	v_lshl_add_u64 v[174:175], v[242:243], 0, s[42:43]
	s_mov_b32 m0, s53
	v_readfirstlane_b32 s53, v170
	global_load_lds_dwordx4 v[174:175], off
	v_lshl_add_u64 v[174:175], v[244:245], 0, s[42:43]
	s_mov_b32 m0, s53
	s_nop 0
	global_load_lds_dwordx4 v[174:175], off
	s_waitcnt vmcnt(6)
	s_setprio 1
	s_barrier
	v_mfma_f32_16x16x32_bf16 v[28:31], v[190:193], v[222:225], v[28:31]
	v_mfma_f32_16x16x32_bf16 v[24:27], v[190:193], v[230:233], v[24:27]
	v_mfma_f32_16x16x32_bf16 v[20:23], v[198:201], v[222:225], v[20:23]
	v_mfma_f32_16x16x32_bf16 v[16:19], v[198:201], v[230:233], v[16:19]
	v_mfma_f32_16x16x32_bf16 v[12:15], v[206:209], v[222:225], v[12:15]
	v_mfma_f32_16x16x32_bf16 v[8:11], v[206:209], v[230:233], v[8:11]
	v_mfma_f32_16x16x32_bf16 v[4:7], v[214:217], v[222:225], v[4:7]
	v_mfma_f32_16x16x32_bf16 v[0:3], v[214:217], v[230:233], v[0:3]
	v_mfma_f32_16x16x32_bf16 v[28:31], v[194:197], v[226:229], v[28:31]
	v_mfma_f32_16x16x32_bf16 v[24:27], v[194:197], v[234:237], v[24:27]
	v_mfma_f32_16x16x32_bf16 v[20:23], v[202:205], v[226:229], v[20:23]
	v_mfma_f32_16x16x32_bf16 v[16:19], v[202:205], v[234:237], v[16:19]
	v_mfma_f32_16x16x32_bf16 v[12:15], v[210:213], v[226:229], v[12:15]
	v_mfma_f32_16x16x32_bf16 v[8:11], v[210:213], v[234:237], v[8:11]
	v_mfma_f32_16x16x32_bf16 v[4:7], v[218:221], v[226:229], v[4:7]
	v_mfma_f32_16x16x32_bf16 v[0:3], v[218:221], v[234:237], v[0:3]
	s_barrier
	s_setprio 0
	s_add_i32 s49, s49, 2
	s_add_u32 s56, s56, 0x100
	s_addc_u32 s57, s57, 0
	s_cmp_lt_u32 s49, 28
	s_cbranch_scc1 .LBB0_856
	s_add_u32 s54, s54, 0x80f80
	s_addc_u32 s55, s55, 0
	v_readfirstlane_b32 s49, v172
	v_lshl_add_u64 v[166:167], s[54:55], 0, v[130:131]
	s_mov_b32 m0, s49
	v_readfirstlane_b32 s49, v173
	ds_read_b128 v[136:139], v171
	ds_read_b128 v[140:143], v171 offset:1024
	ds_read_b128 v[158:161], v171 offset:2048
	ds_read_b128 v[162:165], v171 offset:3072
	ds_read_b128 v[174:177], v153
	ds_read_b128 v[178:181], v153 offset:1024
	ds_read_b128 v[182:185], v152
	ds_read_b128 v[186:189], v152 offset:1024
	ds_read_b128 v[190:193], v151
	ds_read_b128 v[194:197], v151 offset:1024
	ds_read_b128 v[198:201], v150
	ds_read_b128 v[202:205], v150 offset:1024
	global_load_lds_dwordx4 v[166:167], off
	v_lshl_add_u64 v[166:167], s[54:55], 0, v[128:129]
	s_mov_b32 m0, s49
	s_nop 0
	global_load_lds_dwordx4 v[166:167], off
	s_setprio 1
	s_barrier
	s_waitcnt lgkmcnt(0)
	v_mfma_f32_16x16x32_bf16 v[124:127], v[174:177], v[136:139], v[124:127]
	v_mfma_f32_16x16x32_bf16 v[120:123], v[174:177], v[158:161], v[120:123]
	v_mfma_f32_16x16x32_bf16 v[108:111], v[190:193], v[136:139], v[108:111]
	v_mfma_f32_16x16x32_bf16 v[104:107], v[190:193], v[158:161], v[104:107]
	v_mfma_f32_16x16x32_bf16 v[124:127], v[178:181], v[140:143], v[124:127]
	v_mfma_f32_16x16x32_bf16 v[120:123], v[178:181], v[162:165], v[120:123]
	v_mfma_f32_16x16x32_bf16 v[116:119], v[182:185], v[136:139], v[116:119]
	v_mfma_f32_16x16x32_bf16 v[112:115], v[182:185], v[158:161], v[112:115]
	v_mfma_f32_16x16x32_bf16 v[108:111], v[194:197], v[140:143], v[108:111]
	v_mfma_f32_16x16x32_bf16 v[104:107], v[194:197], v[162:165], v[104:107]
	v_mfma_f32_16x16x32_bf16 v[100:103], v[198:201], v[136:139], v[100:103]
	v_mfma_f32_16x16x32_bf16 v[96:99], v[198:201], v[158:161], v[96:99]
	v_mfma_f32_16x16x32_bf16 v[170:173], v[186:189], v[140:143], v[116:119]
	v_mfma_f32_16x16x32_bf16 v[206:209], v[186:189], v[162:165], v[112:115]
	v_mfma_f32_16x16x32_bf16 v[210:213], v[202:205], v[140:143], v[100:103]
	v_mfma_f32_16x16x32_bf16 v[214:217], v[202:205], v[162:165], v[96:99]
	s_barrier
	s_setprio 0
	s_nop 1
	ds_read_b128 v[96:99], v168
	ds_read_b128 v[100:103], v168 offset:1024
	ds_read_b128 v[112:115], v168 offset:2048
	ds_read_b128 v[116:119], v168 offset:3072
	s_setprio 1
	s_barrier
	s_waitcnt lgkmcnt(0)
	v_mfma_f32_16x16x32_bf16 v[92:95], v[174:177], v[96:99], v[92:95]
	v_mfma_f32_16x16x32_bf16 v[88:91], v[174:177], v[112:115], v[88:91]
	v_mfma_f32_16x16x32_bf16 v[76:79], v[190:193], v[96:99], v[76:79]
	v_mfma_f32_16x16x32_bf16 v[72:75], v[190:193], v[112:115], v[72:75]
	v_mfma_f32_16x16x32_bf16 v[92:95], v[178:181], v[100:103], v[92:95]
	v_mfma_f32_16x16x32_bf16 v[88:91], v[178:181], v[116:119], v[88:91]
	v_mfma_f32_16x16x32_bf16 v[84:87], v[182:185], v[96:99], v[84:87]
	v_mfma_f32_16x16x32_bf16 v[80:83], v[182:185], v[112:115], v[80:83]
	v_mfma_f32_16x16x32_bf16 v[76:79], v[194:197], v[100:103], v[76:79]
	v_mfma_f32_16x16x32_bf16 v[72:75], v[194:197], v[116:119], v[72:75]
	v_mfma_f32_16x16x32_bf16 v[68:71], v[198:201], v[96:99], v[68:71]
	v_mfma_f32_16x16x32_bf16 v[64:67], v[198:201], v[112:115], v[64:67]
	v_mfma_f32_16x16x32_bf16 v[166:169], v[186:189], v[100:103], v[84:87]
	v_mfma_f32_16x16x32_bf16 v[174:177], v[186:189], v[116:119], v[80:83]
	v_mfma_f32_16x16x32_bf16 v[178:181], v[202:205], v[100:103], v[68:71]
	v_mfma_f32_16x16x32_bf16 v[182:185], v[202:205], v[116:119], v[64:67]
	s_barrier
; #define LDA(dst, b, h) for (int m = 0; m < 4; ++m) for (int k = 0; k < 2; ++k) \
;     dst[m][k] = *reinterpret_cast<const bf16x8*>((char*)SA(b, h) + lds_byte(wr * 64 + m * 16 + fr, k * 32 + fq * 8))
; #define LDB(dst, b, h) for (int n = 0; n < 2; ++n) for (int k = 0; k < 2; ++k) \
;     dst[n][k] = *reinterpret_cast<const bf16x8*>((char*)SB(b, h) + lds_byte(wc * 32 + n * 16 + fr, k * 32 + fq * 8))
; #define MMA(ai, bj, At, Bt) do { __builtin_amdgcn_s_setprio(1); \
;     for (int m = 0; m < 4; ++m) for (int n = 0; n < 2; ++n) for (int k = 0; k < 2; ++k) \
;       acc[ai][bj][m][n] = __builtin_amdgcn_mfma_f32_16x16x32_bf16(At[m][k], Bt[n][k], acc[ai][bj][m][n], 0, 0, 0); \
;     __builtin_amdgcn_s_setprio(0); } while (0)
; #define WAIT_V(n) asm volatile("s_waitcnt vmcnt(" #n ")" ::: "memory")
; #define WAIT_L(n) asm volatile("s_waitcnt lgkmcnt(" #n ")" ::: "memory")
; #define BAR __builtin_amdgcn_s_barrier()
; template <int EPI> ...
;     ...
;     LDA(At, 0, 1); WAIT_V(4); BAR; WAIT_L(0); MMA(1, 0, At, B0); MMA(1, 1, At, B1); BAR; }
;   { LDB(B0, 1, 0); LDA(At, 1, 0); WAIT_V(2); BAR; WAIT_L(0); MMA(0, 0, At, B0); BAR;
	s_setprio 0
	s_nop 1
	ds_read_b128 v[64:67], v153 offset:16384
	ds_read_b128 v[68:71], v153 offset:17408
	ds_read_b128 v[80:83], v152 offset:16384
	ds_read_b128 v[84:87], v152 offset:17408
	ds_read_b128 v[186:189], v151 offset:16384
	ds_read_b128 v[190:193], v151 offset:17408
	ds_read_b128 v[194:197], v150 offset:16384
	ds_read_b128 v[198:201], v150 offset:17408
	s_waitcnt vmcnt(4)
	s_setprio 1
	s_barrier
	s_waitcnt lgkmcnt(0)
	v_mfma_f32_16x16x32_bf16 v[60:63], v[64:67], v[136:139], v[60:63]
	v_mfma_f32_16x16x32_bf16 v[56:59], v[64:67], v[158:161], v[56:59]
	v_mfma_f32_16x16x32_bf16 v[44:47], v[186:189], v[136:139], v[44:47]
	v_mfma_f32_16x16x32_bf16 v[40:43], v[186:189], v[158:161], v[40:43]
	v_mfma_f32_16x16x32_bf16 v[60:63], v[68:71], v[140:143], v[60:63]
	v_mfma_f32_16x16x32_bf16 v[56:59], v[68:71], v[162:165], v[56:59]
	v_mfma_f32_16x16x32_bf16 v[52:55], v[80:83], v[136:139], v[52:55]
	v_mfma_f32_16x16x32_bf16 v[48:51], v[80:83], v[158:161], v[48:51]
	v_mfma_f32_16x16x32_bf16 v[44:47], v[190:193], v[140:143], v[44:47]
	v_mfma_f32_16x16x32_bf16 v[40:43], v[190:193], v[162:165], v[40:43]
	v_mfma_f32_16x16x32_bf16 v[36:39], v[194:197], v[136:139], v[36:39]
	v_mfma_f32_16x16x32_bf16 v[32:35], v[194:197], v[158:161], v[32:35]
	v_mfma_f32_16x16x32_bf16 v[202:205], v[84:87], v[140:143], v[52:55]
	v_mfma_f32_16x16x32_bf16 v[218:221], v[84:87], v[162:165], v[48:51]
	v_mfma_f32_16x16x32_bf16 v[136:139], v[198:201], v[140:143], v[36:39]
	v_mfma_f32_16x16x32_bf16 v[140:143], v[198:201], v[162:165], v[32:35]
	s_setprio 0
	s_setprio 1
	v_mfma_f32_16x16x32_bf16 v[28:31], v[64:67], v[96:99], v[28:31]
	v_mfma_f32_16x16x32_bf16 v[24:27], v[64:67], v[112:115], v[24:27]
	v_mfma_f32_16x16x32_bf16 v[12:15], v[186:189], v[96:99], v[12:15]
	v_mfma_f32_16x16x32_bf16 v[8:11], v[186:189], v[112:115], v[8:11]
	v_mfma_f32_16x16x32_bf16 v[28:31], v[68:71], v[100:103], v[28:31]
	v_mfma_f32_16x16x32_bf16 v[24:27], v[68:71], v[116:119], v[24:27]
	v_mfma_f32_16x16x32_bf16 v[20:23], v[80:83], v[96:99], v[20:23]
	v_mfma_f32_16x16x32_bf16 v[16:19], v[80:83], v[112:115], v[16:19]
	v_mfma_f32_16x16x32_bf16 v[12:15], v[190:193], v[100:103], v[12:15]
	v_mfma_f32_16x16x32_bf16 v[8:11], v[190:193], v[116:119], v[8:11]
	v_mfma_f32_16x16x32_bf16 v[4:7], v[194:197], v[96:99], v[4:7]
	v_mfma_f32_16x16x32_bf16 v[0:3], v[194:197], v[112:115], v[0:3]
	v_mfma_f32_16x16x32_bf16 v[158:161], v[84:87], v[100:103], v[20:23]
	v_mfma_f32_16x16x32_bf16 v[162:165], v[84:87], v[116:119], v[16:19]
	v_mfma_f32_16x16x32_bf16 v[186:189], v[198:201], v[100:103], v[4:7]
	v_mfma_f32_16x16x32_bf16 v[190:193], v[198:201], v[116:119], v[0:3]
	s_barrier
	s_setprio 0
	s_nop 1
	ds_read_b128 v[0:3], v157
	ds_read_b128 v[4:7], v157 offset:1024
	ds_read_b128 v[194:197], v157 offset:2048
	ds_read_b128 v[198:201], v157 offset:3072
	ds_read_b128 v[16:19], v153 offset:32768
	ds_read_b128 v[20:23], v153 offset:33792
	ds_read_b128 v[32:35], v152 offset:32768
	ds_read_b128 v[36:39], v152 offset:33792
	ds_read_b128 v[48:51], v151 offset:32768
	ds_read_b128 v[52:55], v151 offset:33792
	ds_read_b128 v[222:225], v150 offset:32768
	ds_read_b128 v[226:229], v150 offset:33792
	s_waitcnt vmcnt(2)
	s_setprio 1
	s_barrier
	s_waitcnt lgkmcnt(0)
	v_mfma_f32_16x16x32_bf16 v[64:67], v[16:19], v[0:3], v[124:127]
	v_mfma_f32_16x16x32_bf16 v[116:119], v[20:23], v[4:7], v[64:67]
	v_mfma_f32_16x16x32_bf16 v[64:67], v[16:19], v[194:197], v[120:123]
	v_mfma_f32_16x16x32_bf16 v[112:115], v[20:23], v[198:201], v[64:67]
	v_mfma_f32_16x16x32_bf16 v[64:67], v[32:35], v[0:3], v[170:173]
	v_mfma_f32_16x16x32_bf16 v[100:103], v[36:39], v[4:7], v[64:67]
	v_mfma_f32_16x16x32_bf16 v[64:67], v[32:35], v[194:197], v[206:209]
	v_mfma_f32_16x16x32_bf16 v[96:99], v[36:39], v[198:201], v[64:67]
	v_mfma_f32_16x16x32_bf16 v[64:67], v[48:51], v[0:3], v[108:111]
	v_mfma_f32_16x16x32_bf16 v[84:87], v[52:55], v[4:7], v[64:67]
	v_mfma_f32_16x16x32_bf16 v[64:67], v[48:51], v[194:197], v[104:107]
	v_mfma_f32_16x16x32_bf16 v[80:83], v[52:55], v[198:201], v[64:67]
	v_mfma_f32_16x16x32_bf16 v[64:67], v[222:225], v[0:3], v[210:213]
	v_mfma_f32_16x16x32_bf16 v[68:71], v[226:229], v[4:7], v[64:67]
	v_mfma_f32_16x16x32_bf16 v[64:67], v[222:225], v[194:197], v[214:217]
	v_mfma_f32_16x16x32_bf16 v[64:67], v[226:229], v[198:201], v[64:67]
	s_barrier
; #define LDA(dst, b, h) for (int m = 0; m < 4; ++m) for (int k = 0; k < 2; ++k) \
;     dst[m][k] = *reinterpret_cast<const bf16x8*>((char*)SA(b, h) + lds_byte(wr * 64 + m * 16 + fr, k * 32 + fq * 8))
; #define LDB(dst, b, h) for (int n = 0; n < 2; ++n) for (int k = 0; k < 2; ++k) \
;     dst[n][k] = *reinterpret_cast<const bf16x8*>((char*)SB(b, h) + lds_byte(wc * 32 + n * 16 + fr, k * 32 + fq * 8))
; #define MMA(ai, bj, At, Bt) do { __builtin_amdgcn_s_setprio(1); \
;     for (int m = 0; m < 4; ++m) for (int n = 0; n < 2; ++n) for (int k = 0; k < 2; ++k) \
;       acc[ai][bj][m][n] = __builtin_amdgcn_mfma_f32_16x16x32_bf16(At[m][k], Bt[n][k], acc[ai][bj][m][n], 0, 0, 0); \
;     __builtin_amdgcn_s_setprio(0); } while (0)
; #define WAIT_V(n) asm volatile("s_waitcnt vmcnt(" #n ")" ::: "memory")
; #define WAIT_L(n) asm volatile("s_waitcnt lgkmcnt(" #n ")" ::: "memory")
; #define BAR __builtin_amdgcn_s_barrier()
; template <int EPI> ...
;     ...
;     LDB(B1, 1, 1); WAIT_V(0); BAR; WAIT_L(0); MMA(0, 1, At, B1); BAR;
;     LDA(At, 1, 1); BAR; WAIT_L(0); MMA(1, 0, At, B0); MMA(1, 1, At, B1); BAR; }
;   if (wr == 0) BAR;
	s_setprio 0
	ds_read_b128 v[170:173], v154
	ds_read_b128 v[206:209], v154 offset:1024
	ds_read_b128 v[210:213], v154 offset:2048
	ds_read_b128 v[154:157], v154 offset:3072
	s_waitcnt vmcnt(0)
	s_setprio 1
	s_barrier
	s_waitcnt lgkmcnt(0)
	v_mfma_f32_16x16x32_bf16 v[92:95], v[16:19], v[170:173], v[92:95]
	v_mfma_f32_16x16x32_bf16 v[16:19], v[16:19], v[210:213], v[88:91]
	v_mfma_f32_16x16x32_bf16 v[120:123], v[20:23], v[154:157], v[16:19]
	v_mfma_f32_16x16x32_bf16 v[16:19], v[32:35], v[170:173], v[166:169]
	v_mfma_f32_16x16x32_bf16 v[108:111], v[36:39], v[206:209], v[16:19]
	v_mfma_f32_16x16x32_bf16 v[16:19], v[32:35], v[210:213], v[174:177]
	v_mfma_f32_16x16x32_bf16 v[104:107], v[36:39], v[154:157], v[16:19]
	v_mfma_f32_16x16x32_bf16 v[16:19], v[48:51], v[170:173], v[76:79]
	v_mfma_f32_16x16x32_bf16 v[124:127], v[20:23], v[206:209], v[92:95]
	v_mfma_f32_16x16x32_bf16 v[92:95], v[52:55], v[206:209], v[16:19]
	v_mfma_f32_16x16x32_bf16 v[16:19], v[48:51], v[210:213], v[72:75]
	v_mfma_f32_16x16x32_bf16 v[88:91], v[52:55], v[154:157], v[16:19]
	v_mfma_f32_16x16x32_bf16 v[16:19], v[222:225], v[170:173], v[178:181]
	v_mfma_f32_16x16x32_bf16 v[76:79], v[226:229], v[206:209], v[16:19]
	v_mfma_f32_16x16x32_bf16 v[16:19], v[222:225], v[210:213], v[182:185]
	v_mfma_f32_16x16x32_bf16 v[72:75], v[226:229], v[154:157], v[16:19]
	s_barrier
	s_setprio 0
	ds_read_b128 v[166:169], v153 offset:49152
	ds_read_b128 v[174:177], v153 offset:50176
	ds_read_b128 v[178:181], v152 offset:49152
	ds_read_b128 v[182:185], v152 offset:50176
	ds_read_b128 v[214:217], v151 offset:49152
	ds_read_b128 v[222:225], v151 offset:50176
	ds_read_b128 v[226:229], v150 offset:49152
	ds_read_b128 v[150:153], v150 offset:50176
	s_setprio 1
	s_barrier
	s_waitcnt lgkmcnt(0)
	v_mfma_f32_16x16x32_bf16 v[16:19], v[166:169], v[0:3], v[60:63]
	v_mfma_f32_16x16x32_bf16 v[52:55], v[174:177], v[4:7], v[16:19]
	v_mfma_f32_16x16x32_bf16 v[16:19], v[166:169], v[194:197], v[56:59]
	v_mfma_f32_16x16x32_bf16 v[48:51], v[174:177], v[198:201], v[16:19]
	v_mfma_f32_16x16x32_bf16 v[16:19], v[178:181], v[0:3], v[202:205]
	v_mfma_f32_16x16x32_bf16 v[36:39], v[182:185], v[4:7], v[16:19]
	v_mfma_f32_16x16x32_bf16 v[16:19], v[178:181], v[194:197], v[218:221]
	v_mfma_f32_16x16x32_bf16 v[32:35], v[182:185], v[198:201], v[16:19]
	v_mfma_f32_16x16x32_bf16 v[16:19], v[214:217], v[0:3], v[44:47]
	v_mfma_f32_16x16x32_bf16 v[0:3], v[226:229], v[0:3], v[136:139]
	v_mfma_f32_16x16x32_bf16 v[20:23], v[222:225], v[4:7], v[16:19]
	v_mfma_f32_16x16x32_bf16 v[16:19], v[214:217], v[194:197], v[40:43]
	v_mfma_f32_16x16x32_bf16 v[4:7], v[150:153], v[4:7], v[0:3]
	v_mfma_f32_16x16x32_bf16 v[0:3], v[226:229], v[194:197], v[140:143]
	v_mfma_f32_16x16x32_bf16 v[16:19], v[222:225], v[198:201], v[16:19]
	v_mfma_f32_16x16x32_bf16 v[0:3], v[150:153], v[198:201], v[0:3]
	s_setprio 0
	s_setprio 1
	v_mfma_f32_16x16x32_bf16 v[24:27], v[166:169], v[210:213], v[24:27]
	v_mfma_f32_16x16x32_bf16 v[56:59], v[174:177], v[154:157], v[24:27]
	v_mfma_f32_16x16x32_bf16 v[24:27], v[178:181], v[170:173], v[158:161]
	v_mfma_f32_16x16x32_bf16 v[44:47], v[182:185], v[206:209], v[24:27]
	v_mfma_f32_16x16x32_bf16 v[24:27], v[178:181], v[210:213], v[162:165]
	v_mfma_f32_16x16x32_bf16 v[8:11], v[214:217], v[210:213], v[8:11]
	v_mfma_f32_16x16x32_bf16 v[28:31], v[166:169], v[170:173], v[28:31]
	v_mfma_f32_16x16x32_bf16 v[40:43], v[182:185], v[154:157], v[24:27]
	v_mfma_f32_16x16x32_bf16 v[12:15], v[214:217], v[170:173], v[12:15]
	v_mfma_f32_16x16x32_bf16 v[24:27], v[222:225], v[154:157], v[8:11]
	v_mfma_f32_16x16x32_bf16 v[8:11], v[226:229], v[170:173], v[186:189]
	v_mfma_f32_16x16x32_bf16 v[60:63], v[174:177], v[206:209], v[28:31]
	v_mfma_f32_16x16x32_bf16 v[28:31], v[222:225], v[206:209], v[12:15]
	v_mfma_f32_16x16x32_bf16 v[12:15], v[150:153], v[206:209], v[8:11]
	v_mfma_f32_16x16x32_bf16 v[8:11], v[226:229], v[210:213], v[190:193]
	v_mfma_f32_16x16x32_bf16 v[8:11], v[150:153], v[154:157], v[8:11]
	s_barrier
	s_setprio 0
	v_cmp_gt_u32_e32 vcc, s81, v144
	s_and_saveexec_b64 s[54:55], vcc
	s_cbranch_execz .LBB0_859
	s_barrier

; #define STAGE(P, BASE, kt) do { const char* _g = (const char*)(BASE) + (size_t)((kt) * (BK * 2)); \
;     __builtin_amdgcn_global_load_lds((const unsigned*)(_g + (size_t)goff0), (unsigned*)((char*)(P) + tid_ * 16), 16, 0, 0); \
;     __builtin_amdgcn_global_load_lds((const unsigned*)(_g + (size_t)goff1), (unsigned*)((char*)(P) + tid_ * 16 + 8192), 16, 0, 0); } while (0)
; #define STAGEA(P, BASE, kt) do { const char* _g = (const char*)(BASE) + (size_t)((kt) * a_kbytes); \
;     __builtin_amdgcn_global_load_lds((const unsigned*)(_g + (size_t)goffA0), (unsigned*)((char*)(P) + tid_ * 16), 16, 0, 0); \
;     __builtin_amdgcn_global_load_lds((const unsigned*)(_g + (size_t)goffA1), (unsigned*)((char*)(P) + tid_ * 16 + 8192), 16, 0, 0); } while (0)
; #define LDA(dst, b, h) for (int m = 0; m < 4; ++m) for (int k = 0; k < 2; ++k) \
;     dst[m][k] = *reinterpret_cast<const bf16x8*>((char*)SA(b, h) + lds_byte(wr * 64 + m * 16 + fr, k * 32 + fq * 8))
; #define LDB(dst, b, h) for (int n = 0; n < 2; ++n) for (int k = 0; k < 2; ++k) \
;     dst[n][k] = *reinterpret_cast<const bf16x8*>((char*)SB(b, h) + lds_byte(wc * 32 + n * 16 + fr, k * 32 + fq * 8))
; #define MMA(ai, bj, At, Bt) do { __builtin_amdgcn_s_setprio(1); \
;     for (int m = 0; m < 4; ++m) for (int n = 0; n < 2; ++n) for (int k = 0; k < 2; ++k) \
;       acc[ai][bj][m][n] = __builtin_amdgcn_mfma_f32_16x16x32_bf16(At[m][k], Bt[n][k], acc[ai][bj][m][n], 0, 0, 0); \
;     __builtin_amdgcn_s_setprio(0); } while (0)
; #define WAIT_L(n) asm volatile("s_waitcnt lgkmcnt(" #n ")" ::: "memory")
; #define BAR __builtin_amdgcn_s_barrier()
; #define SCHED __builtin_amdgcn_sched_barrier(0)
; template <int EPI> ...
;     ...
;     LDB(B0, 0, 0); SCHED; LDA(At, 0, 0); STAGEA(SA(1, 1), A1, t + 1);
;     WAIT_L(8); BAR; WAIT_L(0); MMA(0, 0, At, B0); BAR; SCHED;
;     LDB(B1, 0, 1); STAGE(SB(0, 0), B0p, t + 2);
;     BAR; WAIT_L(0); MMA(0, 1, At, B1); BAR;
;     LDA(At, 0, 1); STAGEA(SA(0, 0), A0, t + 2);
;     BAR; WAIT_L(0); MMA(1, 0, At, B0); BAR; SCHED;
.LBB0_1382:
	ds_read_b128 v[174:177], v171
	ds_read_b128 v[178:181], v171 offset:1024
	ds_read_b128 v[182:185], v171 offset:2048
	ds_read_b128 v[186:189], v171 offset:3072
	v_add_u32_e32 v172, 0xc000, v158
	v_lshl_add_u64 v[238:239], s[38:39], 0, v[140:141]
	v_readfirstlane_b32 s40, v172
	v_add_u32_e32 v173, 0xe000, v158
	v_lshl_add_u64 v[222:223], v[238:239], 0, s[4:5]
	s_mov_b32 m0, s40
	v_lshl_add_u64 v[240:241], s[38:39], 0, v[142:143]
	v_readfirstlane_b32 s40, v173
	ds_read_b128 v[190:193], v153
	ds_read_b128 v[194:197], v153 offset:1024
	ds_read_b128 v[198:201], v152
	ds_read_b128 v[202:205], v152 offset:1024
	ds_read_b128 v[206:209], v151
	ds_read_b128 v[210:213], v151 offset:1024
	ds_read_b128 v[214:217], v150
	ds_read_b128 v[218:221], v150 offset:1024
	global_load_lds_dwordx4 v[222:223], off
	v_lshl_add_u64 v[222:223], v[240:241], 0, s[4:5]
	s_mov_b32 m0, s40
	s_nop 0
	global_load_lds_dwordx4 v[222:223], off
	s_waitcnt lgkmcnt(8)
	s_setprio 1
	s_barrier
	s_waitcnt lgkmcnt(0)
	v_mfma_f32_16x16x32_bf16 v[124:127], v[190:193], v[174:177], v[124:127]
	v_mfma_f32_16x16x32_bf16 v[120:123], v[190:193], v[182:185], v[120:123]
	v_mfma_f32_16x16x32_bf16 v[116:119], v[198:201], v[174:177], v[116:119]
	v_mfma_f32_16x16x32_bf16 v[112:115], v[198:201], v[182:185], v[112:115]
	v_mfma_f32_16x16x32_bf16 v[108:111], v[206:209], v[174:177], v[108:111]
	v_mfma_f32_16x16x32_bf16 v[104:107], v[206:209], v[182:185], v[104:107]
	v_mfma_f32_16x16x32_bf16 v[100:103], v[214:217], v[174:177], v[100:103]
	v_mfma_f32_16x16x32_bf16 v[96:99], v[214:217], v[182:185], v[96:99]
	v_mfma_f32_16x16x32_bf16 v[124:127], v[194:197], v[178:181], v[124:127]
	v_mfma_f32_16x16x32_bf16 v[120:123], v[194:197], v[186:189], v[120:123]
	v_mfma_f32_16x16x32_bf16 v[116:119], v[202:205], v[178:181], v[116:119]
	v_mfma_f32_16x16x32_bf16 v[112:115], v[202:205], v[186:189], v[112:115]
	v_mfma_f32_16x16x32_bf16 v[108:111], v[210:213], v[178:181], v[108:111]
	v_mfma_f32_16x16x32_bf16 v[104:107], v[210:213], v[186:189], v[104:107]
	v_mfma_f32_16x16x32_bf16 v[100:103], v[218:221], v[178:181], v[100:103]
	v_mfma_f32_16x16x32_bf16 v[96:99], v[218:221], v[186:189], v[96:99]
	s_barrier
	s_setprio 0
	v_lshl_add_u64 v[242:243], s[38:39], 0, v[136:137]
	v_readfirstlane_b32 s40, v155
	v_lshl_add_u64 v[244:245], v[242:243], 0, s[6:7]
	s_mov_b32 m0, s40
	ds_read_b128 v[222:225], v168
	ds_read_b128 v[226:229], v168 offset:1024
	ds_read_b128 v[230:233], v168 offset:2048
	ds_read_b128 v[234:237], v168 offset:3072
	global_load_lds_dwordx4 v[244:245], off
	v_lshl_add_u64 v[244:245], s[38:39], 0, v[138:139]
	v_readfirstlane_b32 s40, v156
	v_lshl_add_u64 v[246:247], v[244:245], 0, s[6:7]
	s_mov_b32 m0, s40
	s_nop 0
	global_load_lds_dwordx4 v[246:247], off
	s_setprio 1
	s_barrier
	s_waitcnt lgkmcnt(0)
	v_mfma_f32_16x16x32_bf16 v[92:95], v[190:193], v[222:225], v[92:95]
	v_mfma_f32_16x16x32_bf16 v[88:91], v[190:193], v[230:233], v[88:91]
	v_mfma_f32_16x16x32_bf16 v[84:87], v[198:201], v[222:225], v[84:87]
	v_mfma_f32_16x16x32_bf16 v[80:83], v[198:201], v[230:233], v[80:83]
	v_mfma_f32_16x16x32_bf16 v[76:79], v[206:209], v[222:225], v[76:79]
	v_mfma_f32_16x16x32_bf16 v[72:75], v[206:209], v[230:233], v[72:75]
	v_mfma_f32_16x16x32_bf16 v[68:71], v[214:217], v[222:225], v[68:71]
	v_mfma_f32_16x16x32_bf16 v[64:67], v[214:217], v[230:233], v[64:67]
	v_mfma_f32_16x16x32_bf16 v[92:95], v[194:197], v[226:229], v[92:95]
	v_mfma_f32_16x16x32_bf16 v[88:91], v[194:197], v[234:237], v[88:91]
	v_mfma_f32_16x16x32_bf16 v[84:87], v[202:205], v[226:229], v[84:87]
	v_mfma_f32_16x16x32_bf16 v[80:83], v[202:205], v[234:237], v[80:83]
	v_mfma_f32_16x16x32_bf16 v[76:79], v[210:213], v[226:229], v[76:79]
	v_mfma_f32_16x16x32_bf16 v[72:75], v[210:213], v[234:237], v[72:75]
	v_mfma_f32_16x16x32_bf16 v[68:71], v[218:221], v[226:229], v[68:71]
	v_mfma_f32_16x16x32_bf16 v[64:67], v[218:221], v[234:237], v[64:67]
	s_barrier
	s_setprio 0
	v_readfirstlane_b32 s40, v158
	v_lshl_add_u64 v[246:247], v[238:239], 0, s[8:9]
	s_mov_b32 m0, s40
	v_readfirstlane_b32 s40, v159
	ds_read_b128 v[190:193], v153 offset:16384
	ds_read_b128 v[194:197], v153 offset:17408
	ds_read_b128 v[198:201], v152 offset:16384
	ds_read_b128 v[202:205], v152 offset:17408
	ds_read_b128 v[206:209], v151 offset:16384
	ds_read_b128 v[210:213], v151 offset:17408
	ds_read_b128 v[214:217], v150 offset:16384
	ds_read_b128 v[218:221], v150 offset:17408
	global_load_lds_dwordx4 v[246:247], off
	v_lshl_add_u64 v[246:247], v[240:241], 0, s[8:9]
	s_mov_b32 m0, s40
	s_nop 0
	global_load_lds_dwordx4 v[246:247], off
	s_setprio 1
	s_barrier
	s_waitcnt lgkmcnt(0)
	v_mfma_f32_16x16x32_bf16 v[60:63], v[190:193], v[174:177], v[60:63]
	v_mfma_f32_16x16x32_bf16 v[56:59], v[190:193], v[182:185], v[56:59]
	v_mfma_f32_16x16x32_bf16 v[52:55], v[198:201], v[174:177], v[52:55]
	v_mfma_f32_16x16x32_bf16 v[48:51], v[198:201], v[182:185], v[48:51]
	v_mfma_f32_16x16x32_bf16 v[44:47], v[206:209], v[174:177], v[44:47]
	v_mfma_f32_16x16x32_bf16 v[40:43], v[206:209], v[182:185], v[40:43]
	v_mfma_f32_16x16x32_bf16 v[36:39], v[214:217], v[174:177], v[36:39]
	v_mfma_f32_16x16x32_bf16 v[32:35], v[214:217], v[182:185], v[32:35]
	v_mfma_f32_16x16x32_bf16 v[60:63], v[194:197], v[178:181], v[60:63]
	v_mfma_f32_16x16x32_bf16 v[56:59], v[194:197], v[186:189], v[56:59]
	v_mfma_f32_16x16x32_bf16 v[52:55], v[202:205], v[178:181], v[52:55]
	v_mfma_f32_16x16x32_bf16 v[48:51], v[202:205], v[186:189], v[48:51]
	v_mfma_f32_16x16x32_bf16 v[44:47], v[210:213], v[178:181], v[44:47]
	v_mfma_f32_16x16x32_bf16 v[40:43], v[210:213], v[186:189], v[40:43]
	v_mfma_f32_16x16x32_bf16 v[36:39], v[218:221], v[178:181], v[36:39]
	v_mfma_f32_16x16x32_bf16 v[32:35], v[218:221], v[186:189], v[32:35]
	s_barrier
; #define STAGE(P, BASE, kt) do { const char* _g = (const char*)(BASE) + (size_t)((kt) * (BK * 2)); \
;     __builtin_amdgcn_global_load_lds((const unsigned*)(_g + (size_t)goff0), (unsigned*)((char*)(P) + tid_ * 16), 16, 0, 0); \
;     __builtin_amdgcn_global_load_lds((const unsigned*)(_g + (size_t)goff1), (unsigned*)((char*)(P) + tid_ * 16 + 8192), 16, 0, 0); } while (0)
; #define STAGEA(P, BASE, kt) do { const char* _g = (const char*)(BASE) + (size_t)((kt) * a_kbytes); \
;     __builtin_amdgcn_global_load_lds((const unsigned*)(_g + (size_t)goffA0), (unsigned*)((char*)(P) + tid_ * 16), 16, 0, 0); \
;     __builtin_amdgcn_global_load_lds((const unsigned*)(_g + (size_t)goffA1), (unsigned*)((char*)(P) + tid_ * 16 + 8192), 16, 0, 0); } while (0)
; #define LDA(dst, b, h) for (int m = 0; m < 4; ++m) for (int k = 0; k < 2; ++k) \
;     dst[m][k] = *reinterpret_cast<const bf16x8*>((char*)SA(b, h) + lds_byte(wr * 64 + m * 16 + fr, k * 32 + fq * 8))
; #define LDB(dst, b, h) for (int n = 0; n < 2; ++n) for (int k = 0; k < 2; ++k) \
;     dst[n][k] = *reinterpret_cast<const bf16x8*>((char*)SB(b, h) + lds_byte(wc * 32 + n * 16 + fr, k * 32 + fq * 8))
; #define MMA(ai, bj, At, Bt) do { __builtin_amdgcn_s_setprio(1); \
;     for (int m = 0; m < 4; ++m) for (int n = 0; n < 2; ++n) for (int k = 0; k < 2; ++k) \
;       acc[ai][bj][m][n] = __builtin_amdgcn_mfma_f32_16x16x32_bf16(At[m][k], Bt[n][k], acc[ai][bj][m][n], 0, 0, 0); \
;     __builtin_amdgcn_s_setprio(0); } while (0)
; #define WAIT_V(n) asm volatile("s_waitcnt vmcnt(" #n ")" ::: "memory")
; #define WAIT_L(n) asm volatile("s_waitcnt lgkmcnt(" #n ")" ::: "memory")
; #define BAR __builtin_amdgcn_s_barrier()
; #define SCHED __builtin_amdgcn_sched_barrier(0)
; template <int EPI> ...
;     ...
;     STAGE(SB(0, 1), B1p, t + 2);
;     WAIT_V(6); BAR; MMA(1, 1, At, B1); BAR;
;     LDB(B0, 1, 0); SCHED; LDA(At, 1, 0); STAGEA(SA(0, 1), A1, t + 2);
;     WAIT_L(8); BAR; WAIT_L(0); MMA(0, 0, At, B0); BAR; SCHED;
;     LDB(B1, 1, 1); STAGE(SB(1, 0), B0p, t + 3);
;     BAR; WAIT_L(0); MMA(0, 1, At, B1); BAR;
;     LDA(At, 1, 1); STAGEA(SA(1, 0), A0, t + 3);
	s_setprio 0
	v_readfirstlane_b32 s40, v160
	v_lshl_add_u64 v[174:175], v[242:243], 0, s[10:11]
	s_mov_b32 m0, s40
	v_readfirstlane_b32 s40, v161
	global_load_lds_dwordx4 v[174:175], off
	v_lshl_add_u64 v[174:175], v[244:245], 0, s[10:11]
	s_mov_b32 m0, s40
	s_nop 0
	global_load_lds_dwordx4 v[174:175], off
	s_waitcnt vmcnt(6)
	s_setprio 1
	s_barrier
	v_mfma_f32_16x16x32_bf16 v[28:31], v[190:193], v[222:225], v[28:31]
	v_mfma_f32_16x16x32_bf16 v[24:27], v[190:193], v[230:233], v[24:27]
	v_mfma_f32_16x16x32_bf16 v[20:23], v[198:201], v[222:225], v[20:23]
	v_mfma_f32_16x16x32_bf16 v[16:19], v[198:201], v[230:233], v[16:19]
	v_mfma_f32_16x16x32_bf16 v[12:15], v[206:209], v[222:225], v[12:15]
	v_mfma_f32_16x16x32_bf16 v[8:11], v[206:209], v[230:233], v[8:11]
	v_mfma_f32_16x16x32_bf16 v[4:7], v[214:217], v[222:225], v[4:7]
	v_mfma_f32_16x16x32_bf16 v[0:3], v[214:217], v[230:233], v[0:3]
	v_mfma_f32_16x16x32_bf16 v[28:31], v[194:197], v[226:229], v[28:31]
	v_mfma_f32_16x16x32_bf16 v[24:27], v[194:197], v[234:237], v[24:27]
	v_mfma_f32_16x16x32_bf16 v[20:23], v[202:205], v[226:229], v[20:23]
	v_mfma_f32_16x16x32_bf16 v[16:19], v[202:205], v[234:237], v[16:19]
	v_mfma_f32_16x16x32_bf16 v[12:15], v[210:213], v[226:229], v[12:15]
	v_mfma_f32_16x16x32_bf16 v[8:11], v[210:213], v[234:237], v[8:11]
	v_mfma_f32_16x16x32_bf16 v[4:7], v[218:221], v[226:229], v[4:7]
	v_mfma_f32_16x16x32_bf16 v[0:3], v[218:221], v[234:237], v[0:3]
	s_barrier
	s_setprio 0
	ds_read_b128 v[174:177], v157
	ds_read_b128 v[178:181], v157 offset:1024
	ds_read_b128 v[182:185], v157 offset:2048
	ds_read_b128 v[186:189], v157 offset:3072
	v_readfirstlane_b32 s40, v162
	v_lshl_add_u64 v[222:223], v[238:239], 0, s[12:13]
	s_mov_b32 m0, s40
	v_readfirstlane_b32 s40, v163
	ds_read_b128 v[190:193], v153 offset:32768
	ds_read_b128 v[194:197], v153 offset:33792
	ds_read_b128 v[198:201], v152 offset:32768
	ds_read_b128 v[202:205], v152 offset:33792
	ds_read_b128 v[206:209], v151 offset:32768
	ds_read_b128 v[210:213], v151 offset:33792
	ds_read_b128 v[214:217], v150 offset:32768
	ds_read_b128 v[218:221], v150 offset:33792
	global_load_lds_dwordx4 v[222:223], off
	v_lshl_add_u64 v[222:223], v[240:241], 0, s[12:13]
	s_mov_b32 m0, s40
	s_nop 0
	global_load_lds_dwordx4 v[222:223], off
	s_waitcnt lgkmcnt(8)
	s_setprio 1
	s_barrier
	s_waitcnt lgkmcnt(0)
	v_mfma_f32_16x16x32_bf16 v[124:127], v[190:193], v[174:177], v[124:127]
	v_mfma_f32_16x16x32_bf16 v[120:123], v[190:193], v[182:185], v[120:123]
	v_mfma_f32_16x16x32_bf16 v[116:119], v[198:201], v[174:177], v[116:119]
	v_mfma_f32_16x16x32_bf16 v[112:115], v[198:201], v[182:185], v[112:115]
	v_mfma_f32_16x16x32_bf16 v[108:111], v[206:209], v[174:177], v[108:111]
	v_mfma_f32_16x16x32_bf16 v[104:107], v[206:209], v[182:185], v[104:107]
	v_mfma_f32_16x16x32_bf16 v[100:103], v[214:217], v[174:177], v[100:103]
	v_mfma_f32_16x16x32_bf16 v[96:99], v[214:217], v[182:185], v[96:99]
	v_mfma_f32_16x16x32_bf16 v[124:127], v[194:197], v[178:181], v[124:127]
	v_mfma_f32_16x16x32_bf16 v[120:123], v[194:197], v[186:189], v[120:123]
	v_mfma_f32_16x16x32_bf16 v[116:119], v[202:205], v[178:181], v[116:119]
	v_mfma_f32_16x16x32_bf16 v[112:115], v[202:205], v[186:189], v[112:115]
	v_mfma_f32_16x16x32_bf16 v[108:111], v[210:213], v[178:181], v[108:111]
	v_mfma_f32_16x16x32_bf16 v[104:107], v[210:213], v[186:189], v[104:107]
	v_mfma_f32_16x16x32_bf16 v[100:103], v[218:221], v[178:181], v[100:103]
	v_mfma_f32_16x16x32_bf16 v[96:99], v[218:221], v[186:189], v[96:99]
	s_barrier
	s_setprio 0
	v_readfirstlane_b32 s40, v164
	v_lshl_add_u64 v[246:247], v[242:243], 0, s[14:15]
	s_mov_b32 m0, s40
	v_readfirstlane_b32 s40, v165
	ds_read_b128 v[222:225], v154
	ds_read_b128 v[226:229], v154 offset:1024
	ds_read_b128 v[230:233], v154 offset:2048
	ds_read_b128 v[234:237], v154 offset:3072
	global_load_lds_dwordx4 v[246:247], off
	v_lshl_add_u64 v[246:247], v[244:245], 0, s[14:15]
	s_mov_b32 m0, s40
	s_nop 0
	global_load_lds_dwordx4 v[246:247], off
	s_setprio 1
	s_barrier
	s_waitcnt lgkmcnt(0)
	v_mfma_f32_16x16x32_bf16 v[92:95], v[190:193], v[222:225], v[92:95]
	v_mfma_f32_16x16x32_bf16 v[88:91], v[190:193], v[230:233], v[88:91]
	v_mfma_f32_16x16x32_bf16 v[84:87], v[198:201], v[222:225], v[84:87]
	v_mfma_f32_16x16x32_bf16 v[80:83], v[198:201], v[230:233], v[80:83]
	v_mfma_f32_16x16x32_bf16 v[76:79], v[206:209], v[222:225], v[76:79]
	v_mfma_f32_16x16x32_bf16 v[72:75], v[206:209], v[230:233], v[72:75]
	v_mfma_f32_16x16x32_bf16 v[68:71], v[214:217], v[222:225], v[68:71]
	v_mfma_f32_16x16x32_bf16 v[64:67], v[214:217], v[230:233], v[64:67]
	v_mfma_f32_16x16x32_bf16 v[92:95], v[194:197], v[226:229], v[92:95]
	v_mfma_f32_16x16x32_bf16 v[88:91], v[194:197], v[234:237], v[88:91]
	v_mfma_f32_16x16x32_bf16 v[84:87], v[202:205], v[226:229], v[84:87]
	v_mfma_f32_16x16x32_bf16 v[80:83], v[202:205], v[234:237], v[80:83]
	v_mfma_f32_16x16x32_bf16 v[76:79], v[210:213], v[226:229], v[76:79]
	v_mfma_f32_16x16x32_bf16 v[72:75], v[210:213], v[234:237], v[72:75]
	v_mfma_f32_16x16x32_bf16 v[68:71], v[218:221], v[226:229], v[68:71]
	v_mfma_f32_16x16x32_bf16 v[64:67], v[218:221], v[234:237], v[64:67]
	s_barrier
	s_setprio 0
	v_readfirstlane_b32 s40, v166
	v_lshl_add_u64 v[238:239], v[238:239], 0, s[16:17]
	s_mov_b32 m0, s40
	v_readfirstlane_b32 s40, v167
	ds_read_b128 v[190:193], v153 offset:49152
	ds_read_b128 v[194:197], v153 offset:50176
	ds_read_b128 v[198:201], v152 offset:49152
	ds_read_b128 v[202:205], v152 offset:50176
	ds_read_b128 v[206:209], v151 offset:49152
	ds_read_b128 v[210:213], v151 offset:50176
	ds_read_b128 v[214:217], v150 offset:49152
	ds_read_b128 v[218:221], v150 offset:50176
	global_load_lds_dwordx4 v[238:239], off
	v_lshl_add_u64 v[238:239], v[240:241], 0, s[16:17]
	s_mov_b32 m0, s40
	s_nop 0
	global_load_lds_dwordx4 v[238:239], off
	s_setprio 1
	s_barrier
; #define STAGE(P, BASE, kt) do { const char* _g = (const char*)(BASE) + (size_t)((kt) * (BK * 2)); \
;     __builtin_amdgcn_global_load_lds((const unsigned*)(_g + (size_t)goff0), (unsigned*)((char*)(P) + tid_ * 16), 16, 0, 0); \
;     __builtin_amdgcn_global_load_lds((const unsigned*)(_g + (size_t)goff1), (unsigned*)((char*)(P) + tid_ * 16 + 8192), 16, 0, 0); } while (0)
; #define STAGEA(P, BASE, kt) do { const char* _g = (const char*)(BASE) + (size_t)((kt) * a_kbytes); \
;     __builtin_amdgcn_global_load_lds((const unsigned*)(_g + (size_t)goffA0), (unsigned*)((char*)(P) + tid_ * 16), 16, 0, 0); \
;     __builtin_amdgcn_global_load_lds((const unsigned*)(_g + (size_t)goffA1), (unsigned*)((char*)(P) + tid_ * 16 + 8192), 16, 0, 0); } while (0)
; #define LDA(dst, b, h) for (int m = 0; m < 4; ++m) for (int k = 0; k < 2; ++k) \
;     dst[m][k] = *reinterpret_cast<const bf16x8*>((char*)SA(b, h) + lds_byte(wr * 64 + m * 16 + fr, k * 32 + fq * 8))
; #define LDB(dst, b, h) for (int n = 0; n < 2; ++n) for (int k = 0; k < 2; ++k) \
;     dst[n][k] = *reinterpret_cast<const bf16x8*>((char*)SB(b, h) + lds_byte(wc * 32 + n * 16 + fr, k * 32 + fq * 8))
; #define MMA(ai, bj, At, Bt) do { __builtin_amdgcn_s_setprio(1); \
;     for (int m = 0; m < 4; ++m) for (int n = 0; n < 2; ++n) for (int k = 0; k < 2; ++k) \
;       acc[ai][bj][m][n] = __builtin_amdgcn_mfma_f32_16x16x32_bf16(At[m][k], Bt[n][k], acc[ai][bj][m][n], 0, 0, 0); \
;     __builtin_amdgcn_s_setprio(0); } while (0)
; #define WAIT_V(n) asm volatile("s_waitcnt vmcnt(" #n ")" ::: "memory")
; #define WAIT_L(n) asm volatile("s_waitcnt lgkmcnt(" #n ")" ::: "memory")
; #define BAR __builtin_amdgcn_s_barrier()
; #define SCHED __builtin_amdgcn_sched_barrier(0)
; template <int EPI> ...
;     ...
;     BAR; WAIT_L(0); MMA(1, 0, At, B0); BAR; SCHED;
;     STAGE(SB(1, 1), B1p, t + 3);
;     WAIT_V(6); BAR; MMA(1, 1, At, B1); BAR;
;   }
;   { LDB(B0, 0, 0); LDA(At, 0, 0); STAGEA(SA(1, 1), A1, nt - 1);
;     BAR; WAIT_L(0); MMA(0, 0, At, B0); BAR;
;     LDB(B1, 0, 1); BAR; WAIT_L(0); MMA(0, 1, At, B1); BAR;
	s_waitcnt lgkmcnt(0)
	v_mfma_f32_16x16x32_bf16 v[60:63], v[190:193], v[174:177], v[60:63]
	v_mfma_f32_16x16x32_bf16 v[56:59], v[190:193], v[182:185], v[56:59]
	v_mfma_f32_16x16x32_bf16 v[52:55], v[198:201], v[174:177], v[52:55]
	v_mfma_f32_16x16x32_bf16 v[48:51], v[198:201], v[182:185], v[48:51]
	v_mfma_f32_16x16x32_bf16 v[44:47], v[206:209], v[174:177], v[44:47]
	v_mfma_f32_16x16x32_bf16 v[40:43], v[206:209], v[182:185], v[40:43]
	v_mfma_f32_16x16x32_bf16 v[36:39], v[214:217], v[174:177], v[36:39]
	v_mfma_f32_16x16x32_bf16 v[32:35], v[214:217], v[182:185], v[32:35]
	v_mfma_f32_16x16x32_bf16 v[60:63], v[194:197], v[178:181], v[60:63]
	v_mfma_f32_16x16x32_bf16 v[56:59], v[194:197], v[186:189], v[56:59]
	v_mfma_f32_16x16x32_bf16 v[52:55], v[202:205], v[178:181], v[52:55]
	v_mfma_f32_16x16x32_bf16 v[48:51], v[202:205], v[186:189], v[48:51]
	v_mfma_f32_16x16x32_bf16 v[44:47], v[210:213], v[178:181], v[44:47]
	v_mfma_f32_16x16x32_bf16 v[40:43], v[210:213], v[186:189], v[40:43]
	v_mfma_f32_16x16x32_bf16 v[36:39], v[218:221], v[178:181], v[36:39]
	v_mfma_f32_16x16x32_bf16 v[32:35], v[218:221], v[186:189], v[32:35]
	s_barrier
	s_setprio 0
	v_readfirstlane_b32 s40, v169
	v_lshl_add_u64 v[174:175], v[242:243], 0, s[18:19]
	s_mov_b32 m0, s40
	v_readfirstlane_b32 s40, v170
	global_load_lds_dwordx4 v[174:175], off
	v_lshl_add_u64 v[174:175], v[244:245], 0, s[18:19]
	s_mov_b32 m0, s40
	s_nop 0
	global_load_lds_dwordx4 v[174:175], off
	s_waitcnt vmcnt(6)
	s_setprio 1
	s_barrier
	v_mfma_f32_16x16x32_bf16 v[28:31], v[190:193], v[222:225], v[28:31]
	v_mfma_f32_16x16x32_bf16 v[24:27], v[190:193], v[230:233], v[24:27]
	v_mfma_f32_16x16x32_bf16 v[20:23], v[198:201], v[222:225], v[20:23]
	v_mfma_f32_16x16x32_bf16 v[16:19], v[198:201], v[230:233], v[16:19]
	v_mfma_f32_16x16x32_bf16 v[12:15], v[206:209], v[222:225], v[12:15]
	v_mfma_f32_16x16x32_bf16 v[8:11], v[206:209], v[230:233], v[8:11]
	v_mfma_f32_16x16x32_bf16 v[4:7], v[214:217], v[222:225], v[4:7]
	v_mfma_f32_16x16x32_bf16 v[0:3], v[214:217], v[230:233], v[0:3]
	v_mfma_f32_16x16x32_bf16 v[28:31], v[194:197], v[226:229], v[28:31]
	v_mfma_f32_16x16x32_bf16 v[24:27], v[194:197], v[234:237], v[24:27]
	v_mfma_f32_16x16x32_bf16 v[20:23], v[202:205], v[226:229], v[20:23]
	v_mfma_f32_16x16x32_bf16 v[16:19], v[202:205], v[234:237], v[16:19]
	v_mfma_f32_16x16x32_bf16 v[12:15], v[210:213], v[226:229], v[12:15]
	v_mfma_f32_16x16x32_bf16 v[8:11], v[210:213], v[234:237], v[8:11]
	v_mfma_f32_16x16x32_bf16 v[4:7], v[218:221], v[226:229], v[4:7]
	v_mfma_f32_16x16x32_bf16 v[0:3], v[218:221], v[234:237], v[0:3]
	s_barrier
	s_setprio 0
	s_add_i32 s23, s23, 2
	s_add_u32 s38, s38, 0x100
	s_addc_u32 s39, s39, 0
	s_cmp_lt_u32 s23, 28
	s_cbranch_scc1 .LBB0_1382
	s_add_u32 s36, s36, 0x80f80
	s_addc_u32 s37, s37, 0
	v_readfirstlane_b32 s23, v172
	v_lshl_add_u64 v[166:167], s[36:37], 0, v[130:131]
	s_mov_b32 m0, s23
	v_readfirstlane_b32 s23, v173
	ds_read_b128 v[136:139], v171
	ds_read_b128 v[140:143], v171 offset:1024
	ds_read_b128 v[158:161], v171 offset:2048
	ds_read_b128 v[162:165], v171 offset:3072
	ds_read_b128 v[174:177], v153
	ds_read_b128 v[178:181], v153 offset:1024
	ds_read_b128 v[182:185], v152
	ds_read_b128 v[186:189], v152 offset:1024
	ds_read_b128 v[190:193], v151
	ds_read_b128 v[194:197], v151 offset:1024
	ds_read_b128 v[198:201], v150
	ds_read_b128 v[202:205], v150 offset:1024
	global_load_lds_dwordx4 v[166:167], off
	v_lshl_add_u64 v[166:167], s[36:37], 0, v[128:129]
	s_mov_b32 m0, s23
	s_nop 0
	global_load_lds_dwordx4 v[166:167], off
	s_setprio 1
	s_barrier
	s_waitcnt lgkmcnt(0)
	v_mfma_f32_16x16x32_bf16 v[124:127], v[174:177], v[136:139], v[124:127]
	v_mfma_f32_16x16x32_bf16 v[120:123], v[174:177], v[158:161], v[120:123]
	v_mfma_f32_16x16x32_bf16 v[108:111], v[190:193], v[136:139], v[108:111]
	v_mfma_f32_16x16x32_bf16 v[104:107], v[190:193], v[158:161], v[104:107]
	v_mfma_f32_16x16x32_bf16 v[124:127], v[178:181], v[140:143], v[124:127]
	v_mfma_f32_16x16x32_bf16 v[120:123], v[178:181], v[162:165], v[120:123]
	v_mfma_f32_16x16x32_bf16 v[116:119], v[182:185], v[136:139], v[116:119]
	v_mfma_f32_16x16x32_bf16 v[112:115], v[182:185], v[158:161], v[112:115]
	v_mfma_f32_16x16x32_bf16 v[108:111], v[194:197], v[140:143], v[108:111]
	v_mfma_f32_16x16x32_bf16 v[104:107], v[194:197], v[162:165], v[104:107]
	v_mfma_f32_16x16x32_bf16 v[100:103], v[198:201], v[136:139], v[100:103]
	v_mfma_f32_16x16x32_bf16 v[96:99], v[198:201], v[158:161], v[96:99]
	v_mfma_f32_16x16x32_bf16 v[170:173], v[186:189], v[140:143], v[116:119]
	v_mfma_f32_16x16x32_bf16 v[206:209], v[186:189], v[162:165], v[112:115]
	v_mfma_f32_16x16x32_bf16 v[210:213], v[202:205], v[140:143], v[100:103]
	v_mfma_f32_16x16x32_bf16 v[214:217], v[202:205], v[162:165], v[96:99]
	s_barrier
	s_setprio 0
	s_nop 1
	ds_read_b128 v[96:99], v168
	ds_read_b128 v[100:103], v168 offset:1024
	ds_read_b128 v[112:115], v168 offset:2048
	ds_read_b128 v[116:119], v168 offset:3072
	s_setprio 1
	s_barrier
	s_waitcnt lgkmcnt(0)
	v_mfma_f32_16x16x32_bf16 v[92:95], v[174:177], v[96:99], v[92:95]
	v_mfma_f32_16x16x32_bf16 v[88:91], v[174:177], v[112:115], v[88:91]
	v_mfma_f32_16x16x32_bf16 v[76:79], v[190:193], v[96:99], v[76:79]
	v_mfma_f32_16x16x32_bf16 v[72:75], v[190:193], v[112:115], v[72:75]
	v_mfma_f32_16x16x32_bf16 v[92:95], v[178:181], v[100:103], v[92:95]
	v_mfma_f32_16x16x32_bf16 v[88:91], v[178:181], v[116:119], v[88:91]
	v_mfma_f32_16x16x32_bf16 v[84:87], v[182:185], v[96:99], v[84:87]
	v_mfma_f32_16x16x32_bf16 v[80:83], v[182:185], v[112:115], v[80:83]
	v_mfma_f32_16x16x32_bf16 v[76:79], v[194:197], v[100:103], v[76:79]
	v_mfma_f32_16x16x32_bf16 v[72:75], v[194:197], v[116:119], v[72:75]
	v_mfma_f32_16x16x32_bf16 v[68:71], v[198:201], v[96:99], v[68:71]
	v_mfma_f32_16x16x32_bf16 v[64:67], v[198:201], v[112:115], v[64:67]
	v_mfma_f32_16x16x32_bf16 v[166:169], v[186:189], v[100:103], v[84:87]
	v_mfma_f32_16x16x32_bf16 v[174:177], v[186:189], v[116:119], v[80:83]
	v_mfma_f32_16x16x32_bf16 v[178:181], v[202:205], v[100:103], v[68:71]
	v_mfma_f32_16x16x32_bf16 v[182:185], v[202:205], v[116:119], v[64:67]
	s_barrier
; #define LDA(dst, b, h) for (int m = 0; m < 4; ++m) for (int k = 0; k < 2; ++k) \
;     dst[m][k] = *reinterpret_cast<const bf16x8*>((char*)SA(b, h) + lds_byte(wr * 64 + m * 16 + fr, k * 32 + fq * 8))
; #define LDB(dst, b, h) for (int n = 0; n < 2; ++n) for (int k = 0; k < 2; ++k) \
;     dst[n][k] = *reinterpret_cast<const bf16x8*>((char*)SB(b, h) + lds_byte(wc * 32 + n * 16 + fr, k * 32 + fq * 8))
; #define MMA(ai, bj, At, Bt) do { __builtin_amdgcn_s_setprio(1); \
;     for (int m = 0; m < 4; ++m) for (int n = 0; n < 2; ++n) for (int k = 0; k < 2; ++k) \
;       acc[ai][bj][m][n] = __builtin_amdgcn_mfma_f32_16x16x32_bf16(At[m][k], Bt[n][k], acc[ai][bj][m][n], 0, 0, 0); \
;     __builtin_amdgcn_s_setprio(0); } while (0)
; #define WAIT_V(n) asm volatile("s_waitcnt vmcnt(" #n ")" ::: "memory")
; #define WAIT_L(n) asm volatile("s_waitcnt lgkmcnt(" #n ")" ::: "memory")
; #define BAR __builtin_amdgcn_s_barrier()
; template <int EPI> ...
;     ...
;     LDA(At, 0, 1); WAIT_V(4); BAR; WAIT_L(0); MMA(1, 0, At, B0); MMA(1, 1, At, B1); BAR; }
;   { LDB(B0, 1, 0); LDA(At, 1, 0); WAIT_V(2); BAR; WAIT_L(0); MMA(0, 0, At, B0); BAR;
	s_setprio 0
	s_nop 1
	ds_read_b128 v[64:67], v153 offset:16384
	ds_read_b128 v[68:71], v153 offset:17408
	ds_read_b128 v[80:83], v152 offset:16384
	ds_read_b128 v[84:87], v152 offset:17408
	ds_read_b128 v[186:189], v151 offset:16384
	ds_read_b128 v[190:193], v151 offset:17408
	ds_read_b128 v[194:197], v150 offset:16384
	ds_read_b128 v[198:201], v150 offset:17408
	s_waitcnt vmcnt(4)
	s_setprio 1
	s_barrier
	s_waitcnt lgkmcnt(0)
	v_mfma_f32_16x16x32_bf16 v[60:63], v[64:67], v[136:139], v[60:63]
	v_mfma_f32_16x16x32_bf16 v[56:59], v[64:67], v[158:161], v[56:59]
	v_mfma_f32_16x16x32_bf16 v[44:47], v[186:189], v[136:139], v[44:47]
	v_mfma_f32_16x16x32_bf16 v[40:43], v[186:189], v[158:161], v[40:43]
	v_mfma_f32_16x16x32_bf16 v[60:63], v[68:71], v[140:143], v[60:63]
	v_mfma_f32_16x16x32_bf16 v[56:59], v[68:71], v[162:165], v[56:59]
	v_mfma_f32_16x16x32_bf16 v[52:55], v[80:83], v[136:139], v[52:55]
	v_mfma_f32_16x16x32_bf16 v[48:51], v[80:83], v[158:161], v[48:51]
	v_mfma_f32_16x16x32_bf16 v[44:47], v[190:193], v[140:143], v[44:47]
	v_mfma_f32_16x16x32_bf16 v[40:43], v[190:193], v[162:165], v[40:43]
	v_mfma_f32_16x16x32_bf16 v[36:39], v[194:197], v[136:139], v[36:39]
	v_mfma_f32_16x16x32_bf16 v[32:35], v[194:197], v[158:161], v[32:35]
	v_mfma_f32_16x16x32_bf16 v[202:205], v[84:87], v[140:143], v[52:55]
	v_mfma_f32_16x16x32_bf16 v[218:221], v[84:87], v[162:165], v[48:51]
	v_mfma_f32_16x16x32_bf16 v[136:139], v[198:201], v[140:143], v[36:39]
	v_mfma_f32_16x16x32_bf16 v[140:143], v[198:201], v[162:165], v[32:35]
	s_setprio 0
	s_setprio 1
	v_mfma_f32_16x16x32_bf16 v[28:31], v[64:67], v[96:99], v[28:31]
	v_mfma_f32_16x16x32_bf16 v[24:27], v[64:67], v[112:115], v[24:27]
	v_mfma_f32_16x16x32_bf16 v[12:15], v[186:189], v[96:99], v[12:15]
	v_mfma_f32_16x16x32_bf16 v[8:11], v[186:189], v[112:115], v[8:11]
	v_mfma_f32_16x16x32_bf16 v[28:31], v[68:71], v[100:103], v[28:31]
	v_mfma_f32_16x16x32_bf16 v[24:27], v[68:71], v[116:119], v[24:27]
	v_mfma_f32_16x16x32_bf16 v[20:23], v[80:83], v[96:99], v[20:23]
	v_mfma_f32_16x16x32_bf16 v[16:19], v[80:83], v[112:115], v[16:19]
	v_mfma_f32_16x16x32_bf16 v[12:15], v[190:193], v[100:103], v[12:15]
	v_mfma_f32_16x16x32_bf16 v[8:11], v[190:193], v[116:119], v[8:11]
	v_mfma_f32_16x16x32_bf16 v[4:7], v[194:197], v[96:99], v[4:7]
	v_mfma_f32_16x16x32_bf16 v[0:3], v[194:197], v[112:115], v[0:3]
	v_mfma_f32_16x16x32_bf16 v[158:161], v[84:87], v[100:103], v[20:23]
	v_mfma_f32_16x16x32_bf16 v[162:165], v[84:87], v[116:119], v[16:19]
	v_mfma_f32_16x16x32_bf16 v[186:189], v[198:201], v[100:103], v[4:7]
	v_mfma_f32_16x16x32_bf16 v[190:193], v[198:201], v[116:119], v[0:3]
	s_barrier
	s_setprio 0
	s_nop 1
	ds_read_b128 v[0:3], v157
	ds_read_b128 v[4:7], v157 offset:1024
	ds_read_b128 v[194:197], v157 offset:2048
	ds_read_b128 v[198:201], v157 offset:3072
	ds_read_b128 v[16:19], v153 offset:32768
	ds_read_b128 v[20:23], v153 offset:33792
	ds_read_b128 v[32:35], v152 offset:32768
	ds_read_b128 v[36:39], v152 offset:33792
	ds_read_b128 v[48:51], v151 offset:32768
	ds_read_b128 v[52:55], v151 offset:33792
	ds_read_b128 v[222:225], v150 offset:32768
	ds_read_b128 v[226:229], v150 offset:33792
	s_waitcnt vmcnt(2)
	s_setprio 1
	s_barrier
	s_waitcnt lgkmcnt(0)
	v_mfma_f32_16x16x32_bf16 v[64:67], v[16:19], v[0:3], v[124:127]
	v_mfma_f32_16x16x32_bf16 v[116:119], v[20:23], v[4:7], v[64:67]
	v_mfma_f32_16x16x32_bf16 v[64:67], v[16:19], v[194:197], v[120:123]
	v_mfma_f32_16x16x32_bf16 v[112:115], v[20:23], v[198:201], v[64:67]
	v_mfma_f32_16x16x32_bf16 v[64:67], v[32:35], v[0:3], v[170:173]
	v_mfma_f32_16x16x32_bf16 v[100:103], v[36:39], v[4:7], v[64:67]
	v_mfma_f32_16x16x32_bf16 v[64:67], v[32:35], v[194:197], v[206:209]
	v_mfma_f32_16x16x32_bf16 v[96:99], v[36:39], v[198:201], v[64:67]
	v_mfma_f32_16x16x32_bf16 v[64:67], v[48:51], v[0:3], v[108:111]
	v_mfma_f32_16x16x32_bf16 v[84:87], v[52:55], v[4:7], v[64:67]
	v_mfma_f32_16x16x32_bf16 v[64:67], v[48:51], v[194:197], v[104:107]
	v_mfma_f32_16x16x32_bf16 v[80:83], v[52:55], v[198:201], v[64:67]
	v_mfma_f32_16x16x32_bf16 v[64:67], v[222:225], v[0:3], v[210:213]
	v_mfma_f32_16x16x32_bf16 v[68:71], v[226:229], v[4:7], v[64:67]
	v_mfma_f32_16x16x32_bf16 v[64:67], v[222:225], v[194:197], v[214:217]
	v_mfma_f32_16x16x32_bf16 v[64:67], v[226:229], v[198:201], v[64:67]
	s_barrier
; #define LDA(dst, b, h) for (int m = 0; m < 4; ++m) for (int k = 0; k < 2; ++k) \
;     dst[m][k] = *reinterpret_cast<const bf16x8*>((char*)SA(b, h) + lds_byte(wr * 64 + m * 16 + fr, k * 32 + fq * 8))
; #define LDB(dst, b, h) for (int n = 0; n < 2; ++n) for (int k = 0; k < 2; ++k) \
;     dst[n][k] = *reinterpret_cast<const bf16x8*>((char*)SB(b, h) + lds_byte(wc * 32 + n * 16 + fr, k * 32 + fq * 8))
; #define MMA(ai, bj, At, Bt) do { __builtin_amdgcn_s_setprio(1); \
;     for (int m = 0; m < 4; ++m) for (int n = 0; n < 2; ++n) for (int k = 0; k < 2; ++k) \
;       acc[ai][bj][m][n] = __builtin_amdgcn_mfma_f32_16x16x32_bf16(At[m][k], Bt[n][k], acc[ai][bj][m][n], 0, 0, 0); \
;     __builtin_amdgcn_s_setprio(0); } while (0)
; #define WAIT_V(n) asm volatile("s_waitcnt vmcnt(" #n ")" ::: "memory")
; #define WAIT_L(n) asm volatile("s_waitcnt lgkmcnt(" #n ")" ::: "memory")
; #define BAR __builtin_amdgcn_s_barrier()
; template <int EPI> ...
;     ...
;     LDB(B1, 1, 1); WAIT_V(0); BAR; WAIT_L(0); MMA(0, 1, At, B1); BAR;
;     LDA(At, 1, 1); BAR; WAIT_L(0); MMA(1, 0, At, B0); MMA(1, 1, At, B1); BAR; }
;   if (wr == 0) BAR;
	s_setprio 0
	ds_read_b128 v[170:173], v154
	ds_read_b128 v[206:209], v154 offset:1024
	ds_read_b128 v[210:213], v154 offset:2048
	ds_read_b128 v[154:157], v154 offset:3072
	s_waitcnt vmcnt(0)
	s_setprio 1
	s_barrier
	s_waitcnt lgkmcnt(0)
	v_mfma_f32_16x16x32_bf16 v[92:95], v[16:19], v[170:173], v[92:95]
	v_mfma_f32_16x16x32_bf16 v[16:19], v[16:19], v[210:213], v[88:91]
	v_mfma_f32_16x16x32_bf16 v[120:123], v[20:23], v[154:157], v[16:19]
	v_mfma_f32_16x16x32_bf16 v[16:19], v[32:35], v[170:173], v[166:169]
	v_mfma_f32_16x16x32_bf16 v[108:111], v[36:39], v[206:209], v[16:19]
	v_mfma_f32_16x16x32_bf16 v[16:19], v[32:35], v[210:213], v[174:177]
	v_mfma_f32_16x16x32_bf16 v[104:107], v[36:39], v[154:157], v[16:19]
	v_mfma_f32_16x16x32_bf16 v[16:19], v[48:51], v[170:173], v[76:79]
	v_mfma_f32_16x16x32_bf16 v[124:127], v[20:23], v[206:209], v[92:95]
	v_mfma_f32_16x16x32_bf16 v[92:95], v[52:55], v[206:209], v[16:19]
	v_mfma_f32_16x16x32_bf16 v[16:19], v[48:51], v[210:213], v[72:75]
	v_mfma_f32_16x16x32_bf16 v[88:91], v[52:55], v[154:157], v[16:19]
	v_mfma_f32_16x16x32_bf16 v[16:19], v[222:225], v[170:173], v[178:181]
	v_mfma_f32_16x16x32_bf16 v[76:79], v[226:229], v[206:209], v[16:19]
	v_mfma_f32_16x16x32_bf16 v[16:19], v[222:225], v[210:213], v[182:185]
	v_mfma_f32_16x16x32_bf16 v[72:75], v[226:229], v[154:157], v[16:19]
	s_barrier
	s_setprio 0
	ds_read_b128 v[166:169], v153 offset:49152
	ds_read_b128 v[174:177], v153 offset:50176
	ds_read_b128 v[178:181], v152 offset:49152
	ds_read_b128 v[182:185], v152 offset:50176
	ds_read_b128 v[214:217], v151 offset:49152
	ds_read_b128 v[222:225], v151 offset:50176
	ds_read_b128 v[226:229], v150 offset:49152
	ds_read_b128 v[150:153], v150 offset:50176
	s_setprio 1
	s_barrier
	s_waitcnt lgkmcnt(0)
	v_mfma_f32_16x16x32_bf16 v[16:19], v[166:169], v[0:3], v[60:63]
	v_mfma_f32_16x16x32_bf16 v[52:55], v[174:177], v[4:7], v[16:19]
	v_mfma_f32_16x16x32_bf16 v[16:19], v[166:169], v[194:197], v[56:59]
	v_mfma_f32_16x16x32_bf16 v[48:51], v[174:177], v[198:201], v[16:19]
	v_mfma_f32_16x16x32_bf16 v[16:19], v[178:181], v[0:3], v[202:205]
	v_mfma_f32_16x16x32_bf16 v[36:39], v[182:185], v[4:7], v[16:19]
	v_mfma_f32_16x16x32_bf16 v[16:19], v[178:181], v[194:197], v[218:221]
	v_mfma_f32_16x16x32_bf16 v[32:35], v[182:185], v[198:201], v[16:19]
	v_mfma_f32_16x16x32_bf16 v[16:19], v[214:217], v[0:3], v[44:47]
	v_mfma_f32_16x16x32_bf16 v[0:3], v[226:229], v[0:3], v[136:139]
	v_mfma_f32_16x16x32_bf16 v[20:23], v[222:225], v[4:7], v[16:19]
	v_mfma_f32_16x16x32_bf16 v[16:19], v[214:217], v[194:197], v[40:43]
	v_mfma_f32_16x16x32_bf16 v[4:7], v[150:153], v[4:7], v[0:3]
	v_mfma_f32_16x16x32_bf16 v[0:3], v[226:229], v[194:197], v[140:143]
	v_mfma_f32_16x16x32_bf16 v[16:19], v[222:225], v[198:201], v[16:19]
	v_mfma_f32_16x16x32_bf16 v[0:3], v[150:153], v[198:201], v[0:3]
	s_setprio 0
	s_setprio 1
	v_mfma_f32_16x16x32_bf16 v[24:27], v[166:169], v[210:213], v[24:27]
	v_mfma_f32_16x16x32_bf16 v[56:59], v[174:177], v[154:157], v[24:27]
	v_mfma_f32_16x16x32_bf16 v[24:27], v[178:181], v[170:173], v[158:161]
	v_mfma_f32_16x16x32_bf16 v[44:47], v[182:185], v[206:209], v[24:27]
	v_mfma_f32_16x16x32_bf16 v[24:27], v[178:181], v[210:213], v[162:165]
	v_mfma_f32_16x16x32_bf16 v[8:11], v[214:217], v[210:213], v[8:11]
	v_mfma_f32_16x16x32_bf16 v[28:31], v[166:169], v[170:173], v[28:31]
	v_mfma_f32_16x16x32_bf16 v[40:43], v[182:185], v[154:157], v[24:27]
	v_mfma_f32_16x16x32_bf16 v[12:15], v[214:217], v[170:173], v[12:15]
	v_mfma_f32_16x16x32_bf16 v[24:27], v[222:225], v[154:157], v[8:11]
	v_mfma_f32_16x16x32_bf16 v[8:11], v[226:229], v[170:173], v[186:189]
	v_mfma_f32_16x16x32_bf16 v[60:63], v[174:177], v[206:209], v[28:31]
	v_mfma_f32_16x16x32_bf16 v[28:31], v[222:225], v[206:209], v[12:15]
	v_mfma_f32_16x16x32_bf16 v[12:15], v[150:153], v[206:209], v[8:11]
	v_mfma_f32_16x16x32_bf16 v[8:11], v[226:229], v[210:213], v[190:193]
	v_mfma_f32_16x16x32_bf16 v[8:11], v[150:153], v[154:157], v[8:11]
	s_barrier
	s_setprio 0
	v_cmp_gt_u32_e32 vcc, s55, v144
	s_and_saveexec_b64 s[36:37], vcc
	s_cbranch_execz .LBB0_1385
	s_barrier

; #define STAGE(P, BASE, kt) do { const char* _g = (const char*)(BASE) + (size_t)((kt) * (BK * 2)); \
;     __builtin_amdgcn_global_load_lds((const unsigned*)(_g + (size_t)goff0), (unsigned*)((char*)(P) + tid_ * 16), 16, 0, 0); \
;     __builtin_amdgcn_global_load_lds((const unsigned*)(_g + (size_t)goff1), (unsigned*)((char*)(P) + tid_ * 16 + 8192), 16, 0, 0); } while (0)
; #define STAGEA(P, BASE, kt) do { const char* _g = (const char*)(BASE) + (size_t)((kt) * a_kbytes); \
;     __builtin_amdgcn_global_load_lds((const unsigned*)(_g + (size_t)goffA0), (unsigned*)((char*)(P) + tid_ * 16), 16, 0, 0); \
;     __builtin_amdgcn_global_load_lds((const unsigned*)(_g + (size_t)goffA1), (unsigned*)((char*)(P) + tid_ * 16 + 8192), 16, 0, 0); } while (0)
; #define LDA(dst, b, h) for (int m = 0; m < 4; ++m) for (int k = 0; k < 2; ++k) \
;     dst[m][k] = *reinterpret_cast<const bf16x8*>((char*)SA(b, h) + lds_byte(wr * 64 + m * 16 + fr, k * 32 + fq * 8))
; #define LDB(dst, b, h) for (int n = 0; n < 2; ++n) for (int k = 0; k < 2; ++k) \
;     dst[n][k] = *reinterpret_cast<const bf16x8*>((char*)SB(b, h) + lds_byte(wc * 32 + n * 16 + fr, k * 32 + fq * 8))
; #define MMA(ai, bj, At, Bt) do { __builtin_amdgcn_s_setprio(1); \
;     for (int m = 0; m < 4; ++m) for (int n = 0; n < 2; ++n) for (int k = 0; k < 2; ++k) \
;       acc[ai][bj][m][n] = __builtin_amdgcn_mfma_f32_16x16x32_bf16(At[m][k], Bt[n][k], acc[ai][bj][m][n], 0, 0, 0); \
;     __builtin_amdgcn_s_setprio(0); } while (0)
; #define WAIT_L(n) asm volatile("s_waitcnt lgkmcnt(" #n ")" ::: "memory")
; #define BAR __builtin_amdgcn_s_barrier()
; #define SCHED __builtin_amdgcn_sched_barrier(0)
; template <int EPI> ...
;     ...
;     LDB(B0, 0, 0); SCHED; LDA(At, 0, 0); STAGEA(SA(1, 1), A1, t + 1);
;     WAIT_L(8); BAR; WAIT_L(0); MMA(0, 0, At, B0); BAR; SCHED;
;     LDB(B1, 0, 1); STAGE(SB(0, 0), B0p, t + 2);
;     BAR; WAIT_L(0); MMA(0, 1, At, B1); BAR;
;     LDA(At, 0, 1); STAGEA(SA(0, 0), A0, t + 2);
;     BAR; WAIT_L(0); MMA(1, 0, At, B0); BAR; SCHED;
.LBB0_1716:
	ds_read_b128 v[176:179], v172
	ds_read_b128 v[180:183], v172 offset:1024
	ds_read_b128 v[184:187], v172 offset:2048
	ds_read_b128 v[188:191], v172 offset:3072
	v_add_u32_e32 v173, 0xc000, v159
	v_lshl_add_u64 v[240:241], s[30:31], 0, v[142:143]
	v_readfirstlane_b32 s27, v173
	v_lshl_add_u64 v[174:175], v[240:241], 0, s[6:7]
	s_mov_b32 m0, s27
	ds_read_b128 v[192:195], v154
	ds_read_b128 v[196:199], v154 offset:1024
	ds_read_b128 v[200:203], v153
	ds_read_b128 v[204:207], v153 offset:1024
	ds_read_b128 v[208:211], v152
	ds_read_b128 v[212:215], v152 offset:1024
	ds_read_b128 v[216:219], v151
	ds_read_b128 v[220:223], v151 offset:1024
	global_load_lds_dwordx4 v[174:175], off
	v_add_u32_e32 v174, 0xe000, v159
	v_lshl_add_u64 v[242:243], s[30:31], 0, v[144:145]
	v_readfirstlane_b32 s27, v174
	v_lshl_add_u64 v[224:225], v[242:243], 0, s[6:7]
	s_mov_b32 m0, s27
	s_nop 0
	global_load_lds_dwordx4 v[224:225], off
	s_waitcnt lgkmcnt(8)
	s_setprio 1
	s_barrier
	s_waitcnt lgkmcnt(0)
	v_mfma_f32_16x16x32_bf16 v[124:127], v[192:195], v[176:179], v[124:127]
	v_mfma_f32_16x16x32_bf16 v[120:123], v[192:195], v[184:187], v[120:123]
	v_mfma_f32_16x16x32_bf16 v[116:119], v[200:203], v[176:179], v[116:119]
	v_mfma_f32_16x16x32_bf16 v[112:115], v[200:203], v[184:187], v[112:115]
	v_mfma_f32_16x16x32_bf16 v[108:111], v[208:211], v[176:179], v[108:111]
	v_mfma_f32_16x16x32_bf16 v[104:107], v[208:211], v[184:187], v[104:107]
	v_mfma_f32_16x16x32_bf16 v[100:103], v[216:219], v[176:179], v[100:103]
	v_mfma_f32_16x16x32_bf16 v[96:99], v[216:219], v[184:187], v[96:99]
	v_mfma_f32_16x16x32_bf16 v[124:127], v[196:199], v[180:183], v[124:127]
	v_mfma_f32_16x16x32_bf16 v[120:123], v[196:199], v[188:191], v[120:123]
	v_mfma_f32_16x16x32_bf16 v[116:119], v[204:207], v[180:183], v[116:119]
	v_mfma_f32_16x16x32_bf16 v[112:115], v[204:207], v[188:191], v[112:115]
	v_mfma_f32_16x16x32_bf16 v[108:111], v[212:215], v[180:183], v[108:111]
	v_mfma_f32_16x16x32_bf16 v[104:107], v[212:215], v[188:191], v[104:107]
	v_mfma_f32_16x16x32_bf16 v[100:103], v[220:223], v[180:183], v[100:103]
	v_mfma_f32_16x16x32_bf16 v[96:99], v[220:223], v[188:191], v[96:99]
	s_barrier
	s_setprio 0
	v_lshl_add_u64 v[244:245], s[30:31], 0, v[128:129]
	v_readfirstlane_b32 s27, v156
	v_lshl_add_u64 v[246:247], v[244:245], 0, s[8:9]
	s_mov_b32 m0, s27
	ds_read_b128 v[224:227], v169
	ds_read_b128 v[228:231], v169 offset:1024
	ds_read_b128 v[232:235], v169 offset:2048
	ds_read_b128 v[236:239], v169 offset:3072
	global_load_lds_dwordx4 v[246:247], off
	v_lshl_add_u64 v[246:247], s[30:31], 0, v[130:131]
	v_readfirstlane_b32 s27, v158
	v_lshl_add_u64 v[248:249], v[246:247], 0, s[8:9]
	s_mov_b32 m0, s27
	s_nop 0
	global_load_lds_dwordx4 v[248:249], off
	s_setprio 1
	s_barrier
	s_waitcnt lgkmcnt(0)
	v_mfma_f32_16x16x32_bf16 v[92:95], v[192:195], v[224:227], v[92:95]
	v_mfma_f32_16x16x32_bf16 v[88:91], v[192:195], v[232:235], v[88:91]
	v_mfma_f32_16x16x32_bf16 v[84:87], v[200:203], v[224:227], v[84:87]
	v_mfma_f32_16x16x32_bf16 v[80:83], v[200:203], v[232:235], v[80:83]
	v_mfma_f32_16x16x32_bf16 v[76:79], v[208:211], v[224:227], v[76:79]
	v_mfma_f32_16x16x32_bf16 v[72:75], v[208:211], v[232:235], v[72:75]
	v_mfma_f32_16x16x32_bf16 v[68:71], v[216:219], v[224:227], v[68:71]
	v_mfma_f32_16x16x32_bf16 v[64:67], v[216:219], v[232:235], v[64:67]
	v_mfma_f32_16x16x32_bf16 v[92:95], v[196:199], v[228:231], v[92:95]
	v_mfma_f32_16x16x32_bf16 v[88:91], v[196:199], v[236:239], v[88:91]
	v_mfma_f32_16x16x32_bf16 v[84:87], v[204:207], v[228:231], v[84:87]
	v_mfma_f32_16x16x32_bf16 v[80:83], v[204:207], v[236:239], v[80:83]
	v_mfma_f32_16x16x32_bf16 v[76:79], v[212:215], v[228:231], v[76:79]
	v_mfma_f32_16x16x32_bf16 v[72:75], v[212:215], v[236:239], v[72:75]
	v_mfma_f32_16x16x32_bf16 v[68:71], v[220:223], v[228:231], v[68:71]
	v_mfma_f32_16x16x32_bf16 v[64:67], v[220:223], v[236:239], v[64:67]
	s_barrier
	s_setprio 0
	v_readfirstlane_b32 s27, v159
	v_lshl_add_u64 v[248:249], v[240:241], 0, s[10:11]
	s_mov_b32 m0, s27
	v_readfirstlane_b32 s27, v160
	ds_read_b128 v[192:195], v154 offset:16384
	ds_read_b128 v[196:199], v154 offset:17408
	ds_read_b128 v[200:203], v153 offset:16384
	ds_read_b128 v[204:207], v153 offset:17408
	ds_read_b128 v[208:211], v152 offset:16384
	ds_read_b128 v[212:215], v152 offset:17408
	ds_read_b128 v[216:219], v151 offset:16384
	ds_read_b128 v[220:223], v151 offset:17408
	global_load_lds_dwordx4 v[248:249], off
	v_lshl_add_u64 v[248:249], v[242:243], 0, s[10:11]
	s_mov_b32 m0, s27
	s_nop 0
	global_load_lds_dwordx4 v[248:249], off
	s_setprio 1
	s_barrier
	s_waitcnt lgkmcnt(0)
	v_mfma_f32_16x16x32_bf16 v[60:63], v[192:195], v[176:179], v[60:63]
	v_mfma_f32_16x16x32_bf16 v[56:59], v[192:195], v[184:187], v[56:59]
	v_mfma_f32_16x16x32_bf16 v[52:55], v[200:203], v[176:179], v[52:55]
	v_mfma_f32_16x16x32_bf16 v[48:51], v[200:203], v[184:187], v[48:51]
	v_mfma_f32_16x16x32_bf16 v[44:47], v[208:211], v[176:179], v[44:47]
	v_mfma_f32_16x16x32_bf16 v[40:43], v[208:211], v[184:187], v[40:43]
	v_mfma_f32_16x16x32_bf16 v[36:39], v[216:219], v[176:179], v[36:39]
	v_mfma_f32_16x16x32_bf16 v[32:35], v[216:219], v[184:187], v[32:35]
	v_mfma_f32_16x16x32_bf16 v[60:63], v[196:199], v[180:183], v[60:63]
	v_mfma_f32_16x16x32_bf16 v[56:59], v[196:199], v[188:191], v[56:59]
	v_mfma_f32_16x16x32_bf16 v[52:55], v[204:207], v[180:183], v[52:55]
	v_mfma_f32_16x16x32_bf16 v[48:51], v[204:207], v[188:191], v[48:51]
	v_mfma_f32_16x16x32_bf16 v[44:47], v[212:215], v[180:183], v[44:47]
	v_mfma_f32_16x16x32_bf16 v[40:43], v[212:215], v[188:191], v[40:43]
	v_mfma_f32_16x16x32_bf16 v[36:39], v[220:223], v[180:183], v[36:39]
	v_mfma_f32_16x16x32_bf16 v[32:35], v[220:223], v[188:191], v[32:35]
	s_barrier
; #define STAGE(P, BASE, kt) do { const char* _g = (const char*)(BASE) + (size_t)((kt) * (BK * 2)); \
;     __builtin_amdgcn_global_load_lds((const unsigned*)(_g + (size_t)goff0), (unsigned*)((char*)(P) + tid_ * 16), 16, 0, 0); \
;     __builtin_amdgcn_global_load_lds((const unsigned*)(_g + (size_t)goff1), (unsigned*)((char*)(P) + tid_ * 16 + 8192), 16, 0, 0); } while (0)
; #define STAGEA(P, BASE, kt) do { const char* _g = (const char*)(BASE) + (size_t)((kt) * a_kbytes); \
;     __builtin_amdgcn_global_load_lds((const unsigned*)(_g + (size_t)goffA0), (unsigned*)((char*)(P) + tid_ * 16), 16, 0, 0); \
;     __builtin_amdgcn_global_load_lds((const unsigned*)(_g + (size_t)goffA1), (unsigned*)((char*)(P) + tid_ * 16 + 8192), 16, 0, 0); } while (0)
; #define LDA(dst, b, h) for (int m = 0; m < 4; ++m) for (int k = 0; k < 2; ++k) \
;     dst[m][k] = *reinterpret_cast<const bf16x8*>((char*)SA(b, h) + lds_byte(wr * 64 + m * 16 + fr, k * 32 + fq * 8))
; #define LDB(dst, b, h) for (int n = 0; n < 2; ++n) for (int k = 0; k < 2; ++k) \
;     dst[n][k] = *reinterpret_cast<const bf16x8*>((char*)SB(b, h) + lds_byte(wc * 32 + n * 16 + fr, k * 32 + fq * 8))
; #define MMA(ai, bj, At, Bt) do { __builtin_amdgcn_s_setprio(1); \
;     for (int m = 0; m < 4; ++m) for (int n = 0; n < 2; ++n) for (int k = 0; k < 2; ++k) \
;       acc[ai][bj][m][n] = __builtin_amdgcn_mfma_f32_16x16x32_bf16(At[m][k], Bt[n][k], acc[ai][bj][m][n], 0, 0, 0); \
;     __builtin_amdgcn_s_setprio(0); } while (0)
; #define WAIT_V(n) asm volatile("s_waitcnt vmcnt(" #n ")" ::: "memory")
; #define WAIT_L(n) asm volatile("s_waitcnt lgkmcnt(" #n ")" ::: "memory")
; #define BAR __builtin_amdgcn_s_barrier()
; #define SCHED __builtin_amdgcn_sched_barrier(0)
; template <int EPI> ...
;     ...
;     STAGE(SB(0, 1), B1p, t + 2);
;     WAIT_V(6); BAR; MMA(1, 1, At, B1); BAR;
;     LDB(B0, 1, 0); SCHED; LDA(At, 1, 0); STAGEA(SA(0, 1), A1, t + 2);
;     WAIT_L(8); BAR; WAIT_L(0); MMA(0, 0, At, B0); BAR; SCHED;
;     LDB(B1, 1, 1); STAGE(SB(1, 0), B0p, t + 3);
;     BAR; WAIT_L(0); MMA(0, 1, At, B1); BAR;
;     LDA(At, 1, 1); STAGEA(SA(1, 0), A0, t + 3);
	s_setprio 0
	v_readfirstlane_b32 s27, v161
	v_lshl_add_u64 v[176:177], v[244:245], 0, s[12:13]
	s_mov_b32 m0, s27
	v_readfirstlane_b32 s27, v162
	global_load_lds_dwordx4 v[176:177], off
	v_lshl_add_u64 v[176:177], v[246:247], 0, s[12:13]
	s_mov_b32 m0, s27
	s_nop 0
	global_load_lds_dwordx4 v[176:177], off
	s_waitcnt vmcnt(6)
	s_setprio 1
	s_barrier
	v_mfma_f32_16x16x32_bf16 v[28:31], v[192:195], v[224:227], v[28:31]
	v_mfma_f32_16x16x32_bf16 v[24:27], v[192:195], v[232:235], v[24:27]
	v_mfma_f32_16x16x32_bf16 v[20:23], v[200:203], v[224:227], v[20:23]
	v_mfma_f32_16x16x32_bf16 v[16:19], v[200:203], v[232:235], v[16:19]
	v_mfma_f32_16x16x32_bf16 v[12:15], v[208:211], v[224:227], v[12:15]
	v_mfma_f32_16x16x32_bf16 v[8:11], v[208:211], v[232:235], v[8:11]
	v_mfma_f32_16x16x32_bf16 v[4:7], v[216:219], v[224:227], v[4:7]
	v_mfma_f32_16x16x32_bf16 v[0:3], v[216:219], v[232:235], v[0:3]
	v_mfma_f32_16x16x32_bf16 v[28:31], v[196:199], v[228:231], v[28:31]
	v_mfma_f32_16x16x32_bf16 v[24:27], v[196:199], v[236:239], v[24:27]
	v_mfma_f32_16x16x32_bf16 v[20:23], v[204:207], v[228:231], v[20:23]
	v_mfma_f32_16x16x32_bf16 v[16:19], v[204:207], v[236:239], v[16:19]
	v_mfma_f32_16x16x32_bf16 v[12:15], v[212:215], v[228:231], v[12:15]
	v_mfma_f32_16x16x32_bf16 v[8:11], v[212:215], v[236:239], v[8:11]
	v_mfma_f32_16x16x32_bf16 v[4:7], v[220:223], v[228:231], v[4:7]
	v_mfma_f32_16x16x32_bf16 v[0:3], v[220:223], v[236:239], v[0:3]
	s_barrier
	s_setprio 0
	ds_read_b128 v[176:179], v157
	ds_read_b128 v[180:183], v157 offset:1024
	ds_read_b128 v[184:187], v157 offset:2048
	ds_read_b128 v[188:191], v157 offset:3072
	v_readfirstlane_b32 s27, v163
	v_lshl_add_u64 v[224:225], v[240:241], 0, s[14:15]
	s_mov_b32 m0, s27
	v_readfirstlane_b32 s27, v164
	ds_read_b128 v[192:195], v154 offset:32768
	ds_read_b128 v[196:199], v154 offset:33792
	ds_read_b128 v[200:203], v153 offset:32768
	ds_read_b128 v[204:207], v153 offset:33792
	ds_read_b128 v[208:211], v152 offset:32768
	ds_read_b128 v[212:215], v152 offset:33792
	ds_read_b128 v[216:219], v151 offset:32768
	ds_read_b128 v[220:223], v151 offset:33792
	global_load_lds_dwordx4 v[224:225], off
	v_lshl_add_u64 v[224:225], v[242:243], 0, s[14:15]
	s_mov_b32 m0, s27
	s_nop 0
	global_load_lds_dwordx4 v[224:225], off
	s_waitcnt lgkmcnt(8)
	s_setprio 1
	s_barrier
	s_waitcnt lgkmcnt(0)
	v_mfma_f32_16x16x32_bf16 v[124:127], v[192:195], v[176:179], v[124:127]
	v_mfma_f32_16x16x32_bf16 v[120:123], v[192:195], v[184:187], v[120:123]
	v_mfma_f32_16x16x32_bf16 v[116:119], v[200:203], v[176:179], v[116:119]
	v_mfma_f32_16x16x32_bf16 v[112:115], v[200:203], v[184:187], v[112:115]
	v_mfma_f32_16x16x32_bf16 v[108:111], v[208:211], v[176:179], v[108:111]
	v_mfma_f32_16x16x32_bf16 v[104:107], v[208:211], v[184:187], v[104:107]
	v_mfma_f32_16x16x32_bf16 v[100:103], v[216:219], v[176:179], v[100:103]
	v_mfma_f32_16x16x32_bf16 v[96:99], v[216:219], v[184:187], v[96:99]
	v_mfma_f32_16x16x32_bf16 v[124:127], v[196:199], v[180:183], v[124:127]
	v_mfma_f32_16x16x32_bf16 v[120:123], v[196:199], v[188:191], v[120:123]
	v_mfma_f32_16x16x32_bf16 v[116:119], v[204:207], v[180:183], v[116:119]
	v_mfma_f32_16x16x32_bf16 v[112:115], v[204:207], v[188:191], v[112:115]
	v_mfma_f32_16x16x32_bf16 v[108:111], v[212:215], v[180:183], v[108:111]
	v_mfma_f32_16x16x32_bf16 v[104:107], v[212:215], v[188:191], v[104:107]
	v_mfma_f32_16x16x32_bf16 v[100:103], v[220:223], v[180:183], v[100:103]
	v_mfma_f32_16x16x32_bf16 v[96:99], v[220:223], v[188:191], v[96:99]
	s_barrier
	s_setprio 0
	v_readfirstlane_b32 s27, v165
	v_lshl_add_u64 v[248:249], v[244:245], 0, s[16:17]
	s_mov_b32 m0, s27
	v_readfirstlane_b32 s27, v166
	ds_read_b128 v[224:227], v155
	ds_read_b128 v[228:231], v155 offset:1024
	ds_read_b128 v[232:235], v155 offset:2048
	ds_read_b128 v[236:239], v155 offset:3072
	global_load_lds_dwordx4 v[248:249], off
	v_lshl_add_u64 v[248:249], v[246:247], 0, s[16:17]
	s_mov_b32 m0, s27
	s_nop 0
	global_load_lds_dwordx4 v[248:249], off
	s_setprio 1
	s_barrier
	s_waitcnt lgkmcnt(0)
	v_mfma_f32_16x16x32_bf16 v[92:95], v[192:195], v[224:227], v[92:95]
	v_mfma_f32_16x16x32_bf16 v[88:91], v[192:195], v[232:235], v[88:91]
	v_mfma_f32_16x16x32_bf16 v[84:87], v[200:203], v[224:227], v[84:87]
	v_mfma_f32_16x16x32_bf16 v[80:83], v[200:203], v[232:235], v[80:83]
	v_mfma_f32_16x16x32_bf16 v[76:79], v[208:211], v[224:227], v[76:79]
	v_mfma_f32_16x16x32_bf16 v[72:75], v[208:211], v[232:235], v[72:75]
	v_mfma_f32_16x16x32_bf16 v[68:71], v[216:219], v[224:227], v[68:71]
	v_mfma_f32_16x16x32_bf16 v[64:67], v[216:219], v[232:235], v[64:67]
	v_mfma_f32_16x16x32_bf16 v[92:95], v[196:199], v[228:231], v[92:95]
	v_mfma_f32_16x16x32_bf16 v[88:91], v[196:199], v[236:239], v[88:91]
	v_mfma_f32_16x16x32_bf16 v[84:87], v[204:207], v[228:231], v[84:87]
	v_mfma_f32_16x16x32_bf16 v[80:83], v[204:207], v[236:239], v[80:83]
	v_mfma_f32_16x16x32_bf16 v[76:79], v[212:215], v[228:231], v[76:79]
	v_mfma_f32_16x16x32_bf16 v[72:75], v[212:215], v[236:239], v[72:75]
	v_mfma_f32_16x16x32_bf16 v[68:71], v[220:223], v[228:231], v[68:71]
	v_mfma_f32_16x16x32_bf16 v[64:67], v[220:223], v[236:239], v[64:67]
	s_barrier
	s_setprio 0
	v_readfirstlane_b32 s27, v167
	v_lshl_add_u64 v[240:241], v[240:241], 0, s[18:19]
	s_mov_b32 m0, s27
	v_readfirstlane_b32 s27, v168
	ds_read_b128 v[192:195], v154 offset:49152
	ds_read_b128 v[196:199], v154 offset:50176
	ds_read_b128 v[200:203], v153 offset:49152
	ds_read_b128 v[204:207], v153 offset:50176
	ds_read_b128 v[208:211], v152 offset:49152
	ds_read_b128 v[212:215], v152 offset:50176
	ds_read_b128 v[216:219], v151 offset:49152
	ds_read_b128 v[220:223], v151 offset:50176
	global_load_lds_dwordx4 v[240:241], off
	v_lshl_add_u64 v[240:241], v[242:243], 0, s[18:19]
	s_mov_b32 m0, s27
	s_nop 0
	global_load_lds_dwordx4 v[240:241], off
	s_setprio 1
	s_barrier
; #define STAGE(P, BASE, kt) do { const char* _g = (const char*)(BASE) + (size_t)((kt) * (BK * 2)); \
;     __builtin_amdgcn_global_load_lds((const unsigned*)(_g + (size_t)goff0), (unsigned*)((char*)(P) + tid_ * 16), 16, 0, 0); \
;     __builtin_amdgcn_global_load_lds((const unsigned*)(_g + (size_t)goff1), (unsigned*)((char*)(P) + tid_ * 16 + 8192), 16, 0, 0); } while (0)
; #define STAGEA(P, BASE, kt) do { const char* _g = (const char*)(BASE) + (size_t)((kt) * a_kbytes); \
;     __builtin_amdgcn_global_load_lds((const unsigned*)(_g + (size_t)goffA0), (unsigned*)((char*)(P) + tid_ * 16), 16, 0, 0); \
;     __builtin_amdgcn_global_load_lds((const unsigned*)(_g + (size_t)goffA1), (unsigned*)((char*)(P) + tid_ * 16 + 8192), 16, 0, 0); } while (0)
; #define LDA(dst, b, h) for (int m = 0; m < 4; ++m) for (int k = 0; k < 2; ++k) \
;     dst[m][k] = *reinterpret_cast<const bf16x8*>((char*)SA(b, h) + lds_byte(wr * 64 + m * 16 + fr, k * 32 + fq * 8))
; #define LDB(dst, b, h) for (int n = 0; n < 2; ++n) for (int k = 0; k < 2; ++k) \
;     dst[n][k] = *reinterpret_cast<const bf16x8*>((char*)SB(b, h) + lds_byte(wc * 32 + n * 16 + fr, k * 32 + fq * 8))
; #define MMA(ai, bj, At, Bt) do { __builtin_amdgcn_s_setprio(1); \
;     for (int m = 0; m < 4; ++m) for (int n = 0; n < 2; ++n) for (int k = 0; k < 2; ++k) \
;       acc[ai][bj][m][n] = __builtin_amdgcn_mfma_f32_16x16x32_bf16(At[m][k], Bt[n][k], acc[ai][bj][m][n], 0, 0, 0); \
;     __builtin_amdgcn_s_setprio(0); } while (0)
; #define WAIT_V(n) asm volatile("s_waitcnt vmcnt(" #n ")" ::: "memory")
; #define WAIT_L(n) asm volatile("s_waitcnt lgkmcnt(" #n ")" ::: "memory")
; #define BAR __builtin_amdgcn_s_barrier()
; #define SCHED __builtin_amdgcn_sched_barrier(0)
; template <int EPI> ...
;     ...
;     BAR; WAIT_L(0); MMA(1, 0, At, B0); BAR; SCHED;
;     STAGE(SB(1, 1), B1p, t + 3);
;     WAIT_V(6); BAR; MMA(1, 1, At, B1); BAR;
;   }
;   { LDB(B0, 0, 0); LDA(At, 0, 0); STAGEA(SA(1, 1), A1, nt - 1);
;     BAR; WAIT_L(0); MMA(0, 0, At, B0); BAR;
;     LDB(B1, 0, 1); BAR; WAIT_L(0); MMA(0, 1, At, B1); BAR;
	s_waitcnt lgkmcnt(0)
	v_mfma_f32_16x16x32_bf16 v[60:63], v[192:195], v[176:179], v[60:63]
	v_mfma_f32_16x16x32_bf16 v[56:59], v[192:195], v[184:187], v[56:59]
	v_mfma_f32_16x16x32_bf16 v[52:55], v[200:203], v[176:179], v[52:55]
	v_mfma_f32_16x16x32_bf16 v[48:51], v[200:203], v[184:187], v[48:51]
	v_mfma_f32_16x16x32_bf16 v[44:47], v[208:211], v[176:179], v[44:47]
	v_mfma_f32_16x16x32_bf16 v[40:43], v[208:211], v[184:187], v[40:43]
	v_mfma_f32_16x16x32_bf16 v[36:39], v[216:219], v[176:179], v[36:39]
	v_mfma_f32_16x16x32_bf16 v[32:35], v[216:219], v[184:187], v[32:35]
	v_mfma_f32_16x16x32_bf16 v[60:63], v[196:199], v[180:183], v[60:63]
	v_mfma_f32_16x16x32_bf16 v[56:59], v[196:199], v[188:191], v[56:59]
	v_mfma_f32_16x16x32_bf16 v[52:55], v[204:207], v[180:183], v[52:55]
	v_mfma_f32_16x16x32_bf16 v[48:51], v[204:207], v[188:191], v[48:51]
	v_mfma_f32_16x16x32_bf16 v[44:47], v[212:215], v[180:183], v[44:47]
	v_mfma_f32_16x16x32_bf16 v[40:43], v[212:215], v[188:191], v[40:43]
	v_mfma_f32_16x16x32_bf16 v[36:39], v[220:223], v[180:183], v[36:39]
	v_mfma_f32_16x16x32_bf16 v[32:35], v[220:223], v[188:191], v[32:35]
	s_barrier
	s_setprio 0
	v_readfirstlane_b32 s27, v170
	v_lshl_add_u64 v[176:177], v[244:245], 0, s[20:21]
	s_mov_b32 m0, s27
	v_readfirstlane_b32 s27, v171
	global_load_lds_dwordx4 v[176:177], off
	v_lshl_add_u64 v[176:177], v[246:247], 0, s[20:21]
	s_mov_b32 m0, s27
	s_nop 0
	global_load_lds_dwordx4 v[176:177], off
	s_waitcnt vmcnt(6)
	s_setprio 1
	s_barrier
	v_mfma_f32_16x16x32_bf16 v[28:31], v[192:195], v[224:227], v[28:31]
	v_mfma_f32_16x16x32_bf16 v[24:27], v[192:195], v[232:235], v[24:27]
	v_mfma_f32_16x16x32_bf16 v[20:23], v[200:203], v[224:227], v[20:23]
	v_mfma_f32_16x16x32_bf16 v[16:19], v[200:203], v[232:235], v[16:19]
	v_mfma_f32_16x16x32_bf16 v[12:15], v[208:211], v[224:227], v[12:15]
	v_mfma_f32_16x16x32_bf16 v[8:11], v[208:211], v[232:235], v[8:11]
	v_mfma_f32_16x16x32_bf16 v[4:7], v[216:219], v[224:227], v[4:7]
	v_mfma_f32_16x16x32_bf16 v[0:3], v[216:219], v[232:235], v[0:3]
	v_mfma_f32_16x16x32_bf16 v[28:31], v[196:199], v[228:231], v[28:31]
	v_mfma_f32_16x16x32_bf16 v[24:27], v[196:199], v[236:239], v[24:27]
	v_mfma_f32_16x16x32_bf16 v[20:23], v[204:207], v[228:231], v[20:23]
	v_mfma_f32_16x16x32_bf16 v[16:19], v[204:207], v[236:239], v[16:19]
	v_mfma_f32_16x16x32_bf16 v[12:15], v[212:215], v[228:231], v[12:15]
	v_mfma_f32_16x16x32_bf16 v[8:11], v[212:215], v[236:239], v[8:11]
	v_mfma_f32_16x16x32_bf16 v[4:7], v[220:223], v[228:231], v[4:7]
	v_mfma_f32_16x16x32_bf16 v[0:3], v[220:223], v[236:239], v[0:3]
	s_barrier
	s_setprio 0
	s_add_i32 s25, s25, 2
	s_add_u32 s30, s30, 0x100
	s_addc_u32 s31, s31, 0
	s_cmp_lt_u32 s25, 28
	s_cbranch_scc1 .LBB0_1716
	s_add_u32 s28, s28, 0x80f80
	s_addc_u32 s29, s29, 0
	v_readfirstlane_b32 s25, v173
	v_lshl_add_u64 v[166:167], s[28:29], 0, v[134:135]
	s_mov_b32 m0, s25
	v_readfirstlane_b32 s25, v174
	ds_read_b128 v[128:131], v172
	ds_read_b128 v[142:145], v172 offset:1024
	ds_read_b128 v[158:161], v172 offset:2048
	ds_read_b128 v[162:165], v172 offset:3072
	ds_read_b128 v[176:179], v154
	ds_read_b128 v[180:183], v154 offset:1024
	ds_read_b128 v[184:187], v153
	ds_read_b128 v[188:191], v153 offset:1024
	ds_read_b128 v[192:195], v152
	ds_read_b128 v[196:199], v152 offset:1024
	ds_read_b128 v[200:203], v151
	ds_read_b128 v[204:207], v151 offset:1024
	global_load_lds_dwordx4 v[166:167], off
	v_lshl_add_u64 v[166:167], s[28:29], 0, v[132:133]
	s_mov_b32 m0, s25
	s_nop 0
	global_load_lds_dwordx4 v[166:167], off
	s_setprio 1
	s_barrier
	s_waitcnt lgkmcnt(0)
	v_mfma_f32_16x16x32_bf16 v[124:127], v[176:179], v[128:131], v[124:127]
	v_mfma_f32_16x16x32_bf16 v[120:123], v[176:179], v[158:161], v[120:123]
	v_mfma_f32_16x16x32_bf16 v[108:111], v[192:195], v[128:131], v[108:111]
	v_mfma_f32_16x16x32_bf16 v[104:107], v[192:195], v[158:161], v[104:107]
	v_mfma_f32_16x16x32_bf16 v[124:127], v[180:183], v[142:145], v[124:127]
	v_mfma_f32_16x16x32_bf16 v[120:123], v[180:183], v[162:165], v[120:123]
	v_mfma_f32_16x16x32_bf16 v[116:119], v[184:187], v[128:131], v[116:119]
	v_mfma_f32_16x16x32_bf16 v[112:115], v[184:187], v[158:161], v[112:115]
	v_mfma_f32_16x16x32_bf16 v[108:111], v[196:199], v[142:145], v[108:111]
	v_mfma_f32_16x16x32_bf16 v[104:107], v[196:199], v[162:165], v[104:107]
	v_mfma_f32_16x16x32_bf16 v[100:103], v[200:203], v[128:131], v[100:103]
	v_mfma_f32_16x16x32_bf16 v[96:99], v[200:203], v[158:161], v[96:99]
	v_mfma_f32_16x16x32_bf16 v[170:173], v[188:191], v[142:145], v[116:119]
	v_mfma_f32_16x16x32_bf16 v[208:211], v[188:191], v[162:165], v[112:115]
	v_mfma_f32_16x16x32_bf16 v[212:215], v[204:207], v[142:145], v[100:103]
	v_mfma_f32_16x16x32_bf16 v[216:219], v[204:207], v[162:165], v[96:99]
	s_barrier
	s_setprio 0
	s_nop 1
	ds_read_b128 v[96:99], v169
	ds_read_b128 v[100:103], v169 offset:1024
	ds_read_b128 v[112:115], v169 offset:2048
	ds_read_b128 v[116:119], v169 offset:3072
	s_setprio 1
	s_barrier
	s_waitcnt lgkmcnt(0)
	v_mfma_f32_16x16x32_bf16 v[92:95], v[176:179], v[96:99], v[92:95]
	v_mfma_f32_16x16x32_bf16 v[88:91], v[176:179], v[112:115], v[88:91]
	v_mfma_f32_16x16x32_bf16 v[76:79], v[192:195], v[96:99], v[76:79]
	v_mfma_f32_16x16x32_bf16 v[72:75], v[192:195], v[112:115], v[72:75]
	v_mfma_f32_16x16x32_bf16 v[92:95], v[180:183], v[100:103], v[92:95]
	v_mfma_f32_16x16x32_bf16 v[88:91], v[180:183], v[116:119], v[88:91]
	v_mfma_f32_16x16x32_bf16 v[84:87], v[184:187], v[96:99], v[84:87]
	v_mfma_f32_16x16x32_bf16 v[80:83], v[184:187], v[112:115], v[80:83]
	v_mfma_f32_16x16x32_bf16 v[76:79], v[196:199], v[100:103], v[76:79]
	v_mfma_f32_16x16x32_bf16 v[72:75], v[196:199], v[116:119], v[72:75]
	v_mfma_f32_16x16x32_bf16 v[68:71], v[200:203], v[96:99], v[68:71]
	v_mfma_f32_16x16x32_bf16 v[64:67], v[200:203], v[112:115], v[64:67]
	v_mfma_f32_16x16x32_bf16 v[166:169], v[188:191], v[100:103], v[84:87]
	v_mfma_f32_16x16x32_bf16 v[174:177], v[188:191], v[116:119], v[80:83]
	v_mfma_f32_16x16x32_bf16 v[178:181], v[204:207], v[100:103], v[68:71]
	v_mfma_f32_16x16x32_bf16 v[182:185], v[204:207], v[116:119], v[64:67]
	s_barrier
; #define LDA(dst, b, h) for (int m = 0; m < 4; ++m) for (int k = 0; k < 2; ++k) \
;     dst[m][k] = *reinterpret_cast<const bf16x8*>((char*)SA(b, h) + lds_byte(wr * 64 + m * 16 + fr, k * 32 + fq * 8))
; #define LDB(dst, b, h) for (int n = 0; n < 2; ++n) for (int k = 0; k < 2; ++k) \
;     dst[n][k] = *reinterpret_cast<const bf16x8*>((char*)SB(b, h) + lds_byte(wc * 32 + n * 16 + fr, k * 32 + fq * 8))
; #define MMA(ai, bj, At, Bt) do { __builtin_amdgcn_s_setprio(1); \
;     for (int m = 0; m < 4; ++m) for (int n = 0; n < 2; ++n) for (int k = 0; k < 2; ++k) \
;       acc[ai][bj][m][n] = __builtin_amdgcn_mfma_f32_16x16x32_bf16(At[m][k], Bt[n][k], acc[ai][bj][m][n], 0, 0, 0); \
;     __builtin_amdgcn_s_setprio(0); } while (0)
; #define WAIT_V(n) asm volatile("s_waitcnt vmcnt(" #n ")" ::: "memory")
; #define WAIT_L(n) asm volatile("s_waitcnt lgkmcnt(" #n ")" ::: "memory")
; #define BAR __builtin_amdgcn_s_barrier()
; template <int EPI> ...
;     ...
;     LDA(At, 0, 1); WAIT_V(4); BAR; WAIT_L(0); MMA(1, 0, At, B0); MMA(1, 1, At, B1); BAR; }
;   { LDB(B0, 1, 0); LDA(At, 1, 0); WAIT_V(2); BAR; WAIT_L(0); MMA(0, 0, At, B0); BAR;
	s_setprio 0
	s_nop 1
	ds_read_b128 v[64:67], v154 offset:16384
	ds_read_b128 v[68:71], v154 offset:17408
	ds_read_b128 v[80:83], v153 offset:16384
	ds_read_b128 v[84:87], v153 offset:17408
	ds_read_b128 v[186:189], v152 offset:16384
	ds_read_b128 v[190:193], v152 offset:17408
	ds_read_b128 v[194:197], v151 offset:16384
	ds_read_b128 v[198:201], v151 offset:17408
	s_waitcnt vmcnt(4)
	s_setprio 1
	s_barrier
	s_waitcnt lgkmcnt(0)
	v_mfma_f32_16x16x32_bf16 v[60:63], v[64:67], v[128:131], v[60:63]
	v_mfma_f32_16x16x32_bf16 v[52:55], v[80:83], v[128:131], v[52:55]
	v_mfma_f32_16x16x32_bf16 v[44:47], v[186:189], v[128:131], v[44:47]
	v_mfma_f32_16x16x32_bf16 v[36:39], v[194:197], v[128:131], v[36:39]
	v_mfma_f32_16x16x32_bf16 v[60:63], v[68:71], v[142:145], v[60:63]
	v_mfma_f32_16x16x32_bf16 v[56:59], v[64:67], v[158:161], v[56:59]
	v_mfma_f32_16x16x32_bf16 v[52:55], v[84:87], v[142:145], v[52:55]
	v_mfma_f32_16x16x32_bf16 v[48:51], v[80:83], v[158:161], v[48:51]
	v_mfma_f32_16x16x32_bf16 v[44:47], v[190:193], v[142:145], v[44:47]
	v_mfma_f32_16x16x32_bf16 v[40:43], v[186:189], v[158:161], v[40:43]
	v_mfma_f32_16x16x32_bf16 v[36:39], v[198:201], v[142:145], v[36:39]
	v_mfma_f32_16x16x32_bf16 v[32:35], v[194:197], v[158:161], v[32:35]
	v_mfma_f32_16x16x32_bf16 v[202:205], v[68:71], v[162:165], v[56:59]
	v_mfma_f32_16x16x32_bf16 v[220:223], v[84:87], v[162:165], v[48:51]
	v_mfma_f32_16x16x32_bf16 v[224:227], v[190:193], v[162:165], v[40:43]
	v_mfma_f32_16x16x32_bf16 v[128:131], v[198:201], v[162:165], v[32:35]
	s_setprio 0
	s_setprio 1
	v_mfma_f32_16x16x32_bf16 v[28:31], v[64:67], v[96:99], v[28:31]
	v_mfma_f32_16x16x32_bf16 v[20:23], v[80:83], v[96:99], v[20:23]
	v_mfma_f32_16x16x32_bf16 v[12:15], v[186:189], v[96:99], v[12:15]
	v_mfma_f32_16x16x32_bf16 v[4:7], v[194:197], v[96:99], v[4:7]
	v_mfma_f32_16x16x32_bf16 v[28:31], v[68:71], v[100:103], v[28:31]
	v_mfma_f32_16x16x32_bf16 v[24:27], v[64:67], v[112:115], v[24:27]
	v_mfma_f32_16x16x32_bf16 v[20:23], v[84:87], v[100:103], v[20:23]
	v_mfma_f32_16x16x32_bf16 v[16:19], v[80:83], v[112:115], v[16:19]
	v_mfma_f32_16x16x32_bf16 v[12:15], v[190:193], v[100:103], v[12:15]
	v_mfma_f32_16x16x32_bf16 v[8:11], v[186:189], v[112:115], v[8:11]
	v_mfma_f32_16x16x32_bf16 v[4:7], v[198:201], v[100:103], v[4:7]
	v_mfma_f32_16x16x32_bf16 v[0:3], v[194:197], v[112:115], v[0:3]
	v_mfma_f32_16x16x32_bf16 v[142:145], v[68:71], v[116:119], v[24:27]
	v_mfma_f32_16x16x32_bf16 v[158:161], v[84:87], v[116:119], v[16:19]
	v_mfma_f32_16x16x32_bf16 v[162:165], v[190:193], v[116:119], v[8:11]
	v_mfma_f32_16x16x32_bf16 v[186:189], v[198:201], v[116:119], v[0:3]
	s_barrier
	s_setprio 0
	s_nop 1
	ds_read_b128 v[0:3], v157
	ds_read_b128 v[8:11], v157 offset:1024
	ds_read_b128 v[190:193], v157 offset:2048
	ds_read_b128 v[194:197], v157 offset:3072
	ds_read_b128 v[16:19], v154 offset:32768
	ds_read_b128 v[24:27], v154 offset:33792
	ds_read_b128 v[32:35], v153 offset:32768
	ds_read_b128 v[40:43], v153 offset:33792
	ds_read_b128 v[48:51], v152 offset:32768
	ds_read_b128 v[56:59], v152 offset:33792
	ds_read_b128 v[198:201], v151 offset:32768
	ds_read_b128 v[228:231], v151 offset:33792
	s_waitcnt vmcnt(2)
	s_setprio 1
	s_barrier
	s_waitcnt lgkmcnt(0)
	v_mfma_f32_16x16x32_bf16 v[64:67], v[16:19], v[0:3], v[124:127]
	v_mfma_f32_16x16x32_bf16 v[116:119], v[24:27], v[8:11], v[64:67]
	v_mfma_f32_16x16x32_bf16 v[64:67], v[16:19], v[190:193], v[120:123]
	v_mfma_f32_16x16x32_bf16 v[112:115], v[24:27], v[194:197], v[64:67]
	v_mfma_f32_16x16x32_bf16 v[64:67], v[32:35], v[0:3], v[170:173]
	v_mfma_f32_16x16x32_bf16 v[100:103], v[40:43], v[8:11], v[64:67]
	v_mfma_f32_16x16x32_bf16 v[64:67], v[32:35], v[190:193], v[208:211]
	v_mfma_f32_16x16x32_bf16 v[96:99], v[40:43], v[194:197], v[64:67]
	v_mfma_f32_16x16x32_bf16 v[64:67], v[48:51], v[0:3], v[108:111]
	v_mfma_f32_16x16x32_bf16 v[84:87], v[56:59], v[8:11], v[64:67]
	v_mfma_f32_16x16x32_bf16 v[64:67], v[48:51], v[190:193], v[104:107]
	v_mfma_f32_16x16x32_bf16 v[80:83], v[56:59], v[194:197], v[64:67]
	v_mfma_f32_16x16x32_bf16 v[64:67], v[198:201], v[0:3], v[212:215]
	v_mfma_f32_16x16x32_bf16 v[68:71], v[228:231], v[8:11], v[64:67]
	v_mfma_f32_16x16x32_bf16 v[64:67], v[198:201], v[190:193], v[216:219]
	v_mfma_f32_16x16x32_bf16 v[64:67], v[228:231], v[194:197], v[64:67]
	s_barrier
; #define LDA(dst, b, h) for (int m = 0; m < 4; ++m) for (int k = 0; k < 2; ++k) \
;     dst[m][k] = *reinterpret_cast<const bf16x8*>((char*)SA(b, h) + lds_byte(wr * 64 + m * 16 + fr, k * 32 + fq * 8))
; #define LDB(dst, b, h) for (int n = 0; n < 2; ++n) for (int k = 0; k < 2; ++k) \
;     dst[n][k] = *reinterpret_cast<const bf16x8*>((char*)SB(b, h) + lds_byte(wc * 32 + n * 16 + fr, k * 32 + fq * 8))
; #define MMA(ai, bj, At, Bt) do { __builtin_amdgcn_s_setprio(1); \
;     for (int m = 0; m < 4; ++m) for (int n = 0; n < 2; ++n) for (int k = 0; k < 2; ++k) \
;       acc[ai][bj][m][n] = __builtin_amdgcn_mfma_f32_16x16x32_bf16(At[m][k], Bt[n][k], acc[ai][bj][m][n], 0, 0, 0); \
;     __builtin_amdgcn_s_setprio(0); } while (0)
; #define WAIT_V(n) asm volatile("s_waitcnt vmcnt(" #n ")" ::: "memory")
; #define WAIT_L(n) asm volatile("s_waitcnt lgkmcnt(" #n ")" ::: "memory")
; #define BAR __builtin_amdgcn_s_barrier()
; template <int EPI> ...
;     ...
;   { LDB(B0, 1, 0); LDA(At, 1, 0); WAIT_V(2); BAR; WAIT_L(0); MMA(0, 0, At, B0); BAR;
;     LDB(B1, 1, 1); WAIT_V(0); BAR; WAIT_L(0); MMA(0, 1, At, B1); BAR;
;     LDA(At, 1, 1); BAR; WAIT_L(0); MMA(1, 0, At, B0); MMA(1, 1, At, B1); BAR; }
;   if (wr == 0) BAR;
	s_setprio 0
	ds_read_b128 v[170:173], v155
	ds_read_b128 v[206:209], v155 offset:1024
	ds_read_b128 v[210:213], v155 offset:2048
	ds_read_b128 v[214:217], v155 offset:3072
	s_waitcnt vmcnt(0)
	s_setprio 1
	s_barrier
	s_waitcnt lgkmcnt(0)
	v_mfma_f32_16x16x32_bf16 v[92:95], v[16:19], v[170:173], v[92:95]
	v_mfma_f32_16x16x32_bf16 v[16:19], v[16:19], v[210:213], v[88:91]
	v_mfma_f32_16x16x32_bf16 v[120:123], v[24:27], v[214:217], v[16:19]
	v_mfma_f32_16x16x32_bf16 v[16:19], v[32:35], v[170:173], v[166:169]
	v_mfma_f32_16x16x32_bf16 v[108:111], v[40:43], v[206:209], v[16:19]
	v_mfma_f32_16x16x32_bf16 v[16:19], v[32:35], v[210:213], v[174:177]
	v_mfma_f32_16x16x32_bf16 v[104:107], v[40:43], v[214:217], v[16:19]
	v_mfma_f32_16x16x32_bf16 v[16:19], v[48:51], v[170:173], v[76:79]
	v_mfma_f32_16x16x32_bf16 v[124:127], v[24:27], v[206:209], v[92:95]
	v_mfma_f32_16x16x32_bf16 v[92:95], v[56:59], v[206:209], v[16:19]
	v_mfma_f32_16x16x32_bf16 v[16:19], v[48:51], v[210:213], v[72:75]
	v_mfma_f32_16x16x32_bf16 v[88:91], v[56:59], v[214:217], v[16:19]
	v_mfma_f32_16x16x32_bf16 v[16:19], v[198:201], v[170:173], v[178:181]
	v_mfma_f32_16x16x32_bf16 v[76:79], v[228:231], v[206:209], v[16:19]
	v_mfma_f32_16x16x32_bf16 v[16:19], v[198:201], v[210:213], v[182:185]
	v_mfma_f32_16x16x32_bf16 v[72:75], v[228:231], v[214:217], v[16:19]
	s_barrier
	s_setprio 0
	ds_read_b128 v[166:169], v154 offset:49152
	ds_read_b128 v[154:157], v154 offset:50176
	ds_read_b128 v[174:177], v153 offset:49152
	ds_read_b128 v[178:181], v153 offset:50176
	ds_read_b128 v[182:185], v152 offset:49152
	ds_read_b128 v[198:201], v152 offset:50176
	ds_read_b128 v[228:231], v151 offset:49152
	ds_read_b128 v[232:235], v151 offset:50176
	s_setprio 1
	s_barrier
	s_waitcnt lgkmcnt(0)
	v_mfma_f32_16x16x32_bf16 v[16:19], v[166:169], v[0:3], v[60:63]
	v_mfma_f32_16x16x32_bf16 v[56:59], v[154:157], v[8:11], v[16:19]
	v_mfma_f32_16x16x32_bf16 v[16:19], v[166:169], v[190:193], v[202:205]
	v_mfma_f32_16x16x32_bf16 v[48:51], v[154:157], v[194:197], v[16:19]
	v_mfma_f32_16x16x32_bf16 v[16:19], v[174:177], v[0:3], v[52:55]
	v_mfma_f32_16x16x32_bf16 v[40:43], v[178:181], v[8:11], v[16:19]
	v_mfma_f32_16x16x32_bf16 v[16:19], v[174:177], v[190:193], v[220:223]
	v_mfma_f32_16x16x32_bf16 v[32:35], v[178:181], v[194:197], v[16:19]
	v_mfma_f32_16x16x32_bf16 v[16:19], v[182:185], v[0:3], v[44:47]
	v_mfma_f32_16x16x32_bf16 v[0:3], v[228:231], v[0:3], v[36:39]
	v_mfma_f32_16x16x32_bf16 v[24:27], v[198:201], v[8:11], v[16:19]
	v_mfma_f32_16x16x32_bf16 v[16:19], v[182:185], v[190:193], v[224:227]
	v_mfma_f32_16x16x32_bf16 v[8:11], v[232:235], v[8:11], v[0:3]
	v_mfma_f32_16x16x32_bf16 v[0:3], v[228:231], v[190:193], v[128:131]
	v_mfma_f32_16x16x32_bf16 v[16:19], v[198:201], v[194:197], v[16:19]
	v_mfma_f32_16x16x32_bf16 v[0:3], v[232:235], v[194:197], v[0:3]
	s_setprio 0
	s_setprio 1
	v_mfma_f32_16x16x32_bf16 v[28:31], v[166:169], v[170:173], v[28:31]
	v_mfma_f32_16x16x32_bf16 v[60:63], v[154:157], v[206:209], v[28:31]
	v_mfma_f32_16x16x32_bf16 v[28:31], v[166:169], v[210:213], v[142:145]
	v_mfma_f32_16x16x32_bf16 v[20:23], v[174:177], v[170:173], v[20:23]
	v_mfma_f32_16x16x32_bf16 v[12:15], v[182:185], v[170:173], v[12:15]
	v_mfma_f32_16x16x32_bf16 v[52:55], v[154:157], v[214:217], v[28:31]
	v_mfma_f32_16x16x32_bf16 v[44:47], v[178:181], v[206:209], v[20:23]
	v_mfma_f32_16x16x32_bf16 v[20:23], v[174:177], v[210:213], v[158:161]
	v_mfma_f32_16x16x32_bf16 v[28:31], v[198:201], v[206:209], v[12:15]
	v_mfma_f32_16x16x32_bf16 v[12:15], v[182:185], v[210:213], v[162:165]
	v_mfma_f32_16x16x32_bf16 v[4:7], v[228:231], v[170:173], v[4:7]
	v_mfma_f32_16x16x32_bf16 v[36:39], v[178:181], v[214:217], v[20:23]
	v_mfma_f32_16x16x32_bf16 v[20:23], v[198:201], v[214:217], v[12:15]
	v_mfma_f32_16x16x32_bf16 v[12:15], v[232:235], v[206:209], v[4:7]
	v_mfma_f32_16x16x32_bf16 v[4:7], v[228:231], v[210:213], v[186:189]
	v_mfma_f32_16x16x32_bf16 v[4:7], v[232:235], v[214:217], v[4:7]
	s_barrier
	s_setprio 0
	v_cmp_gt_u32_e32 vcc, s50, v136
	s_and_saveexec_b64 s[28:29], vcc
	s_cbranch_execz .LBB0_1719
	s_barrier

; #define STAGE(P, BASE, kt) do { const char* _g = (const char*)(BASE) + (size_t)((kt) * (BK * 2)); \
;     __builtin_amdgcn_global_load_lds((const unsigned*)(_g + (size_t)goff0), (unsigned*)((char*)(P) + tid_ * 16), 16, 0, 0); \
;     __builtin_amdgcn_global_load_lds((const unsigned*)(_g + (size_t)goff1), (unsigned*)((char*)(P) + tid_ * 16 + 8192), 16, 0, 0); } while (0)
; #define STAGEA(P, BASE, kt) do { const char* _g = (const char*)(BASE) + (size_t)((kt) * a_kbytes); \
;     __builtin_amdgcn_global_load_lds((const unsigned*)(_g + (size_t)goffA0), (unsigned*)((char*)(P) + tid_ * 16), 16, 0, 0); \
;     __builtin_amdgcn_global_load_lds((const unsigned*)(_g + (size_t)goffA1), (unsigned*)((char*)(P) + tid_ * 16 + 8192), 16, 0, 0); } while (0)
; #define LDA(dst, b, h) for (int m = 0; m < 4; ++m) for (int k = 0; k < 2; ++k) \
;     dst[m][k] = *reinterpret_cast<const bf16x8*>((char*)SA(b, h) + lds_byte(wr * 64 + m * 16 + fr, k * 32 + fq * 8))
; #define LDB(dst, b, h) for (int n = 0; n < 2; ++n) for (int k = 0; k < 2; ++k) \
;     dst[n][k] = *reinterpret_cast<const bf16x8*>((char*)SB(b, h) + lds_byte(wc * 32 + n * 16 + fr, k * 32 + fq * 8))
; #define MMA(ai, bj, At, Bt) do { __builtin_amdgcn_s_setprio(1); \
;     for (int m = 0; m < 4; ++m) for (int n = 0; n < 2; ++n) for (int k = 0; k < 2; ++k) \
;       acc[ai][bj][m][n] = __builtin_amdgcn_mfma_f32_16x16x32_bf16(At[m][k], Bt[n][k], acc[ai][bj][m][n], 0, 0, 0); \
;     __builtin_amdgcn_s_setprio(0); } while (0)
; #define WAIT_L(n) asm volatile("s_waitcnt lgkmcnt(" #n ")" ::: "memory")
; #define BAR __builtin_amdgcn_s_barrier()
; #define SCHED __builtin_amdgcn_sched_barrier(0)
; template <int EPI> ...
;     ...
;     LDB(B0, 0, 0); SCHED; LDA(At, 0, 0); STAGEA(SA(1, 1), A1, t + 1);
;     WAIT_L(8); BAR; WAIT_L(0); MMA(0, 0, At, B0); BAR; SCHED;
;     LDB(B1, 0, 1); STAGE(SB(0, 0), B0p, t + 2);
;     BAR; WAIT_L(0); MMA(0, 1, At, B1); BAR;
;     LDA(At, 0, 1); STAGEA(SA(0, 0), A0, t + 2);
;     BAR; WAIT_L(0); MMA(1, 0, At, B0); BAR; SCHED;
.LBB0_1738:
	ds_read_b128 v[174:177], v171
	ds_read_b128 v[178:181], v171 offset:1024
	ds_read_b128 v[182:185], v171 offset:2048
	ds_read_b128 v[186:189], v171 offset:3072
	v_add_u32_e32 v172, 0xc000, v158
	v_lshl_add_u64 v[238:239], s[26:27], 0, v[136:137]
	v_readfirstlane_b32 s51, v172
	v_add_u32_e32 v173, 0xe000, v158
	v_lshl_add_u64 v[222:223], v[238:239], 0, s[4:5]
	s_mov_b32 m0, s51
	v_lshl_add_u64 v[240:241], s[26:27], 0, v[138:139]
	v_readfirstlane_b32 s51, v173
	ds_read_b128 v[190:193], v153
	ds_read_b128 v[194:197], v153 offset:1024
	ds_read_b128 v[198:201], v152
	ds_read_b128 v[202:205], v152 offset:1024
	ds_read_b128 v[206:209], v151
	ds_read_b128 v[210:213], v151 offset:1024
	ds_read_b128 v[214:217], v150
	ds_read_b128 v[218:221], v150 offset:1024
	global_load_lds_dwordx4 v[222:223], off
	v_lshl_add_u64 v[222:223], v[240:241], 0, s[4:5]
	s_mov_b32 m0, s51
	s_nop 0
	global_load_lds_dwordx4 v[222:223], off
	s_waitcnt lgkmcnt(8)
	s_setprio 1
	s_barrier
	s_waitcnt lgkmcnt(0)
	v_mfma_f32_16x16x32_bf16 v[124:127], v[190:193], v[174:177], v[124:127]
	v_mfma_f32_16x16x32_bf16 v[120:123], v[190:193], v[182:185], v[120:123]
	v_mfma_f32_16x16x32_bf16 v[116:119], v[198:201], v[174:177], v[116:119]
	v_mfma_f32_16x16x32_bf16 v[112:115], v[198:201], v[182:185], v[112:115]
	v_mfma_f32_16x16x32_bf16 v[108:111], v[206:209], v[174:177], v[108:111]
	v_mfma_f32_16x16x32_bf16 v[104:107], v[206:209], v[182:185], v[104:107]
	v_mfma_f32_16x16x32_bf16 v[100:103], v[214:217], v[174:177], v[100:103]
	v_mfma_f32_16x16x32_bf16 v[96:99], v[214:217], v[182:185], v[96:99]
	v_mfma_f32_16x16x32_bf16 v[124:127], v[194:197], v[178:181], v[124:127]
	v_mfma_f32_16x16x32_bf16 v[120:123], v[194:197], v[186:189], v[120:123]
	v_mfma_f32_16x16x32_bf16 v[116:119], v[202:205], v[178:181], v[116:119]
	v_mfma_f32_16x16x32_bf16 v[112:115], v[202:205], v[186:189], v[112:115]
	v_mfma_f32_16x16x32_bf16 v[108:111], v[210:213], v[178:181], v[108:111]
	v_mfma_f32_16x16x32_bf16 v[104:107], v[210:213], v[186:189], v[104:107]
	v_mfma_f32_16x16x32_bf16 v[100:103], v[218:221], v[178:181], v[100:103]
	v_mfma_f32_16x16x32_bf16 v[96:99], v[218:221], v[186:189], v[96:99]
	s_barrier
	s_setprio 0
	v_lshl_add_u64 v[242:243], s[24:25], 0, v[140:141]
	v_readfirstlane_b32 s51, v155
	v_lshl_add_u64 v[244:245], v[242:243], 0, s[6:7]
	s_mov_b32 m0, s51
	ds_read_b128 v[222:225], v167
	ds_read_b128 v[226:229], v167 offset:1024
	ds_read_b128 v[230:233], v167 offset:2048
	ds_read_b128 v[234:237], v167 offset:3072
	global_load_lds_dwordx4 v[244:245], off
	v_lshl_add_u64 v[244:245], s[24:25], 0, v[142:143]
	v_readfirstlane_b32 s51, v157
	v_lshl_add_u64 v[246:247], v[244:245], 0, s[6:7]
	s_mov_b32 m0, s51
	s_nop 0
	global_load_lds_dwordx4 v[246:247], off
	s_setprio 1
	s_barrier
	s_waitcnt lgkmcnt(0)
	v_mfma_f32_16x16x32_bf16 v[92:95], v[190:193], v[222:225], v[92:95]
	v_mfma_f32_16x16x32_bf16 v[88:91], v[190:193], v[230:233], v[88:91]
	v_mfma_f32_16x16x32_bf16 v[84:87], v[198:201], v[222:225], v[84:87]
	v_mfma_f32_16x16x32_bf16 v[80:83], v[198:201], v[230:233], v[80:83]
	v_mfma_f32_16x16x32_bf16 v[76:79], v[206:209], v[222:225], v[76:79]
	v_mfma_f32_16x16x32_bf16 v[72:75], v[206:209], v[230:233], v[72:75]
	v_mfma_f32_16x16x32_bf16 v[68:71], v[214:217], v[222:225], v[68:71]
	v_mfma_f32_16x16x32_bf16 v[64:67], v[214:217], v[230:233], v[64:67]
	v_mfma_f32_16x16x32_bf16 v[92:95], v[194:197], v[226:229], v[92:95]
	v_mfma_f32_16x16x32_bf16 v[88:91], v[194:197], v[234:237], v[88:91]
	v_mfma_f32_16x16x32_bf16 v[84:87], v[202:205], v[226:229], v[84:87]
	v_mfma_f32_16x16x32_bf16 v[80:83], v[202:205], v[234:237], v[80:83]
	v_mfma_f32_16x16x32_bf16 v[76:79], v[210:213], v[226:229], v[76:79]
	v_mfma_f32_16x16x32_bf16 v[72:75], v[210:213], v[234:237], v[72:75]
	v_mfma_f32_16x16x32_bf16 v[68:71], v[218:221], v[226:229], v[68:71]
	v_mfma_f32_16x16x32_bf16 v[64:67], v[218:221], v[234:237], v[64:67]
	s_barrier
	s_setprio 0
	v_readfirstlane_b32 s51, v158
	v_lshl_add_u64 v[246:247], v[238:239], 0, s[8:9]
	s_mov_b32 m0, s51
	v_readfirstlane_b32 s51, v159
	ds_read_b128 v[190:193], v153 offset:16384
	ds_read_b128 v[194:197], v153 offset:17408
	ds_read_b128 v[198:201], v152 offset:16384
	ds_read_b128 v[202:205], v152 offset:17408
	ds_read_b128 v[206:209], v151 offset:16384
	ds_read_b128 v[210:213], v151 offset:17408
	ds_read_b128 v[214:217], v150 offset:16384
	ds_read_b128 v[218:221], v150 offset:17408
	global_load_lds_dwordx4 v[246:247], off
	v_lshl_add_u64 v[246:247], v[240:241], 0, s[8:9]
	s_mov_b32 m0, s51
	s_nop 0
	global_load_lds_dwordx4 v[246:247], off
	s_setprio 1
	s_barrier
	s_waitcnt lgkmcnt(0)
	v_mfma_f32_16x16x32_bf16 v[60:63], v[190:193], v[174:177], v[60:63]
	v_mfma_f32_16x16x32_bf16 v[56:59], v[190:193], v[182:185], v[56:59]
	v_mfma_f32_16x16x32_bf16 v[52:55], v[198:201], v[174:177], v[52:55]
	v_mfma_f32_16x16x32_bf16 v[48:51], v[198:201], v[182:185], v[48:51]
	v_mfma_f32_16x16x32_bf16 v[44:47], v[206:209], v[174:177], v[44:47]
	v_mfma_f32_16x16x32_bf16 v[40:43], v[206:209], v[182:185], v[40:43]
	v_mfma_f32_16x16x32_bf16 v[36:39], v[214:217], v[174:177], v[36:39]
	v_mfma_f32_16x16x32_bf16 v[32:35], v[214:217], v[182:185], v[32:35]
	v_mfma_f32_16x16x32_bf16 v[60:63], v[194:197], v[178:181], v[60:63]
	v_mfma_f32_16x16x32_bf16 v[56:59], v[194:197], v[186:189], v[56:59]
	v_mfma_f32_16x16x32_bf16 v[52:55], v[202:205], v[178:181], v[52:55]
	v_mfma_f32_16x16x32_bf16 v[48:51], v[202:205], v[186:189], v[48:51]
	v_mfma_f32_16x16x32_bf16 v[44:47], v[210:213], v[178:181], v[44:47]
	v_mfma_f32_16x16x32_bf16 v[40:43], v[210:213], v[186:189], v[40:43]
	v_mfma_f32_16x16x32_bf16 v[36:39], v[218:221], v[178:181], v[36:39]
	v_mfma_f32_16x16x32_bf16 v[32:35], v[218:221], v[186:189], v[32:35]
	s_barrier
; #define STAGE(P, BASE, kt) do { const char* _g = (const char*)(BASE) + (size_t)((kt) * (BK * 2)); \
;     __builtin_amdgcn_global_load_lds((const unsigned*)(_g + (size_t)goff0), (unsigned*)((char*)(P) + tid_ * 16), 16, 0, 0); \
;     __builtin_amdgcn_global_load_lds((const unsigned*)(_g + (size_t)goff1), (unsigned*)((char*)(P) + tid_ * 16 + 8192), 16, 0, 0); } while (0)
; #define STAGEA(P, BASE, kt) do { const char* _g = (const char*)(BASE) + (size_t)((kt) * a_kbytes); \
;     __builtin_amdgcn_global_load_lds((const unsigned*)(_g + (size_t)goffA0), (unsigned*)((char*)(P) + tid_ * 16), 16, 0, 0); \
;     __builtin_amdgcn_global_load_lds((const unsigned*)(_g + (size_t)goffA1), (unsigned*)((char*)(P) + tid_ * 16 + 8192), 16, 0, 0); } while (0)
; #define LDA(dst, b, h) for (int m = 0; m < 4; ++m) for (int k = 0; k < 2; ++k) \
;     dst[m][k] = *reinterpret_cast<const bf16x8*>((char*)SA(b, h) + lds_byte(wr * 64 + m * 16 + fr, k * 32 + fq * 8))
; #define LDB(dst, b, h) for (int n = 0; n < 2; ++n) for (int k = 0; k < 2; ++k) \
;     dst[n][k] = *reinterpret_cast<const bf16x8*>((char*)SB(b, h) + lds_byte(wc * 32 + n * 16 + fr, k * 32 + fq * 8))
; #define MMA(ai, bj, At, Bt) do { __builtin_amdgcn_s_setprio(1); \
;     for (int m = 0; m < 4; ++m) for (int n = 0; n < 2; ++n) for (int k = 0; k < 2; ++k) \
;       acc[ai][bj][m][n] = __builtin_amdgcn_mfma_f32_16x16x32_bf16(At[m][k], Bt[n][k], acc[ai][bj][m][n], 0, 0, 0); \
;     __builtin_amdgcn_s_setprio(0); } while (0)
; #define WAIT_V(n) asm volatile("s_waitcnt vmcnt(" #n ")" ::: "memory")
; #define WAIT_L(n) asm volatile("s_waitcnt lgkmcnt(" #n ")" ::: "memory")
; #define BAR __builtin_amdgcn_s_barrier()
; #define SCHED __builtin_amdgcn_sched_barrier(0)
; template <int EPI> ...
;     ...
;     STAGE(SB(0, 1), B1p, t + 2);
;     WAIT_V(6); BAR; MMA(1, 1, At, B1); BAR;
;     LDB(B0, 1, 0); SCHED; LDA(At, 1, 0); STAGEA(SA(0, 1), A1, t + 2);
;     WAIT_L(8); BAR; WAIT_L(0); MMA(0, 0, At, B0); BAR; SCHED;
;     LDB(B1, 1, 1); STAGE(SB(1, 0), B0p, t + 3);
;     BAR; WAIT_L(0); MMA(0, 1, At, B1); BAR;
;     LDA(At, 1, 1); STAGEA(SA(1, 0), A0, t + 3);
;     BAR; WAIT_L(0); MMA(1, 0, At, B0); BAR; SCHED;
	s_setprio 0
	v_readfirstlane_b32 s51, v160
	v_lshl_add_u64 v[174:175], v[242:243], 0, s[10:11]
	s_mov_b32 m0, s51
	v_readfirstlane_b32 s51, v161
	global_load_lds_dwordx4 v[174:175], off
	v_lshl_add_u64 v[174:175], v[244:245], 0, s[10:11]
	s_mov_b32 m0, s51
	s_nop 0
	global_load_lds_dwordx4 v[174:175], off
	s_waitcnt vmcnt(6)
	s_setprio 1
	s_barrier
	v_mfma_f32_16x16x32_bf16 v[28:31], v[190:193], v[222:225], v[28:31]
	v_mfma_f32_16x16x32_bf16 v[24:27], v[190:193], v[230:233], v[24:27]
	v_mfma_f32_16x16x32_bf16 v[20:23], v[198:201], v[222:225], v[20:23]
	v_mfma_f32_16x16x32_bf16 v[16:19], v[198:201], v[230:233], v[16:19]
	v_mfma_f32_16x16x32_bf16 v[12:15], v[206:209], v[222:225], v[12:15]
	v_mfma_f32_16x16x32_bf16 v[8:11], v[206:209], v[230:233], v[8:11]
	v_mfma_f32_16x16x32_bf16 v[4:7], v[214:217], v[222:225], v[4:7]
	v_mfma_f32_16x16x32_bf16 v[0:3], v[214:217], v[230:233], v[0:3]
	v_mfma_f32_16x16x32_bf16 v[28:31], v[194:197], v[226:229], v[28:31]
	v_mfma_f32_16x16x32_bf16 v[24:27], v[194:197], v[234:237], v[24:27]
	v_mfma_f32_16x16x32_bf16 v[20:23], v[202:205], v[226:229], v[20:23]
	v_mfma_f32_16x16x32_bf16 v[16:19], v[202:205], v[234:237], v[16:19]
	v_mfma_f32_16x16x32_bf16 v[12:15], v[210:213], v[226:229], v[12:15]
	v_mfma_f32_16x16x32_bf16 v[8:11], v[210:213], v[234:237], v[8:11]
	v_mfma_f32_16x16x32_bf16 v[4:7], v[218:221], v[226:229], v[4:7]
	v_mfma_f32_16x16x32_bf16 v[0:3], v[218:221], v[234:237], v[0:3]
	s_barrier
	s_setprio 0
	ds_read_b128 v[174:177], v156
	ds_read_b128 v[178:181], v156 offset:1024
	ds_read_b128 v[182:185], v156 offset:2048
	ds_read_b128 v[186:189], v156 offset:3072
	v_readfirstlane_b32 s51, v162
	v_lshl_add_u64 v[222:223], v[238:239], 0, s[12:13]
	s_mov_b32 m0, s51
	v_readfirstlane_b32 s51, v163
	ds_read_b128 v[190:193], v153 offset:32768
	ds_read_b128 v[194:197], v153 offset:33792
	ds_read_b128 v[198:201], v152 offset:32768
	ds_read_b128 v[202:205], v152 offset:33792
	ds_read_b128 v[206:209], v151 offset:32768
	ds_read_b128 v[210:213], v151 offset:33792
	ds_read_b128 v[214:217], v150 offset:32768
	ds_read_b128 v[218:221], v150 offset:33792
	global_load_lds_dwordx4 v[222:223], off
	v_lshl_add_u64 v[222:223], v[240:241], 0, s[12:13]
	s_mov_b32 m0, s51
	s_nop 0
	global_load_lds_dwordx4 v[222:223], off
	s_waitcnt lgkmcnt(8)
	s_setprio 1
	s_barrier
	s_waitcnt lgkmcnt(0)
	v_mfma_f32_16x16x32_bf16 v[124:127], v[190:193], v[174:177], v[124:127]
	v_mfma_f32_16x16x32_bf16 v[120:123], v[190:193], v[182:185], v[120:123]
	v_mfma_f32_16x16x32_bf16 v[116:119], v[198:201], v[174:177], v[116:119]
	v_mfma_f32_16x16x32_bf16 v[112:115], v[198:201], v[182:185], v[112:115]
	v_mfma_f32_16x16x32_bf16 v[108:111], v[206:209], v[174:177], v[108:111]
	v_mfma_f32_16x16x32_bf16 v[104:107], v[206:209], v[182:185], v[104:107]
	v_mfma_f32_16x16x32_bf16 v[100:103], v[214:217], v[174:177], v[100:103]
	v_mfma_f32_16x16x32_bf16 v[96:99], v[214:217], v[182:185], v[96:99]
	v_mfma_f32_16x16x32_bf16 v[124:127], v[194:197], v[178:181], v[124:127]
	v_mfma_f32_16x16x32_bf16 v[120:123], v[194:197], v[186:189], v[120:123]
	v_mfma_f32_16x16x32_bf16 v[116:119], v[202:205], v[178:181], v[116:119]
	v_mfma_f32_16x16x32_bf16 v[112:115], v[202:205], v[186:189], v[112:115]
	v_mfma_f32_16x16x32_bf16 v[108:111], v[210:213], v[178:181], v[108:111]
	v_mfma_f32_16x16x32_bf16 v[104:107], v[210:213], v[186:189], v[104:107]
	v_mfma_f32_16x16x32_bf16 v[100:103], v[218:221], v[178:181], v[100:103]
	v_mfma_f32_16x16x32_bf16 v[96:99], v[218:221], v[186:189], v[96:99]
	s_barrier
	s_setprio 0
	v_readfirstlane_b32 s51, v164
	v_lshl_add_u64 v[246:247], v[242:243], 0, s[14:15]
	s_mov_b32 m0, s51
	v_readfirstlane_b32 s51, v165
	ds_read_b128 v[222:225], v154
	ds_read_b128 v[226:229], v154 offset:1024
	ds_read_b128 v[230:233], v154 offset:2048
	ds_read_b128 v[234:237], v154 offset:3072
	global_load_lds_dwordx4 v[246:247], off
	v_lshl_add_u64 v[246:247], v[244:245], 0, s[14:15]
	s_mov_b32 m0, s51
	s_nop 0
	global_load_lds_dwordx4 v[246:247], off
	s_setprio 1
	s_barrier
	s_waitcnt lgkmcnt(0)
	v_mfma_f32_16x16x32_bf16 v[92:95], v[190:193], v[222:225], v[92:95]
	v_mfma_f32_16x16x32_bf16 v[88:91], v[190:193], v[230:233], v[88:91]
	v_mfma_f32_16x16x32_bf16 v[84:87], v[198:201], v[222:225], v[84:87]
	v_mfma_f32_16x16x32_bf16 v[80:83], v[198:201], v[230:233], v[80:83]
	v_mfma_f32_16x16x32_bf16 v[76:79], v[206:209], v[222:225], v[76:79]
	v_mfma_f32_16x16x32_bf16 v[72:75], v[206:209], v[230:233], v[72:75]
	v_mfma_f32_16x16x32_bf16 v[68:71], v[214:217], v[222:225], v[68:71]
	v_mfma_f32_16x16x32_bf16 v[64:67], v[214:217], v[230:233], v[64:67]
	v_mfma_f32_16x16x32_bf16 v[92:95], v[194:197], v[226:229], v[92:95]
	v_mfma_f32_16x16x32_bf16 v[88:91], v[194:197], v[234:237], v[88:91]
	v_mfma_f32_16x16x32_bf16 v[84:87], v[202:205], v[226:229], v[84:87]
	v_mfma_f32_16x16x32_bf16 v[80:83], v[202:205], v[234:237], v[80:83]
	v_mfma_f32_16x16x32_bf16 v[76:79], v[210:213], v[226:229], v[76:79]
	v_mfma_f32_16x16x32_bf16 v[72:75], v[210:213], v[234:237], v[72:75]
	v_mfma_f32_16x16x32_bf16 v[68:71], v[218:221], v[226:229], v[68:71]
	v_mfma_f32_16x16x32_bf16 v[64:67], v[218:221], v[234:237], v[64:67]
	s_barrier
	s_setprio 0
	v_readfirstlane_b32 s51, v166
	v_lshl_add_u64 v[238:239], v[238:239], 0, s[16:17]
	s_mov_b32 m0, s51
	v_readfirstlane_b32 s51, v168
	ds_read_b128 v[190:193], v153 offset:49152
	ds_read_b128 v[194:197], v153 offset:50176
	ds_read_b128 v[198:201], v152 offset:49152
	ds_read_b128 v[202:205], v152 offset:50176
	ds_read_b128 v[206:209], v151 offset:49152
	ds_read_b128 v[210:213], v151 offset:50176
	ds_read_b128 v[214:217], v150 offset:49152
	ds_read_b128 v[218:221], v150 offset:50176
	global_load_lds_dwordx4 v[238:239], off
	v_lshl_add_u64 v[238:239], v[240:241], 0, s[16:17]
	s_mov_b32 m0, s51
	s_nop 0
	global_load_lds_dwordx4 v[238:239], off
	s_setprio 1
	s_barrier
; #define STAGE(P, BASE, kt) do { const char* _g = (const char*)(BASE) + (size_t)((kt) * (BK * 2)); \
;     __builtin_amdgcn_global_load_lds((const unsigned*)(_g + (size_t)goff0), (unsigned*)((char*)(P) + tid_ * 16), 16, 0, 0); \
;     __builtin_amdgcn_global_load_lds((const unsigned*)(_g + (size_t)goff1), (unsigned*)((char*)(P) + tid_ * 16 + 8192), 16, 0, 0); } while (0)
; #define STAGEA(P, BASE, kt) do { const char* _g = (const char*)(BASE) + (size_t)((kt) * a_kbytes); \
;     __builtin_amdgcn_global_load_lds((const unsigned*)(_g + (size_t)goffA0), (unsigned*)((char*)(P) + tid_ * 16), 16, 0, 0); \
;     __builtin_amdgcn_global_load_lds((const unsigned*)(_g + (size_t)goffA1), (unsigned*)((char*)(P) + tid_ * 16 + 8192), 16, 0, 0); } while (0)
; #define LDA(dst, b, h) for (int m = 0; m < 4; ++m) for (int k = 0; k < 2; ++k) \
;     dst[m][k] = *reinterpret_cast<const bf16x8*>((char*)SA(b, h) + lds_byte(wr * 64 + m * 16 + fr, k * 32 + fq * 8))
; #define LDB(dst, b, h) for (int n = 0; n < 2; ++n) for (int k = 0; k < 2; ++k) \
;     dst[n][k] = *reinterpret_cast<const bf16x8*>((char*)SB(b, h) + lds_byte(wc * 32 + n * 16 + fr, k * 32 + fq * 8))
; #define MMA(ai, bj, At, Bt) do { __builtin_amdgcn_s_setprio(1); \
;     for (int m = 0; m < 4; ++m) for (int n = 0; n < 2; ++n) for (int k = 0; k < 2; ++k) \
;       acc[ai][bj][m][n] = __builtin_amdgcn_mfma_f32_16x16x32_bf16(At[m][k], Bt[n][k], acc[ai][bj][m][n], 0, 0, 0); \
;     __builtin_amdgcn_s_setprio(0); } while (0)
; #define WAIT_V(n) asm volatile("s_waitcnt vmcnt(" #n ")" ::: "memory")
; #define WAIT_L(n) asm volatile("s_waitcnt lgkmcnt(" #n ")" ::: "memory")
; #define BAR __builtin_amdgcn_s_barrier()
; #define SCHED __builtin_amdgcn_sched_barrier(0)
; template <int EPI> ...
;     ...
;     BAR; WAIT_L(0); MMA(1, 0, At, B0); BAR; SCHED;
;     STAGE(SB(1, 1), B1p, t + 3);
;     WAIT_V(6); BAR; MMA(1, 1, At, B1); BAR;
;   }
;   { LDB(B0, 0, 0); LDA(At, 0, 0); STAGEA(SA(1, 1), A1, nt - 1);
;     BAR; WAIT_L(0); MMA(0, 0, At, B0); BAR;
;     LDB(B1, 0, 1); BAR; WAIT_L(0); MMA(0, 1, At, B1); BAR;
	s_waitcnt lgkmcnt(0)
	v_mfma_f32_16x16x32_bf16 v[60:63], v[190:193], v[174:177], v[60:63]
	v_mfma_f32_16x16x32_bf16 v[56:59], v[190:193], v[182:185], v[56:59]
	v_mfma_f32_16x16x32_bf16 v[52:55], v[198:201], v[174:177], v[52:55]
	v_mfma_f32_16x16x32_bf16 v[48:51], v[198:201], v[182:185], v[48:51]
	v_mfma_f32_16x16x32_bf16 v[44:47], v[206:209], v[174:177], v[44:47]
	v_mfma_f32_16x16x32_bf16 v[40:43], v[206:209], v[182:185], v[40:43]
	v_mfma_f32_16x16x32_bf16 v[36:39], v[214:217], v[174:177], v[36:39]
	v_mfma_f32_16x16x32_bf16 v[32:35], v[214:217], v[182:185], v[32:35]
	v_mfma_f32_16x16x32_bf16 v[60:63], v[194:197], v[178:181], v[60:63]
	v_mfma_f32_16x16x32_bf16 v[56:59], v[194:197], v[186:189], v[56:59]
	v_mfma_f32_16x16x32_bf16 v[52:55], v[202:205], v[178:181], v[52:55]
	v_mfma_f32_16x16x32_bf16 v[48:51], v[202:205], v[186:189], v[48:51]
	v_mfma_f32_16x16x32_bf16 v[44:47], v[210:213], v[178:181], v[44:47]
	v_mfma_f32_16x16x32_bf16 v[40:43], v[210:213], v[186:189], v[40:43]
	v_mfma_f32_16x16x32_bf16 v[36:39], v[218:221], v[178:181], v[36:39]
	v_mfma_f32_16x16x32_bf16 v[32:35], v[218:221], v[186:189], v[32:35]
	s_barrier
	s_setprio 0
	v_readfirstlane_b32 s51, v169
	v_lshl_add_u64 v[174:175], v[242:243], 0, s[18:19]
	s_mov_b32 m0, s51
	v_readfirstlane_b32 s51, v170
	global_load_lds_dwordx4 v[174:175], off
	v_lshl_add_u64 v[174:175], v[244:245], 0, s[18:19]
	s_mov_b32 m0, s51
	s_nop 0
	global_load_lds_dwordx4 v[174:175], off
	s_waitcnt vmcnt(6)
	s_setprio 1
	s_barrier
	v_mfma_f32_16x16x32_bf16 v[28:31], v[190:193], v[222:225], v[28:31]
	v_mfma_f32_16x16x32_bf16 v[24:27], v[190:193], v[230:233], v[24:27]
	v_mfma_f32_16x16x32_bf16 v[20:23], v[198:201], v[222:225], v[20:23]
	v_mfma_f32_16x16x32_bf16 v[16:19], v[198:201], v[230:233], v[16:19]
	v_mfma_f32_16x16x32_bf16 v[12:15], v[206:209], v[222:225], v[12:15]
	v_mfma_f32_16x16x32_bf16 v[8:11], v[206:209], v[230:233], v[8:11]
	v_mfma_f32_16x16x32_bf16 v[4:7], v[214:217], v[222:225], v[4:7]
	v_mfma_f32_16x16x32_bf16 v[0:3], v[214:217], v[230:233], v[0:3]
	v_mfma_f32_16x16x32_bf16 v[28:31], v[194:197], v[226:229], v[28:31]
	v_mfma_f32_16x16x32_bf16 v[24:27], v[194:197], v[234:237], v[24:27]
	v_mfma_f32_16x16x32_bf16 v[20:23], v[202:205], v[226:229], v[20:23]
	v_mfma_f32_16x16x32_bf16 v[16:19], v[202:205], v[234:237], v[16:19]
	v_mfma_f32_16x16x32_bf16 v[12:15], v[210:213], v[226:229], v[12:15]
	v_mfma_f32_16x16x32_bf16 v[8:11], v[210:213], v[234:237], v[8:11]
	v_mfma_f32_16x16x32_bf16 v[4:7], v[218:221], v[226:229], v[4:7]
	v_mfma_f32_16x16x32_bf16 v[0:3], v[218:221], v[234:237], v[0:3]
	s_barrier
	s_setprio 0
	s_add_i32 s50, s50, 2
	s_add_u32 s26, s26, 0x10000
	s_addc_u32 s27, s27, 0
	s_add_u32 s24, s24, 0x100
	s_addc_u32 s25, s25, 0
	s_cmpk_lt_u32 s50, 0x54
	s_cbranch_scc1 .LBB0_1738
	s_add_u32 s22, s22, 0x2bc000
	s_addc_u32 s23, s23, 0
	v_readfirstlane_b32 s24, v172
	v_lshl_add_u64 v[210:211], s[22:23], 0, v[130:131]
	s_mov_b32 m0, s24
	ds_read_b128 v[158:161], v171
	ds_read_b128 v[162:165], v171 offset:1024
	ds_read_b128 v[174:177], v171 offset:2048
	ds_read_b128 v[168:171], v171 offset:3072
	ds_read_b128 v[178:181], v153
	ds_read_b128 v[182:185], v153 offset:1024
	ds_read_b128 v[186:189], v152
	ds_read_b128 v[190:193], v152 offset:1024
	ds_read_b128 v[194:197], v151
	ds_read_b128 v[198:201], v151 offset:1024
	ds_read_b128 v[202:205], v150
	ds_read_b128 v[206:209], v150 offset:1024
	global_load_lds_dwordx4 v[210:211], off
	v_lshl_add_u64 v[210:211], s[22:23], 0, v[128:129]
	v_readfirstlane_b32 s22, v173
	s_mov_b32 m0, s22
	s_nop 0
	global_load_lds_dwordx4 v[210:211], off
	s_setprio 1
	s_barrier
	s_waitcnt lgkmcnt(0)
	v_mfma_f32_16x16x32_bf16 v[124:127], v[178:181], v[158:161], v[124:127]
	v_mfma_f32_16x16x32_bf16 v[120:123], v[178:181], v[174:177], v[120:123]
	v_mfma_f32_16x16x32_bf16 v[108:111], v[194:197], v[158:161], v[108:111]
	v_mfma_f32_16x16x32_bf16 v[104:107], v[194:197], v[174:177], v[104:107]
	v_mfma_f32_16x16x32_bf16 v[124:127], v[182:185], v[162:165], v[124:127]
	v_mfma_f32_16x16x32_bf16 v[120:123], v[182:185], v[168:171], v[120:123]
	v_mfma_f32_16x16x32_bf16 v[116:119], v[186:189], v[158:161], v[116:119]
	v_mfma_f32_16x16x32_bf16 v[112:115], v[186:189], v[174:177], v[112:115]
	v_mfma_f32_16x16x32_bf16 v[108:111], v[198:201], v[162:165], v[108:111]
	v_mfma_f32_16x16x32_bf16 v[104:107], v[198:201], v[168:171], v[104:107]
	v_mfma_f32_16x16x32_bf16 v[100:103], v[202:205], v[158:161], v[100:103]
	v_mfma_f32_16x16x32_bf16 v[96:99], v[202:205], v[174:177], v[96:99]
	v_mfma_f32_16x16x32_bf16 v[210:213], v[190:193], v[162:165], v[116:119]
	v_mfma_f32_16x16x32_bf16 v[214:217], v[190:193], v[168:171], v[112:115]
	v_mfma_f32_16x16x32_bf16 v[218:221], v[206:209], v[162:165], v[100:103]
	v_mfma_f32_16x16x32_bf16 v[222:225], v[206:209], v[168:171], v[96:99]
	s_barrier
	s_setprio 0
	s_nop 1
	ds_read_b128 v[96:99], v167
	ds_read_b128 v[100:103], v167 offset:1024
	ds_read_b128 v[112:115], v167 offset:2048
	ds_read_b128 v[116:119], v167 offset:3072
	s_setprio 1
	s_barrier
	s_waitcnt lgkmcnt(0)
	v_mfma_f32_16x16x32_bf16 v[92:95], v[178:181], v[96:99], v[92:95]
	v_mfma_f32_16x16x32_bf16 v[88:91], v[178:181], v[112:115], v[88:91]
	v_mfma_f32_16x16x32_bf16 v[76:79], v[194:197], v[96:99], v[76:79]
	v_mfma_f32_16x16x32_bf16 v[72:75], v[194:197], v[112:115], v[72:75]
	v_mfma_f32_16x16x32_bf16 v[92:95], v[182:185], v[100:103], v[92:95]
	v_mfma_f32_16x16x32_bf16 v[88:91], v[182:185], v[116:119], v[88:91]
	v_mfma_f32_16x16x32_bf16 v[84:87], v[186:189], v[96:99], v[84:87]
	v_mfma_f32_16x16x32_bf16 v[80:83], v[186:189], v[112:115], v[80:83]
	v_mfma_f32_16x16x32_bf16 v[76:79], v[198:201], v[100:103], v[76:79]
	v_mfma_f32_16x16x32_bf16 v[72:75], v[198:201], v[116:119], v[72:75]
	v_mfma_f32_16x16x32_bf16 v[68:71], v[202:205], v[96:99], v[68:71]
	v_mfma_f32_16x16x32_bf16 v[64:67], v[202:205], v[112:115], v[64:67]
	v_mfma_f32_16x16x32_bf16 v[178:181], v[190:193], v[100:103], v[84:87]
	v_mfma_f32_16x16x32_bf16 v[182:185], v[190:193], v[116:119], v[80:83]
	v_mfma_f32_16x16x32_bf16 v[186:189], v[206:209], v[100:103], v[68:71]
	v_mfma_f32_16x16x32_bf16 v[190:193], v[206:209], v[116:119], v[64:67]
	s_barrier
; #define LDA(dst, b, h) for (int m = 0; m < 4; ++m) for (int k = 0; k < 2; ++k) \
;     dst[m][k] = *reinterpret_cast<const bf16x8*>((char*)SA(b, h) + lds_byte(wr * 64 + m * 16 + fr, k * 32 + fq * 8))
; #define LDB(dst, b, h) for (int n = 0; n < 2; ++n) for (int k = 0; k < 2; ++k) \
;     dst[n][k] = *reinterpret_cast<const bf16x8*>((char*)SB(b, h) + lds_byte(wc * 32 + n * 16 + fr, k * 32 + fq * 8))
; #define MMA(ai, bj, At, Bt) do { __builtin_amdgcn_s_setprio(1); \
;     for (int m = 0; m < 4; ++m) for (int n = 0; n < 2; ++n) for (int k = 0; k < 2; ++k) \
;       acc[ai][bj][m][n] = __builtin_amdgcn_mfma_f32_16x16x32_bf16(At[m][k], Bt[n][k], acc[ai][bj][m][n], 0, 0, 0); \
;     __builtin_amdgcn_s_setprio(0); } while (0)
; #define WAIT_V(n) asm volatile("s_waitcnt vmcnt(" #n ")" ::: "memory")
; #define WAIT_L(n) asm volatile("s_waitcnt lgkmcnt(" #n ")" ::: "memory")
; #define BAR __builtin_amdgcn_s_barrier()
; template <int EPI> ...
;     ...
;     LDA(At, 0, 1); WAIT_V(4); BAR; WAIT_L(0); MMA(1, 0, At, B0); MMA(1, 1, At, B1); BAR; }
;   { LDB(B0, 1, 0); LDA(At, 1, 0); WAIT_V(2); BAR; WAIT_L(0); MMA(0, 0, At, B0); BAR;
	s_setprio 0
	s_nop 1
	ds_read_b128 v[64:67], v153 offset:16384
	ds_read_b128 v[68:71], v153 offset:17408
	ds_read_b128 v[80:83], v152 offset:16384
	ds_read_b128 v[84:87], v152 offset:17408
	ds_read_b128 v[194:197], v151 offset:16384
	ds_read_b128 v[198:201], v151 offset:17408
	ds_read_b128 v[202:205], v150 offset:16384
	ds_read_b128 v[206:209], v150 offset:17408
	s_waitcnt vmcnt(4)
	s_setprio 1
	s_barrier
	s_waitcnt lgkmcnt(0)
	v_mfma_f32_16x16x32_bf16 v[60:63], v[64:67], v[158:161], v[60:63]
	v_mfma_f32_16x16x32_bf16 v[56:59], v[64:67], v[174:177], v[56:59]
	v_mfma_f32_16x16x32_bf16 v[44:47], v[194:197], v[158:161], v[44:47]
	v_mfma_f32_16x16x32_bf16 v[40:43], v[194:197], v[174:177], v[40:43]
	v_mfma_f32_16x16x32_bf16 v[60:63], v[68:71], v[162:165], v[60:63]
	v_mfma_f32_16x16x32_bf16 v[56:59], v[68:71], v[168:171], v[56:59]
	v_mfma_f32_16x16x32_bf16 v[52:55], v[80:83], v[158:161], v[52:55]
	v_mfma_f32_16x16x32_bf16 v[48:51], v[80:83], v[174:177], v[48:51]
	v_mfma_f32_16x16x32_bf16 v[44:47], v[198:201], v[162:165], v[44:47]
	v_mfma_f32_16x16x32_bf16 v[40:43], v[198:201], v[168:171], v[40:43]
	v_mfma_f32_16x16x32_bf16 v[36:39], v[202:205], v[158:161], v[36:39]
	v_mfma_f32_16x16x32_bf16 v[32:35], v[202:205], v[174:177], v[32:35]
	v_mfma_f32_16x16x32_bf16 v[226:229], v[84:87], v[162:165], v[52:55]
	v_mfma_f32_16x16x32_bf16 v[230:233], v[84:87], v[168:171], v[48:51]
	v_mfma_f32_16x16x32_bf16 v[158:161], v[206:209], v[162:165], v[36:39]
	v_mfma_f32_16x16x32_bf16 v[162:165], v[206:209], v[168:171], v[32:35]
	s_setprio 0
	s_setprio 1
	v_mfma_f32_16x16x32_bf16 v[28:31], v[64:67], v[96:99], v[28:31]
	v_mfma_f32_16x16x32_bf16 v[24:27], v[64:67], v[112:115], v[24:27]
	v_mfma_f32_16x16x32_bf16 v[12:15], v[194:197], v[96:99], v[12:15]
	v_mfma_f32_16x16x32_bf16 v[8:11], v[194:197], v[112:115], v[8:11]
	v_mfma_f32_16x16x32_bf16 v[28:31], v[68:71], v[100:103], v[28:31]
	v_mfma_f32_16x16x32_bf16 v[24:27], v[68:71], v[116:119], v[24:27]
	v_mfma_f32_16x16x32_bf16 v[20:23], v[80:83], v[96:99], v[20:23]
	v_mfma_f32_16x16x32_bf16 v[16:19], v[80:83], v[112:115], v[16:19]
	v_mfma_f32_16x16x32_bf16 v[12:15], v[198:201], v[100:103], v[12:15]
	v_mfma_f32_16x16x32_bf16 v[8:11], v[198:201], v[116:119], v[8:11]
	v_mfma_f32_16x16x32_bf16 v[4:7], v[202:205], v[96:99], v[4:7]
	v_mfma_f32_16x16x32_bf16 v[0:3], v[202:205], v[112:115], v[0:3]
	v_mfma_f32_16x16x32_bf16 v[166:169], v[84:87], v[100:103], v[20:23]
	v_mfma_f32_16x16x32_bf16 v[170:173], v[84:87], v[116:119], v[16:19]
	v_mfma_f32_16x16x32_bf16 v[174:177], v[206:209], v[100:103], v[4:7]
	v_mfma_f32_16x16x32_bf16 v[194:197], v[206:209], v[116:119], v[0:3]
	s_barrier
	s_setprio 0
	s_nop 1
	ds_read_b128 v[0:3], v156
	ds_read_b128 v[4:7], v156 offset:1024
	ds_read_b128 v[198:201], v156 offset:2048
	ds_read_b128 v[202:205], v156 offset:3072
	ds_read_b128 v[16:19], v153 offset:32768
	ds_read_b128 v[20:23], v153 offset:33792
	ds_read_b128 v[32:35], v152 offset:32768
	ds_read_b128 v[36:39], v152 offset:33792
	ds_read_b128 v[48:51], v151 offset:32768
	ds_read_b128 v[52:55], v151 offset:33792
	ds_read_b128 v[206:209], v150 offset:32768
	ds_read_b128 v[234:237], v150 offset:33792
	s_waitcnt vmcnt(2)
	s_setprio 1
	s_barrier
	s_waitcnt lgkmcnt(0)
	v_mfma_f32_16x16x32_bf16 v[64:67], v[16:19], v[0:3], v[124:127]
	v_mfma_f32_16x16x32_bf16 v[116:119], v[20:23], v[4:7], v[64:67]
	v_mfma_f32_16x16x32_bf16 v[64:67], v[16:19], v[198:201], v[120:123]
	v_mfma_f32_16x16x32_bf16 v[112:115], v[20:23], v[202:205], v[64:67]
	v_mfma_f32_16x16x32_bf16 v[64:67], v[32:35], v[0:3], v[210:213]
	v_mfma_f32_16x16x32_bf16 v[100:103], v[36:39], v[4:7], v[64:67]
	v_mfma_f32_16x16x32_bf16 v[64:67], v[32:35], v[198:201], v[214:217]
	v_mfma_f32_16x16x32_bf16 v[96:99], v[36:39], v[202:205], v[64:67]
	v_mfma_f32_16x16x32_bf16 v[64:67], v[48:51], v[0:3], v[108:111]
	v_mfma_f32_16x16x32_bf16 v[84:87], v[52:55], v[4:7], v[64:67]
	v_mfma_f32_16x16x32_bf16 v[64:67], v[48:51], v[198:201], v[104:107]
	v_mfma_f32_16x16x32_bf16 v[80:83], v[52:55], v[202:205], v[64:67]
	v_mfma_f32_16x16x32_bf16 v[64:67], v[206:209], v[0:3], v[218:221]
	v_mfma_f32_16x16x32_bf16 v[68:71], v[234:237], v[4:7], v[64:67]
	v_mfma_f32_16x16x32_bf16 v[64:67], v[206:209], v[198:201], v[222:225]
	v_mfma_f32_16x16x32_bf16 v[64:67], v[234:237], v[202:205], v[64:67]
	s_barrier
; #define LDA(dst, b, h) for (int m = 0; m < 4; ++m) for (int k = 0; k < 2; ++k) \
;     dst[m][k] = *reinterpret_cast<const bf16x8*>((char*)SA(b, h) + lds_byte(wr * 64 + m * 16 + fr, k * 32 + fq * 8))
; #define LDB(dst, b, h) for (int n = 0; n < 2; ++n) for (int k = 0; k < 2; ++k) \
;     dst[n][k] = *reinterpret_cast<const bf16x8*>((char*)SB(b, h) + lds_byte(wc * 32 + n * 16 + fr, k * 32 + fq * 8))
; #define MMA(ai, bj, At, Bt) do { __builtin_amdgcn_s_setprio(1); \
;     for (int m = 0; m < 4; ++m) for (int n = 0; n < 2; ++n) for (int k = 0; k < 2; ++k) \
;       acc[ai][bj][m][n] = __builtin_amdgcn_mfma_f32_16x16x32_bf16(At[m][k], Bt[n][k], acc[ai][bj][m][n], 0, 0, 0); \
;     __builtin_amdgcn_s_setprio(0); } while (0)
; #define WAIT_V(n) asm volatile("s_waitcnt vmcnt(" #n ")" ::: "memory")
; #define WAIT_L(n) asm volatile("s_waitcnt lgkmcnt(" #n ")" ::: "memory")
; #define BAR __builtin_amdgcn_s_barrier()
; template <int EPI> ...
;     ...
;   { LDB(B0, 1, 0); LDA(At, 1, 0); WAIT_V(2); BAR; WAIT_L(0); MMA(0, 0, At, B0); BAR;
;     LDB(B1, 1, 1); WAIT_V(0); BAR; WAIT_L(0); MMA(0, 1, At, B1); BAR;
;     LDA(At, 1, 1); BAR; WAIT_L(0); MMA(1, 0, At, B0); MMA(1, 1, At, B1); BAR; }
;   if (wr == 0) BAR;
	s_setprio 0
	ds_read_b128 v[210:213], v154
	ds_read_b128 v[214:217], v154 offset:1024
	ds_read_b128 v[218:221], v154 offset:2048
	ds_read_b128 v[154:157], v154 offset:3072
	s_waitcnt vmcnt(0)
	s_setprio 1
	s_barrier
	s_waitcnt lgkmcnt(0)
	v_mfma_f32_16x16x32_bf16 v[92:95], v[16:19], v[210:213], v[92:95]
	v_mfma_f32_16x16x32_bf16 v[16:19], v[16:19], v[218:221], v[88:91]
	v_mfma_f32_16x16x32_bf16 v[120:123], v[20:23], v[154:157], v[16:19]
	v_mfma_f32_16x16x32_bf16 v[16:19], v[32:35], v[210:213], v[178:181]
	v_mfma_f32_16x16x32_bf16 v[108:111], v[36:39], v[214:217], v[16:19]
	v_mfma_f32_16x16x32_bf16 v[16:19], v[32:35], v[218:221], v[182:185]
	v_mfma_f32_16x16x32_bf16 v[104:107], v[36:39], v[154:157], v[16:19]
	v_mfma_f32_16x16x32_bf16 v[16:19], v[48:51], v[210:213], v[76:79]
	v_mfma_f32_16x16x32_bf16 v[124:127], v[20:23], v[214:217], v[92:95]
	v_mfma_f32_16x16x32_bf16 v[92:95], v[52:55], v[214:217], v[16:19]
	v_mfma_f32_16x16x32_bf16 v[16:19], v[48:51], v[218:221], v[72:75]
	v_mfma_f32_16x16x32_bf16 v[88:91], v[52:55], v[154:157], v[16:19]
	v_mfma_f32_16x16x32_bf16 v[16:19], v[206:209], v[210:213], v[186:189]
	v_mfma_f32_16x16x32_bf16 v[76:79], v[234:237], v[214:217], v[16:19]
	v_mfma_f32_16x16x32_bf16 v[16:19], v[206:209], v[218:221], v[190:193]
	v_mfma_f32_16x16x32_bf16 v[72:75], v[234:237], v[154:157], v[16:19]
	s_barrier
	s_setprio 0
	ds_read_b128 v[178:181], v153 offset:49152
	ds_read_b128 v[182:185], v153 offset:50176
	ds_read_b128 v[186:189], v152 offset:49152
	ds_read_b128 v[190:193], v152 offset:50176
	ds_read_b128 v[206:209], v151 offset:49152
	ds_read_b128 v[222:225], v151 offset:50176
	ds_read_b128 v[234:237], v150 offset:49152
	ds_read_b128 v[150:153], v150 offset:50176
	s_setprio 1
	s_barrier
	s_waitcnt lgkmcnt(0)
	v_mfma_f32_16x16x32_bf16 v[16:19], v[178:181], v[0:3], v[60:63]
	v_mfma_f32_16x16x32_bf16 v[52:55], v[182:185], v[4:7], v[16:19]
	v_mfma_f32_16x16x32_bf16 v[16:19], v[178:181], v[198:201], v[56:59]
	v_mfma_f32_16x16x32_bf16 v[48:51], v[182:185], v[202:205], v[16:19]
	v_mfma_f32_16x16x32_bf16 v[16:19], v[186:189], v[0:3], v[226:229]
	v_mfma_f32_16x16x32_bf16 v[36:39], v[190:193], v[4:7], v[16:19]
	v_mfma_f32_16x16x32_bf16 v[16:19], v[186:189], v[198:201], v[230:233]
	v_mfma_f32_16x16x32_bf16 v[32:35], v[190:193], v[202:205], v[16:19]
	v_mfma_f32_16x16x32_bf16 v[16:19], v[206:209], v[0:3], v[44:47]
	v_mfma_f32_16x16x32_bf16 v[0:3], v[234:237], v[0:3], v[158:161]
	v_mfma_f32_16x16x32_bf16 v[20:23], v[222:225], v[4:7], v[16:19]
	v_mfma_f32_16x16x32_bf16 v[16:19], v[206:209], v[198:201], v[40:43]
	v_mfma_f32_16x16x32_bf16 v[4:7], v[150:153], v[4:7], v[0:3]
	v_mfma_f32_16x16x32_bf16 v[0:3], v[234:237], v[198:201], v[162:165]
	v_mfma_f32_16x16x32_bf16 v[16:19], v[222:225], v[202:205], v[16:19]
	v_mfma_f32_16x16x32_bf16 v[0:3], v[150:153], v[202:205], v[0:3]
	s_setprio 0
	s_setprio 1
	v_mfma_f32_16x16x32_bf16 v[24:27], v[178:181], v[218:221], v[24:27]
	v_mfma_f32_16x16x32_bf16 v[56:59], v[182:185], v[154:157], v[24:27]
	v_mfma_f32_16x16x32_bf16 v[24:27], v[186:189], v[210:213], v[166:169]
	v_mfma_f32_16x16x32_bf16 v[44:47], v[190:193], v[214:217], v[24:27]
	v_mfma_f32_16x16x32_bf16 v[24:27], v[186:189], v[218:221], v[170:173]
	v_mfma_f32_16x16x32_bf16 v[8:11], v[206:209], v[218:221], v[8:11]
	v_mfma_f32_16x16x32_bf16 v[28:31], v[178:181], v[210:213], v[28:31]
	v_mfma_f32_16x16x32_bf16 v[40:43], v[190:193], v[154:157], v[24:27]
	v_mfma_f32_16x16x32_bf16 v[12:15], v[206:209], v[210:213], v[12:15]
	v_mfma_f32_16x16x32_bf16 v[24:27], v[222:225], v[154:157], v[8:11]
	v_mfma_f32_16x16x32_bf16 v[8:11], v[234:237], v[210:213], v[174:177]
	v_mfma_f32_16x16x32_bf16 v[60:63], v[182:185], v[214:217], v[28:31]
	v_mfma_f32_16x16x32_bf16 v[28:31], v[222:225], v[214:217], v[12:15]
	v_mfma_f32_16x16x32_bf16 v[12:15], v[150:153], v[214:217], v[8:11]
	v_mfma_f32_16x16x32_bf16 v[8:11], v[234:237], v[218:221], v[194:197]
	v_mfma_f32_16x16x32_bf16 v[8:11], v[150:153], v[154:157], v[8:11]
	s_barrier
	s_setprio 0
	v_cmp_gt_u32_e32 vcc, s43, v144
	s_and_saveexec_b64 s[22:23], vcc
	s_cbranch_execz .LBB0_1741
	s_barrier
